# RESID/split-K epilogues: residual read as 16 dwordx4 per lane + permlane16_swap instead of 32 dwordx2
# speedup vs baseline: 1.0346x; 1.0118x over previous
; #define LAS __attribute__((address_space(3)))
; DEVI int tidx() { int t = threadIdx.x; asm volatile("" : "+v"(t)); return t; }
;   const int tid = tidx(), lane = tid & 63, wid = tid >> 6;
;   const int wm = wid >> 1, wn = wid & 1, r16 = lane & 15, quad = lane >> 4;
;   f32x4 acc[4][8];
; #pragma unroll
;   for (int i = 0; i < 4; i++)
; #pragma unroll
;     for (int j = 0; j < 8; j++) acc[i][j] = (f32x4){0.f, 0.f, 0.f, 0.f};
;   const int nk = (nk_part < 0) ? (K >> 5) : nk_part;
;   const int lrow = tid >> 2, lpc = tid & 3;
;   const int lch = lpc ^ ((0x78 >> (((lrow >> 2) & 3) * 2)) & 3);
;   const u16* ga = A + (size_t)(m0 + lrow) * lda + kbeg + lch * 8;
;   const u16* gb = Bt + (size_t)(n0 + lrow) * K + kbeg + lch * 8;
;   const size_t ga1 = (size_t)64 * lda, gb1 = (size_t)64 * K;
;   const unsigned lds0 = (unsigned)(uintptr_t)(LAS char*)smem + (unsigned)__builtin_amdgcn_readfirstlane(wid) * 1024u;
; DEVI void run_phase(const Params& p, int ph, char* smem) {
;     ...
;         } else {
;           const int u_ = t - 512, tl_ = u_ / 11, q_ = u_ - tl_ * 11;
;           gemm_tile256<EPI_RESID_ATOMIC>(p, hb, DFF, Bt, DFF, (64 + (tl_ & 1)) * 256, (tl_ >> 1) * 128, nullptr, 0, smem, q_ * 256, 8, q_);
.LBB0_42:
	s_cmpk_gt_i32 s38, 0x1ff
	s_mov_b64 s[2:3], -1
	s_cbranch_scc0 .LBB0_116
	s_sub_i32 s46, s38, 512
	s_mul_i32 s45, s46, 373
	s_lshr_b32 s45, s45, 12
	s_mul_i32 s47, s45, 11
	s_sub_i32 s47, s46, s47
	s_lshr_b32 s42, s45, 1
	s_and_b32 s45, s45, 1
	s_add_i32 s45, s45, 64
	s_cmp_lt_u32 s45, 64
	s_cselect_b32 s44, 1, 0
	v_readlane_b32 s2, v250, 5
	v_readlane_b32 s3, v250, 6
	v_readlane_b32 s46, v254, 62
	s_mul_i32 s40, s45, 0x160000
	s_add_u32 s4, s2, s40
	s_addc_u32 s5, s3, 0
	s_add_u32 s4, s4, 0xef40000
	s_addc_u32 s5, s5, 0
	s_mul_i32 s40, s46, 0x580000
	s_mul_i32 s41, s42, 0xb0000
	s_add_i32 s40, s40, s41
	s_add_u32 s10, s2, s40
	s_addc_u32 s11, s3, 0
	s_add_u32 s10, s10, 0x19a00000
	s_addc_u32 s11, s11, 0
	s_mul_i32 s40, s47, 512
	s_add_u32 s4, s4, s40
	s_addc_u32 s5, s5, 0
	s_mul_i32 s40, s47, 1024
	s_add_u32 s10, s10, s40
	s_addc_u32 s11, s11, 0
	s_movk_i32 s39, 0x78
	v_lshrrev_b32_e32 v0, 2, v145
	v_and_b32_e32 v131, 3, v145
	v_bfe_u32 v136, v145, 4, 2
	v_lshlrev_b32_e32 v136, 1, v136
	v_lshrrev_b32_e64 v136, v136, s39
	v_and_b32_e32 v136, 3, v136
	v_xor_b32_e32 v131, v131, v136
	v_lshlrev_b32_e32 v131, 4, v131
	s_movk_i32 s41, 0x1600
	v_mad_u32_u24 v0, v0, s41, v131
	v_bfe_u32 v137, v145, 2, 1
	s_movk_i32 s41, 0x15c0
	v_mul_u32_u24_e32 v136, s41, v137
	v_sub_u32_e32 v136, v0, v136
	v_mov_b32_e32 v137, 0
	v_lshl_add_u64 v[134:135], s[10:11], 0, v[136:137]
	v_bfe_u32 v137, v145, 2, 1
	s_mul_i32 s41, s44, 0x15c0
	v_mul_u32_u24_e32 v136, s41, v137
	v_sub_u32_e32 v0, v0, v136
	s_lshl_b32 s12, s44, 6
	s_add_i32 s12, s12, 64
	s_mov_b32 s13, 0
	v_lshl_add_u64 v[132:133], s[4:5], 0, v[0:1]
	v_bfe_u32 v136, v145, 2, 2
	v_lshlrev_b32_e32 v136, 1, v136
	v_lshrrev_b32_e64 v136, v136, s39
	v_and_b32_e32 v136, 3, v136
	v_bfe_u32 v137, v145, 4, 2
	v_xor_b32_e32 v136, v136, v137
	v_lshlrev_b32_e32 v136, 4, v136
	v_and_b32_e32 v131, 15, v145
	v_lshl_or_b32 v136, v131, 6, v136
	v_bfe_u32 v137, v145, 6, 1
	v_lshl_or_b32 v137, v137, 12, v136
	v_lshrrev_b32_e32 v0, 7, v145
	v_lshl_or_b32 v136, v0, 13, v136
	v_and_b32_e32 v140, 1, v131
	v_lshl_or_b32 v131, v0, 7, v131
	v_bfe_u32 v0, v145, 4, 2
	v_lshlrev_b32_e32 v0, 3, v0
	v_bfe_u32 v141, v145, 6, 1
	s_lshl_b32 s40, s45, 19
	s_lshl_b32 s41, s42, 8
	s_add_i32 s40, s40, s41
	s_add_u32 s4, s2, s40
	s_addc_u32 s5, s3, 0
	s_add_u32 s4, s4, 0x4200000
	s_addc_u32 s5, s5, 0
	v_lshlrev_b32_e32 v138, 11, v131
	v_lshl_add_u32 v138, v141, 7, v138
	v_bfe_u32 v139, v145, 4, 1
	v_lshl_add_u32 v138, v139, 5, v138
	v_bfe_u32 v139, v145, 5, 1
	v_lshl_add_u32 v138, v139, 4, v138
	v_mov_b32_e32 v139, 0
	v_lshl_add_u64 v[138:139], s[4:5], 0, v[138:139]
	s_and_b32 s40, s45, 1
	s_lshl_b32 s40, s40, 20
	s_lshl_b32 s41, s47, 21
	s_add_i32 s40, s40, s41
	s_lshl_b32 s41, s42, 9
	s_add_i32 s40, s40, s41
	s_add_u32 s10, s2, s40
	s_addc_u32 s11, s3, 0
	s_add_u32 s10, s10, 0x1dcc0000
	s_addc_u32 s11, s11, 0
	v_lshlrev_b32_e32 v140, 12, v131
	v_lshl_add_u32 v140, v141, 8, v140
	v_lshl_add_u32 v140, v0, 1, v140
	v_mov_b32_e32 v141, 0
	v_lshl_add_u64 v[140:141], s[10:11], 0, v[140:141]
	s_mov_b32 s2, 0x58000
	s_mov_b32 s3, 0
	v_lshrrev_b32_e32 v0, 6, v145
	v_lshlrev_b32_e32 v0, 10, v0
	s_nop 0
	v_readfirstlane_b32 s46, v0
	s_mov_b32 s43, m0
	s_mov_b32 s4, 128
	s_mov_b32 s5, 0
	v_mov_b32_e32 v2, 0
	v_mov_b32_e32 v3, 0
	v_mov_b32_e32 v4, 0
	v_mov_b32_e32 v5, 0
	v_mov_b32_e32 v6, 0
	v_mov_b32_e32 v7, 0
	v_mov_b32_e32 v8, 0
	v_mov_b32_e32 v9, 0
	v_mov_b32_e32 v10, 0
	v_mov_b32_e32 v11, 0
	v_mov_b32_e32 v12, 0
	v_mov_b32_e32 v13, 0
	v_mov_b32_e32 v14, 0
	v_mov_b32_e32 v15, 0
	v_mov_b32_e32 v16, 0
	v_mov_b32_e32 v17, 0
	v_mov_b32_e32 v18, 0
	v_mov_b32_e32 v19, 0
	v_mov_b32_e32 v20, 0
	v_mov_b32_e32 v21, 0
	v_mov_b32_e32 v22, 0
	v_mov_b32_e32 v23, 0
	v_mov_b32_e32 v24, 0
	v_mov_b32_e32 v25, 0
	v_mov_b32_e32 v26, 0
	v_mov_b32_e32 v27, 0
	v_mov_b32_e32 v28, 0
	v_mov_b32_e32 v29, 0
	v_mov_b32_e32 v30, 0
	v_mov_b32_e32 v31, 0
	v_mov_b32_e32 v32, 0
	v_mov_b32_e32 v33, 0
	v_mov_b32_e32 v34, 0
	v_mov_b32_e32 v35, 0
	v_mov_b32_e32 v36, 0
	v_mov_b32_e32 v37, 0
	v_mov_b32_e32 v38, 0
	v_mov_b32_e32 v39, 0
	v_mov_b32_e32 v40, 0
	v_mov_b32_e32 v41, 0
	v_mov_b32_e32 v42, 0
	v_mov_b32_e32 v43, 0
	v_mov_b32_e32 v44, 0
	v_mov_b32_e32 v45, 0
	v_mov_b32_e32 v46, 0
	v_mov_b32_e32 v47, 0
	v_mov_b32_e32 v48, 0
	v_mov_b32_e32 v49, 0
	v_mov_b32_e32 v50, 0
	v_mov_b32_e32 v51, 0
	v_mov_b32_e32 v52, 0
	v_mov_b32_e32 v53, 0
	v_mov_b32_e32 v54, 0
	v_mov_b32_e32 v55, 0
	v_mov_b32_e32 v56, 0
	v_mov_b32_e32 v57, 0
	v_mov_b32_e32 v58, 0
	v_mov_b32_e32 v59, 0
	v_mov_b32_e32 v60, 0
	v_mov_b32_e32 v61, 0
	v_mov_b32_e32 v62, 0
	v_mov_b32_e32 v63, 0
	v_mov_b32_e32 v64, 0
	v_mov_b32_e32 v65, 0
	v_mov_b32_e32 v66, 0
	v_mov_b32_e32 v67, 0
	v_mov_b32_e32 v68, 0
	v_mov_b32_e32 v69, 0
	v_mov_b32_e32 v70, 0
	v_mov_b32_e32 v71, 0
	v_mov_b32_e32 v72, 0
	v_mov_b32_e32 v73, 0
	v_mov_b32_e32 v74, 0
	v_mov_b32_e32 v75, 0
	v_mov_b32_e32 v76, 0
	v_mov_b32_e32 v77, 0
	v_mov_b32_e32 v78, 0
	v_mov_b32_e32 v79, 0
	v_mov_b32_e32 v80, 0
	v_mov_b32_e32 v81, 0
	v_mov_b32_e32 v82, 0
	v_mov_b32_e32 v83, 0
	v_mov_b32_e32 v84, 0
	v_mov_b32_e32 v85, 0
	v_mov_b32_e32 v86, 0
	v_mov_b32_e32 v87, 0
	v_mov_b32_e32 v88, 0
	v_mov_b32_e32 v89, 0
	v_mov_b32_e32 v90, 0
	v_mov_b32_e32 v91, 0
	v_mov_b32_e32 v92, 0
	v_mov_b32_e32 v93, 0
	v_mov_b32_e32 v94, 0
	v_mov_b32_e32 v95, 0
	v_mov_b32_e32 v96, 0
	v_mov_b32_e32 v97, 0
	v_mov_b32_e32 v98, 0
	v_mov_b32_e32 v99, 0
	v_mov_b32_e32 v100, 0
	v_mov_b32_e32 v101, 0
	v_mov_b32_e32 v102, 0
	v_mov_b32_e32 v103, 0
	v_mov_b32_e32 v104, 0
	v_mov_b32_e32 v105, 0
	v_mov_b32_e32 v106, 0
	v_mov_b32_e32 v107, 0
	v_mov_b32_e32 v108, 0
	v_mov_b32_e32 v109, 0
	v_mov_b32_e32 v110, 0
	v_mov_b32_e32 v111, 0
	v_mov_b32_e32 v112, 0
	v_mov_b32_e32 v113, 0
	v_mov_b32_e32 v114, 0
	v_mov_b32_e32 v115, 0
	v_mov_b32_e32 v116, 0
	v_mov_b32_e32 v117, 0
	v_mov_b32_e32 v118, 0
	v_mov_b32_e32 v119, 0
	v_mov_b32_e32 v120, 0
	v_mov_b32_e32 v121, 0
	v_mov_b32_e32 v122, 0
	v_mov_b32_e32 v123, 0
	v_mov_b32_e32 v124, 0
	v_mov_b32_e32 v125, 0
	v_mov_b32_e32 v126, 0
	v_mov_b32_e32 v127, 0
	v_mov_b32_e32 v128, 0
	v_mov_b32_e32 v129, 0
	s_barrier
;     ...
;   __syncthreads();
;   G2_STAGE(0); G2_STAGE(1);
;   const int fsw = (0x78 >> (((r16 >> 2) & 3) * 2)) & 3;
;   const int aoff = (wm * 128 + r16) * 64 + ((quad ^ fsw) << 4);
;   const int boff = 16384 + (wn * 64 + r16) * 64 + ((quad ^ fsw) << 4);
;   for (int kt = 0; kt < nk; kt++) {
;     if (kt + 1 < nk) asm volatile("s_waitcnt vmcnt(6)" ::: "memory");
;     else asm volatile("s_waitcnt vmcnt(0)" ::: "memory");
;     __builtin_amdgcn_s_barrier();
;     asm volatile("" ::: "memory");
;     if (kt + 2 < nk) G2_STAGE(kt + 2);
;     const char* cS = smem + (kt % 3) * 24576;
;     bf16x8 xa[8], wb[4];
; #pragma unroll
;     for (int f = 0; f < 8; f++) xa[f] = *(const bf16x8*)(cS + aoff + f * 1024);
; #pragma unroll
;     for (int f = 0; f < 4; f++) wb[f] = *(const bf16x8*)(cS + boff + f * 1024);
	s_add_i32 s42, s46, 0x0
	s_mov_b32 m0, s42
	v_lshl_add_u64 v[142:143], v[132:133], 0, s[2:3]
	global_load_lds_dwordx4 v[132:133], off
	s_addk_i32 m0, 0x1000
	s_nop 0
	global_load_lds_dwordx4 v[142:143], off
	v_lshl_add_u64 v[142:143], v[142:143], 0, s[2:3]
	s_addk_i32 m0, 0x1000
	s_nop 0
	global_load_lds_dwordx4 v[142:143], off
	v_lshl_add_u64 v[142:143], v[142:143], 0, s[2:3]
	s_addk_i32 m0, 0x1000
	s_nop 0
	global_load_lds_dwordx4 v[142:143], off
	s_addk_i32 m0, 0x1000
	v_lshl_add_u64 v[142:143], v[134:135], 0, s[2:3]
	s_nop 0
	global_load_lds_dwordx4 v[134:135], off
	s_addk_i32 m0, 0x1000
	v_lshl_add_u64 v[132:133], v[132:133], 0, s[12:13]
	s_nop 0
	global_load_lds_dwordx4 v[142:143], off
	v_lshl_add_u64 v[134:135], v[134:135], 0, s[4:5]
	s_nop 0
	s_add_i32 s42, s46, 0x6000
	s_mov_b32 m0, s42
	v_lshl_add_u64 v[142:143], v[132:133], 0, s[2:3]
	global_load_lds_dwordx4 v[132:133], off
	s_addk_i32 m0, 0x1000
	s_nop 0
	global_load_lds_dwordx4 v[142:143], off
	v_lshl_add_u64 v[142:143], v[142:143], 0, s[2:3]
	s_addk_i32 m0, 0x1000
	s_nop 0
	global_load_lds_dwordx4 v[142:143], off
	v_lshl_add_u64 v[142:143], v[142:143], 0, s[2:3]
	s_addk_i32 m0, 0x1000
	s_nop 0
	global_load_lds_dwordx4 v[142:143], off
	s_addk_i32 m0, 0x1000
	v_lshl_add_u64 v[142:143], v[134:135], 0, s[2:3]
	s_nop 0
	global_load_lds_dwordx4 v[134:135], off
	s_addk_i32 m0, 0x1000
	v_lshl_add_u64 v[132:133], v[132:133], 0, s[12:13]
	s_nop 0
	global_load_lds_dwordx4 v[142:143], off
	v_lshl_add_u64 v[134:135], v[134:135], 0, s[4:5]
	s_nop 0
	s_add_i32 s42, s46, 0xc000
	s_mov_b32 m0, s42
	v_lshl_add_u64 v[142:143], v[132:133], 0, s[2:3]
	global_load_lds_dwordx4 v[132:133], off
	s_addk_i32 m0, 0x1000
	s_nop 0
	global_load_lds_dwordx4 v[142:143], off
	v_lshl_add_u64 v[142:143], v[142:143], 0, s[2:3]
	s_addk_i32 m0, 0x1000
	s_nop 0
	global_load_lds_dwordx4 v[142:143], off
	v_lshl_add_u64 v[142:143], v[142:143], 0, s[2:3]
	s_addk_i32 m0, 0x1000
	s_nop 0
	global_load_lds_dwordx4 v[142:143], off
	s_addk_i32 m0, 0x1000
	v_lshl_add_u64 v[142:143], v[134:135], 0, s[2:3]
	s_nop 0
	global_load_lds_dwordx4 v[134:135], off
	s_addk_i32 m0, 0x1000
	v_lshl_add_u64 v[132:133], v[132:133], 0, s[12:13]
	s_nop 0
	global_load_lds_dwordx4 v[142:143], off
	v_lshl_add_u64 v[134:135], v[134:135], 0, s[4:5]
	s_nop 0
	s_waitcnt vmcnt(12)
	s_barrier
	ds_read_b128 v[146:149], v136 offset:0
	ds_read_b128 v[152:155], v136 offset:1024
	ds_read_b128 v[156:159], v136 offset:2048
	ds_read_b128 v[162:165], v136 offset:3072
	ds_read_b128 v[166:169], v136 offset:4096
	ds_read_b128 v[170:173], v136 offset:5120
	ds_read_b128 v[176:179], v136 offset:6144
	ds_read_b128 v[180:183], v136 offset:7168
	ds_read_b128 v[184:187], v137 offset:16384
	ds_read_b128 v[188:191], v137 offset:17408
	ds_read_b128 v[192:195], v137 offset:18432
	ds_read_b128 v[196:199], v137 offset:19456
	s_movk_i32 s40, 0x6000
	s_mov_b32 s41, 0
	s_movk_i32 s39, 2

; DEVI float blo(unsigned u) { return __uint_as_float(u << 16); }
; DEVI float bhi(unsigned u) { return __uint_as_float(u & 0xffff0000u); }
;     ...
;         if (EPI == EPI_RESID || EPI == EPI_RESID_ATOMIC) {
;           f32x4 x = a;
;           if (EPI == EPI_RESID || kpart == 0) {
;             const u32x2 xr = *(const u32x2*)((const u16*)(p.ws + WS_XB) + (size_t)row * 1024 + col);
;             x[0] += ALPHA * blo(xr[0]); x[1] += ALPHA * bhi(xr[0]); x[2] += ALPHA * blo(xr[1]); x[3] += ALPHA * bhi(xr[1]);
;           }
;           if (EPI == EPI_RESID) *(f32x4*)((float*)(p.ws + WS_XF) + (size_t)row * 1024 + col) = x;
;           else *(f32x4*)((float*)(p.ws + WS_SLAB) + ((size_t)kpart * 512 + (row - T_P)) * 1024 + col) = x;
.Lta11_first:
	global_load_dwordx4 v[146:149], v[138:139], off offset:0
	global_load_dwordx4 v[152:155], v[138:139], off offset:64
	v_lshl_add_u64 v[138:139], v[138:139], 0, s[4:5]
	global_load_dwordx4 v[156:159], v[138:139], off offset:0
	global_load_dwordx4 v[162:165], v[138:139], off offset:64
	v_lshl_add_u64 v[138:139], v[138:139], 0, s[4:5]
	global_load_dwordx4 v[166:169], v[138:139], off offset:0
	global_load_dwordx4 v[170:173], v[138:139], off offset:64
	v_lshl_add_u64 v[138:139], v[138:139], 0, s[4:5]
	global_load_dwordx4 v[176:179], v[138:139], off offset:0
	global_load_dwordx4 v[180:183], v[138:139], off offset:64
	v_lshl_add_u64 v[138:139], v[138:139], 0, s[4:5]
	global_load_dwordx4 v[184:187], v[138:139], off offset:0
	global_load_dwordx4 v[188:191], v[138:139], off offset:64
	v_lshl_add_u64 v[138:139], v[138:139], 0, s[4:5]
	global_load_dwordx4 v[192:195], v[138:139], off offset:0
	global_load_dwordx4 v[196:199], v[138:139], off offset:64
	v_lshl_add_u64 v[138:139], v[138:139], 0, s[4:5]
	global_load_dwordx4 v[200:203], v[138:139], off offset:0
	global_load_dwordx4 v[204:207], v[138:139], off offset:64
	v_lshl_add_u64 v[138:139], v[138:139], 0, s[4:5]
	global_load_dwordx4 v[208:211], v[138:139], off offset:0
	global_load_dwordx4 v[212:215], v[138:139], off offset:64
	v_lshl_add_u64 v[138:139], v[138:139], 0, s[4:5]
	s_nop 7
	s_waitcnt vmcnt(15)
	v_permlane16_swap_b32_e32 v146, v148
	v_permlane16_swap_b32_e32 v147, v149
	v_lshlrev_b32_e32 v216, 16, v146
	v_and_b32_e32 v146, 0xffff0000, v146
	v_lshlrev_b32_e32 v217, 16, v147
	v_and_b32_e32 v147, 0xffff0000, v147
	v_fmac_f32_e32 v126, s44, v216
	v_fmac_f32_e32 v127, s44, v146
	v_fmac_f32_e32 v128, s44, v217
	v_fmac_f32_e32 v129, s44, v147
	global_store_dwordx4 v[140:141], v[126:129], off offset:0
	v_lshlrev_b32_e32 v216, 16, v148
	v_and_b32_e32 v148, 0xffff0000, v148
	v_lshlrev_b32_e32 v217, 16, v149
	v_and_b32_e32 v149, 0xffff0000, v149
	v_fmac_f32_e32 v94, s44, v216
	v_fmac_f32_e32 v95, s44, v148
	v_fmac_f32_e32 v96, s44, v217
	v_fmac_f32_e32 v97, s44, v149
	global_store_dwordx4 v[140:141], v[94:97], off offset:64
	s_waitcnt vmcnt(16)
	v_permlane16_swap_b32_e32 v152, v154
	v_permlane16_swap_b32_e32 v153, v155
	v_lshlrev_b32_e32 v216, 16, v152
	v_and_b32_e32 v152, 0xffff0000, v152
	v_lshlrev_b32_e32 v217, 16, v153
	v_and_b32_e32 v153, 0xffff0000, v153
	v_fmac_f32_e32 v62, s44, v216
	v_fmac_f32_e32 v63, s44, v152
	v_fmac_f32_e32 v64, s44, v217
	v_fmac_f32_e32 v65, s44, v153
	global_store_dwordx4 v[140:141], v[62:65], off offset:128
	v_lshlrev_b32_e32 v216, 16, v154
	v_and_b32_e32 v154, 0xffff0000, v154
	v_lshlrev_b32_e32 v217, 16, v155
	v_and_b32_e32 v155, 0xffff0000, v155
	v_fmac_f32_e32 v30, s44, v216
	v_fmac_f32_e32 v31, s44, v154
	v_fmac_f32_e32 v32, s44, v217
	v_fmac_f32_e32 v33, s44, v155
	global_store_dwordx4 v[140:141], v[30:33], off offset:192
	v_lshl_add_u64 v[140:141], v[140:141], 0, s[10:11]
	s_waitcnt vmcnt(17)
	v_permlane16_swap_b32_e32 v156, v158
	v_permlane16_swap_b32_e32 v157, v159
	v_lshlrev_b32_e32 v216, 16, v156
	v_and_b32_e32 v156, 0xffff0000, v156
	v_lshlrev_b32_e32 v217, 16, v157
	v_and_b32_e32 v157, 0xffff0000, v157
	v_fmac_f32_e32 v122, s44, v216
	v_fmac_f32_e32 v123, s44, v156
	v_fmac_f32_e32 v124, s44, v217
	v_fmac_f32_e32 v125, s44, v157
	global_store_dwordx4 v[140:141], v[122:125], off offset:0
	v_lshlrev_b32_e32 v216, 16, v158
	v_and_b32_e32 v158, 0xffff0000, v158
	v_lshlrev_b32_e32 v217, 16, v159
	v_and_b32_e32 v159, 0xffff0000, v159
	v_fmac_f32_e32 v90, s44, v216
	v_fmac_f32_e32 v91, s44, v158
	v_fmac_f32_e32 v92, s44, v217
	v_fmac_f32_e32 v93, s44, v159
	global_store_dwordx4 v[140:141], v[90:93], off offset:64
	s_waitcnt vmcnt(18)
	v_permlane16_swap_b32_e32 v162, v164
	v_permlane16_swap_b32_e32 v163, v165
	v_lshlrev_b32_e32 v216, 16, v162
	v_and_b32_e32 v162, 0xffff0000, v162
	v_lshlrev_b32_e32 v217, 16, v163
	v_and_b32_e32 v163, 0xffff0000, v163
	v_fmac_f32_e32 v58, s44, v216
	v_fmac_f32_e32 v59, s44, v162
	v_fmac_f32_e32 v60, s44, v217
	v_fmac_f32_e32 v61, s44, v163
	global_store_dwordx4 v[140:141], v[58:61], off offset:128
	v_lshlrev_b32_e32 v216, 16, v164
	v_and_b32_e32 v164, 0xffff0000, v164
	v_lshlrev_b32_e32 v217, 16, v165
	v_and_b32_e32 v165, 0xffff0000, v165
	v_fmac_f32_e32 v26, s44, v216
	v_fmac_f32_e32 v27, s44, v164
	v_fmac_f32_e32 v28, s44, v217
	v_fmac_f32_e32 v29, s44, v165
	global_store_dwordx4 v[140:141], v[26:29], off offset:192
	v_lshl_add_u64 v[140:141], v[140:141], 0, s[10:11]
	s_waitcnt vmcnt(19)
	v_permlane16_swap_b32_e32 v166, v168
	v_permlane16_swap_b32_e32 v167, v169
	v_lshlrev_b32_e32 v216, 16, v166
	v_and_b32_e32 v166, 0xffff0000, v166
	v_lshlrev_b32_e32 v217, 16, v167
	v_and_b32_e32 v167, 0xffff0000, v167
	v_fmac_f32_e32 v118, s44, v216
	v_fmac_f32_e32 v119, s44, v166
	v_fmac_f32_e32 v120, s44, v217
	v_fmac_f32_e32 v121, s44, v167
	global_store_dwordx4 v[140:141], v[118:121], off offset:0
	v_lshlrev_b32_e32 v216, 16, v168
	v_and_b32_e32 v168, 0xffff0000, v168
	v_lshlrev_b32_e32 v217, 16, v169
	v_and_b32_e32 v169, 0xffff0000, v169
	v_fmac_f32_e32 v86, s44, v216
	v_fmac_f32_e32 v87, s44, v168
	v_fmac_f32_e32 v88, s44, v217
	v_fmac_f32_e32 v89, s44, v169
	global_store_dwordx4 v[140:141], v[86:89], off offset:64
	s_waitcnt vmcnt(20)
; DEVI float blo(unsigned u) { return __uint_as_float(u << 16); }
; DEVI float bhi(unsigned u) { return __uint_as_float(u & 0xffff0000u); }
;     ...
;         if (EPI == EPI_RESID || EPI == EPI_RESID_ATOMIC) {
;           f32x4 x = a;
;           if (EPI == EPI_RESID || kpart == 0) {
;             const u32x2 xr = *(const u32x2*)((const u16*)(p.ws + WS_XB) + (size_t)row * 1024 + col);
;             x[0] += ALPHA * blo(xr[0]); x[1] += ALPHA * bhi(xr[0]); x[2] += ALPHA * blo(xr[1]); x[3] += ALPHA * bhi(xr[1]);
;           }
;           if (EPI == EPI_RESID) *(f32x4*)((float*)(p.ws + WS_XF) + (size_t)row * 1024 + col) = x;
;           else *(f32x4*)((float*)(p.ws + WS_SLAB) + ((size_t)kpart * 512 + (row - T_P)) * 1024 + col) = x;
	v_permlane16_swap_b32_e32 v170, v172
	v_permlane16_swap_b32_e32 v171, v173
	v_lshlrev_b32_e32 v216, 16, v170
	v_and_b32_e32 v170, 0xffff0000, v170
	v_lshlrev_b32_e32 v217, 16, v171
	v_and_b32_e32 v171, 0xffff0000, v171
	v_fmac_f32_e32 v54, s44, v216
	v_fmac_f32_e32 v55, s44, v170
	v_fmac_f32_e32 v56, s44, v217
	v_fmac_f32_e32 v57, s44, v171
	global_store_dwordx4 v[140:141], v[54:57], off offset:128
	v_lshlrev_b32_e32 v216, 16, v172
	v_and_b32_e32 v172, 0xffff0000, v172
	v_lshlrev_b32_e32 v217, 16, v173
	v_and_b32_e32 v173, 0xffff0000, v173
	v_fmac_f32_e32 v22, s44, v216
	v_fmac_f32_e32 v23, s44, v172
	v_fmac_f32_e32 v24, s44, v217
	v_fmac_f32_e32 v25, s44, v173
	global_store_dwordx4 v[140:141], v[22:25], off offset:192
	v_lshl_add_u64 v[140:141], v[140:141], 0, s[10:11]
	s_waitcnt vmcnt(21)
	v_permlane16_swap_b32_e32 v176, v178
	v_permlane16_swap_b32_e32 v177, v179
	v_lshlrev_b32_e32 v216, 16, v176
	v_and_b32_e32 v176, 0xffff0000, v176
	v_lshlrev_b32_e32 v217, 16, v177
	v_and_b32_e32 v177, 0xffff0000, v177
	v_fmac_f32_e32 v114, s44, v216
	v_fmac_f32_e32 v115, s44, v176
	v_fmac_f32_e32 v116, s44, v217
	v_fmac_f32_e32 v117, s44, v177
	global_store_dwordx4 v[140:141], v[114:117], off offset:0
	v_lshlrev_b32_e32 v216, 16, v178
	v_and_b32_e32 v178, 0xffff0000, v178
	v_lshlrev_b32_e32 v217, 16, v179
	v_and_b32_e32 v179, 0xffff0000, v179
	v_fmac_f32_e32 v82, s44, v216
	v_fmac_f32_e32 v83, s44, v178
	v_fmac_f32_e32 v84, s44, v217
	v_fmac_f32_e32 v85, s44, v179
	global_store_dwordx4 v[140:141], v[82:85], off offset:64
	s_waitcnt vmcnt(22)
	v_permlane16_swap_b32_e32 v180, v182
	v_permlane16_swap_b32_e32 v181, v183
	v_lshlrev_b32_e32 v216, 16, v180
	v_and_b32_e32 v180, 0xffff0000, v180
	v_lshlrev_b32_e32 v217, 16, v181
	v_and_b32_e32 v181, 0xffff0000, v181
	v_fmac_f32_e32 v50, s44, v216
	v_fmac_f32_e32 v51, s44, v180
	v_fmac_f32_e32 v52, s44, v217
	v_fmac_f32_e32 v53, s44, v181
	global_store_dwordx4 v[140:141], v[50:53], off offset:128
	v_lshlrev_b32_e32 v216, 16, v182
	v_and_b32_e32 v182, 0xffff0000, v182
	v_lshlrev_b32_e32 v217, 16, v183
	v_and_b32_e32 v183, 0xffff0000, v183
	v_fmac_f32_e32 v18, s44, v216
	v_fmac_f32_e32 v19, s44, v182
	v_fmac_f32_e32 v20, s44, v217
	v_fmac_f32_e32 v21, s44, v183
	global_store_dwordx4 v[140:141], v[18:21], off offset:192
	v_lshl_add_u64 v[140:141], v[140:141], 0, s[10:11]
	s_waitcnt vmcnt(23)
	v_permlane16_swap_b32_e32 v184, v186
	v_permlane16_swap_b32_e32 v185, v187
	v_lshlrev_b32_e32 v216, 16, v184
	v_and_b32_e32 v184, 0xffff0000, v184
	v_lshlrev_b32_e32 v217, 16, v185
	v_and_b32_e32 v185, 0xffff0000, v185
	v_fmac_f32_e32 v110, s44, v216
	v_fmac_f32_e32 v111, s44, v184
	v_fmac_f32_e32 v112, s44, v217
	v_fmac_f32_e32 v113, s44, v185
	global_store_dwordx4 v[140:141], v[110:113], off offset:0
	v_lshlrev_b32_e32 v216, 16, v186
	v_and_b32_e32 v186, 0xffff0000, v186
	v_lshlrev_b32_e32 v217, 16, v187
	v_and_b32_e32 v187, 0xffff0000, v187
	v_fmac_f32_e32 v78, s44, v216
	v_fmac_f32_e32 v79, s44, v186
	v_fmac_f32_e32 v80, s44, v217
	v_fmac_f32_e32 v81, s44, v187
	global_store_dwordx4 v[140:141], v[78:81], off offset:64
	s_waitcnt vmcnt(24)
	v_permlane16_swap_b32_e32 v188, v190
	v_permlane16_swap_b32_e32 v189, v191
	v_lshlrev_b32_e32 v216, 16, v188
	v_and_b32_e32 v188, 0xffff0000, v188
	v_lshlrev_b32_e32 v217, 16, v189
	v_and_b32_e32 v189, 0xffff0000, v189
	v_fmac_f32_e32 v46, s44, v216
	v_fmac_f32_e32 v47, s44, v188
	v_fmac_f32_e32 v48, s44, v217
	v_fmac_f32_e32 v49, s44, v189
	global_store_dwordx4 v[140:141], v[46:49], off offset:128
	v_lshlrev_b32_e32 v216, 16, v190
	v_and_b32_e32 v190, 0xffff0000, v190
	v_lshlrev_b32_e32 v217, 16, v191
	v_and_b32_e32 v191, 0xffff0000, v191
	v_fmac_f32_e32 v14, s44, v216
	v_fmac_f32_e32 v15, s44, v190
	v_fmac_f32_e32 v16, s44, v217
	v_fmac_f32_e32 v17, s44, v191
	global_store_dwordx4 v[140:141], v[14:17], off offset:192
	v_lshl_add_u64 v[140:141], v[140:141], 0, s[10:11]
	s_waitcnt vmcnt(25)
	v_permlane16_swap_b32_e32 v192, v194
	v_permlane16_swap_b32_e32 v193, v195
	v_lshlrev_b32_e32 v216, 16, v192
	v_and_b32_e32 v192, 0xffff0000, v192
	v_lshlrev_b32_e32 v217, 16, v193
	v_and_b32_e32 v193, 0xffff0000, v193
	v_fmac_f32_e32 v106, s44, v216
	v_fmac_f32_e32 v107, s44, v192
	v_fmac_f32_e32 v108, s44, v217
	v_fmac_f32_e32 v109, s44, v193
	global_store_dwordx4 v[140:141], v[106:109], off offset:0
	v_lshlrev_b32_e32 v216, 16, v194
	v_and_b32_e32 v194, 0xffff0000, v194
	v_lshlrev_b32_e32 v217, 16, v195
	v_and_b32_e32 v195, 0xffff0000, v195
	v_fmac_f32_e32 v74, s44, v216
	v_fmac_f32_e32 v75, s44, v194
	v_fmac_f32_e32 v76, s44, v217
	v_fmac_f32_e32 v77, s44, v195
	global_store_dwordx4 v[140:141], v[74:77], off offset:64
	s_waitcnt vmcnt(26)
	v_permlane16_swap_b32_e32 v196, v198
	v_permlane16_swap_b32_e32 v197, v199
	v_lshlrev_b32_e32 v216, 16, v196
	v_and_b32_e32 v196, 0xffff0000, v196
	v_lshlrev_b32_e32 v217, 16, v197
	v_and_b32_e32 v197, 0xffff0000, v197
	v_fmac_f32_e32 v42, s44, v216
	v_fmac_f32_e32 v43, s44, v196
	v_fmac_f32_e32 v44, s44, v217
	v_fmac_f32_e32 v45, s44, v197
	global_store_dwordx4 v[140:141], v[42:45], off offset:128
	v_lshlrev_b32_e32 v216, 16, v198
	v_and_b32_e32 v198, 0xffff0000, v198
	v_lshlrev_b32_e32 v217, 16, v199
	v_and_b32_e32 v199, 0xffff0000, v199
	v_fmac_f32_e32 v10, s44, v216
	v_fmac_f32_e32 v11, s44, v198
	v_fmac_f32_e32 v12, s44, v217
	v_fmac_f32_e32 v13, s44, v199
	global_store_dwordx4 v[140:141], v[10:13], off offset:192
	v_lshl_add_u64 v[140:141], v[140:141], 0, s[10:11]
	s_waitcnt vmcnt(27)
; #define LAS __attribute__((address_space(3)))
; DEVI int tidx() { int t = threadIdx.x; asm volatile("" : "+v"(t)); return t; }
; DEVI float blo(unsigned u) { return __uint_as_float(u << 16); }
; DEVI float bhi(unsigned u) { return __uint_as_float(u & 0xffff0000u); }
;   const int tid = tidx(), lane = tid & 63, wid = tid >> 6;
;   const int wm = wid >> 1, wn = wid & 1, r16 = lane & 15, quad = lane >> 4;
;   f32x4 acc[4][8];
; #pragma unroll
;   for (int i = 0; i < 4; i++)
; #pragma unroll
;     for (int j = 0; j < 8; j++) acc[i][j] = (f32x4){0.f, 0.f, 0.f, 0.f};
;   const int nk = (nk_part < 0) ? (K >> 5) : nk_part;
;   const int lrow = tid >> 2, lpc = tid & 3;
;   const int lch = lpc ^ ((0x78 >> (((lrow >> 2) & 3) * 2)) & 3);
;   const u16* ga = A + (size_t)(m0 + lrow) * lda + kbeg + lch * 8;
;   const u16* gb = Bt + (size_t)(n0 + lrow) * K + kbeg + lch * 8;
;   const size_t ga1 = (size_t)64 * lda, gb1 = (size_t)64 * K;
;   const unsigned lds0 = (unsigned)(uintptr_t)(LAS char*)smem + (unsigned)__builtin_amdgcn_readfirstlane(wid) * 1024u;
;     ...
;         if (EPI == EPI_RESID || EPI == EPI_RESID_ATOMIC) {
;           f32x4 x = a;
;           if (EPI == EPI_RESID || kpart == 0) {
;             const u32x2 xr = *(const u32x2*)((const u16*)(p.ws + WS_XB) + (size_t)row * 1024 + col);
;             x[0] += ALPHA * blo(xr[0]); x[1] += ALPHA * bhi(xr[0]); x[2] += ALPHA * blo(xr[1]); x[3] += ALPHA * bhi(xr[1]);
;           }
;           if (EPI == EPI_RESID) *(f32x4*)((float*)(p.ws + WS_XF) + (size_t)row * 1024 + col) = x;
;           else *(f32x4*)((float*)(p.ws + WS_SLAB) + ((size_t)kpart * 512 + (row - T_P)) * 1024 + col) = x;
	v_permlane16_swap_b32_e32 v200, v202
	v_permlane16_swap_b32_e32 v201, v203
	v_lshlrev_b32_e32 v216, 16, v200
	v_and_b32_e32 v200, 0xffff0000, v200
	v_lshlrev_b32_e32 v217, 16, v201
	v_and_b32_e32 v201, 0xffff0000, v201
	v_fmac_f32_e32 v102, s44, v216
	v_fmac_f32_e32 v103, s44, v200
	v_fmac_f32_e32 v104, s44, v217
	v_fmac_f32_e32 v105, s44, v201
	global_store_dwordx4 v[140:141], v[102:105], off offset:0
	v_lshlrev_b32_e32 v216, 16, v202
	v_and_b32_e32 v202, 0xffff0000, v202
	v_lshlrev_b32_e32 v217, 16, v203
	v_and_b32_e32 v203, 0xffff0000, v203
	v_fmac_f32_e32 v70, s44, v216
	v_fmac_f32_e32 v71, s44, v202
	v_fmac_f32_e32 v72, s44, v217
	v_fmac_f32_e32 v73, s44, v203
	global_store_dwordx4 v[140:141], v[70:73], off offset:64
	s_waitcnt vmcnt(28)
	v_permlane16_swap_b32_e32 v204, v206
	v_permlane16_swap_b32_e32 v205, v207
	v_lshlrev_b32_e32 v216, 16, v204
	v_and_b32_e32 v204, 0xffff0000, v204
	v_lshlrev_b32_e32 v217, 16, v205
	v_and_b32_e32 v205, 0xffff0000, v205
	v_fmac_f32_e32 v38, s44, v216
	v_fmac_f32_e32 v39, s44, v204
	v_fmac_f32_e32 v40, s44, v217
	v_fmac_f32_e32 v41, s44, v205
	global_store_dwordx4 v[140:141], v[38:41], off offset:128
	v_lshlrev_b32_e32 v216, 16, v206
	v_and_b32_e32 v206, 0xffff0000, v206
	v_lshlrev_b32_e32 v217, 16, v207
	v_and_b32_e32 v207, 0xffff0000, v207
	v_fmac_f32_e32 v6, s44, v216
	v_fmac_f32_e32 v7, s44, v206
	v_fmac_f32_e32 v8, s44, v217
	v_fmac_f32_e32 v9, s44, v207
	global_store_dwordx4 v[140:141], v[6:9], off offset:192
	v_lshl_add_u64 v[140:141], v[140:141], 0, s[10:11]
	s_waitcnt vmcnt(29)
	v_permlane16_swap_b32_e32 v208, v210
	v_permlane16_swap_b32_e32 v209, v211
	v_lshlrev_b32_e32 v216, 16, v208
	v_and_b32_e32 v208, 0xffff0000, v208
	v_lshlrev_b32_e32 v217, 16, v209
	v_and_b32_e32 v209, 0xffff0000, v209
	v_fmac_f32_e32 v98, s44, v216
	v_fmac_f32_e32 v99, s44, v208
	v_fmac_f32_e32 v100, s44, v217
	v_fmac_f32_e32 v101, s44, v209
	global_store_dwordx4 v[140:141], v[98:101], off offset:0
	v_lshlrev_b32_e32 v216, 16, v210
	v_and_b32_e32 v210, 0xffff0000, v210
	v_lshlrev_b32_e32 v217, 16, v211
	v_and_b32_e32 v211, 0xffff0000, v211
	v_fmac_f32_e32 v66, s44, v216
	v_fmac_f32_e32 v67, s44, v210
	v_fmac_f32_e32 v68, s44, v217
	v_fmac_f32_e32 v69, s44, v211
	global_store_dwordx4 v[140:141], v[66:69], off offset:64
	s_waitcnt vmcnt(30)
	v_permlane16_swap_b32_e32 v212, v214
	v_permlane16_swap_b32_e32 v213, v215
	v_lshlrev_b32_e32 v216, 16, v212
	v_and_b32_e32 v212, 0xffff0000, v212
	v_lshlrev_b32_e32 v217, 16, v213
	v_and_b32_e32 v213, 0xffff0000, v213
	v_fmac_f32_e32 v34, s44, v216
	v_fmac_f32_e32 v35, s44, v212
	v_fmac_f32_e32 v36, s44, v217
	v_fmac_f32_e32 v37, s44, v213
	global_store_dwordx4 v[140:141], v[34:37], off offset:128
	v_lshlrev_b32_e32 v216, 16, v214
	v_and_b32_e32 v214, 0xffff0000, v214
	v_lshlrev_b32_e32 v217, 16, v215
	v_and_b32_e32 v215, 0xffff0000, v215
	v_fmac_f32_e32 v2, s44, v216
	v_fmac_f32_e32 v3, s44, v214
	v_fmac_f32_e32 v4, s44, v217
	v_fmac_f32_e32 v5, s44, v215
	global_store_dwordx4 v[140:141], v[2:5], off offset:192
	s_branch .LBB0_41
.LBB0_116:
	s_and_b64 vcc, exec, s[2:3]
	s_cbranch_vccz .LBB0_41
	s_lshr_b32 s45, s38, 6
	s_and_b32 s46, s38, 63
	s_lshr_b32 s42, s46, 3
	s_and_b32 s46, s46, 7
	s_lshl_b32 s45, s45, 3
	s_add_i32 s45, s45, s46
	s_cmp_lt_u32 s45, 64
	s_cselect_b32 s44, 1, 0
	v_readlane_b32 s2, v250, 5
	v_readlane_b32 s3, v250, 6
	v_readlane_b32 s46, v254, 62
	s_mul_i32 s40, s45, 0x160000
	s_add_u32 s4, s2, s40
	s_addc_u32 s5, s3, 0
	s_add_u32 s4, s4, 0xef40000
	s_addc_u32 s5, s5, 0
	s_mul_i32 s40, s46, 0x580000
	s_mul_i32 s41, s42, 0xb0000
	s_add_i32 s40, s40, s41
	s_add_u32 s10, s2, s40
	s_addc_u32 s11, s3, 0
	s_add_u32 s10, s10, 0x19a00000
	s_addc_u32 s11, s11, 0
	s_movk_i32 s39, 0x78
	v_lshrrev_b32_e32 v0, 2, v145
	v_and_b32_e32 v131, 3, v145
	v_bfe_u32 v136, v145, 4, 2
	v_lshlrev_b32_e32 v136, 1, v136
	v_lshrrev_b32_e64 v136, v136, s39
	v_and_b32_e32 v136, 3, v136
	v_xor_b32_e32 v131, v131, v136
	v_lshlrev_b32_e32 v131, 4, v131
	s_movk_i32 s41, 0x1600
	v_mad_u32_u24 v0, v0, s41, v131
	v_bfe_u32 v137, v145, 2, 1
	s_movk_i32 s41, 0x15c0
	v_mul_u32_u24_e32 v136, s41, v137
	v_sub_u32_e32 v136, v0, v136
	v_mov_b32_e32 v137, 0
	v_lshl_add_u64 v[134:135], s[10:11], 0, v[136:137]
	v_bfe_u32 v137, v145, 2, 1
	s_mul_i32 s41, s44, 0x15c0
	v_mul_u32_u24_e32 v136, s41, v137
	v_sub_u32_e32 v0, v0, v136
	s_lshl_b32 s12, s44, 6
	s_add_i32 s12, s12, 64
	s_mov_b32 s13, 0
	v_lshl_add_u64 v[132:133], s[4:5], 0, v[0:1]
	v_bfe_u32 v136, v145, 2, 2
	v_lshlrev_b32_e32 v136, 1, v136
	v_lshrrev_b32_e64 v136, v136, s39
	v_and_b32_e32 v136, 3, v136
	v_bfe_u32 v137, v145, 4, 2
	v_xor_b32_e32 v136, v136, v137
	v_lshlrev_b32_e32 v136, 4, v136
	v_and_b32_e32 v131, 15, v145
	v_lshl_or_b32 v136, v131, 6, v136
	v_bfe_u32 v137, v145, 6, 1
	v_lshl_or_b32 v137, v137, 12, v136
	v_lshrrev_b32_e32 v0, 7, v145
	v_lshl_or_b32 v136, v0, 13, v136
	v_and_b32_e32 v140, 1, v131
	v_lshl_or_b32 v131, v0, 7, v131
	v_bfe_u32 v0, v145, 4, 2
	v_lshlrev_b32_e32 v0, 3, v0
	v_bfe_u32 v141, v145, 6, 1
	s_lshl_b32 s40, s45, 19
	s_lshl_b32 s41, s42, 9
	s_add_i32 s40, s40, s41
	s_add_u32 s4, s2, s40
	s_addc_u32 s5, s3, 0
	s_add_u32 s4, s4, 0x4200000
	s_addc_u32 s5, s5, 0
	v_lshlrev_b32_e32 v138, 11, v131
	v_lshl_add_u32 v138, v141, 8, v138
	v_bfe_u32 v139, v145, 4, 1
	v_lshl_add_u32 v138, v139, 5, v138
	v_bfe_u32 v139, v145, 5, 1
	v_lshl_add_u32 v138, v139, 4, v138
	s_movk_i32 s41, 1984
	v_mul_u32_u24_e32 v139, s41, v140
	v_sub_u32_e32 v138, v138, v139
	v_mov_b32_e32 v139, 0
	v_lshl_add_u64 v[138:139], s[4:5], 0, v[138:139]
	s_lshl_b32 s40, s45, 20
	s_lshl_b32 s41, s42, 9
	s_add_i32 s40, s40, s41
	s_add_u32 s10, s2, s40
; #define LAS __attribute__((address_space(3)))
; DEVI int tidx() { int t = threadIdx.x; asm volatile("" : "+v"(t)); return t; }
;   const int tid = tidx(), lane = tid & 63, wid = tid >> 6;
;   const int wm = wid >> 1, wn = wid & 1, r16 = lane & 15, quad = lane >> 4;
;   f32x4 acc[4][8];
; #pragma unroll
;   for (int i = 0; i < 4; i++)
; #pragma unroll
;     for (int j = 0; j < 8; j++) acc[i][j] = (f32x4){0.f, 0.f, 0.f, 0.f};
;   const int nk = (nk_part < 0) ? (K >> 5) : nk_part;
;   const int lrow = tid >> 2, lpc = tid & 3;
;   const int lch = lpc ^ ((0x78 >> (((lrow >> 2) & 3) * 2)) & 3);
;   const u16* ga = A + (size_t)(m0 + lrow) * lda + kbeg + lch * 8;
;   const u16* gb = Bt + (size_t)(n0 + lrow) * K + kbeg + lch * 8;
;   const size_t ga1 = (size_t)64 * lda, gb1 = (size_t)64 * K;
;   const unsigned lds0 = (unsigned)(uintptr_t)(LAS char*)smem + (unsigned)__builtin_amdgcn_readfirstlane(wid) * 1024u;
;     ...
;   __syncthreads();
;   G2_STAGE(0); G2_STAGE(1);
;   const int fsw = (0x78 >> (((r16 >> 2) & 3) * 2)) & 3;
;   const int aoff = (wm * 128 + r16) * 64 + ((quad ^ fsw) << 4);
;   const int boff = 16384 + (wn * 64 + r16) * 64 + ((quad ^ fsw) << 4);
;   for (int kt = 0; kt < nk; kt++) {
;     if (kt + 1 < nk) asm volatile("s_waitcnt vmcnt(6)" ::: "memory");
;     else asm volatile("s_waitcnt vmcnt(0)" ::: "memory");
;     __builtin_amdgcn_s_barrier();
;     asm volatile("" ::: "memory");
;     if (kt + 2 < nk) G2_STAGE(kt + 2);
	s_addc_u32 s11, s3, 0
	v_lshlrev_b32_e32 v140, 12, v131
	v_lshl_add_u32 v140, v141, 8, v140
	v_lshl_add_u32 v140, v0, 1, v140
	v_mov_b32_e32 v141, 0
	v_lshl_add_u64 v[140:141], s[10:11], 0, v[140:141]
	s_mov_b32 s2, 0x58000
	s_mov_b32 s3, 0
	v_lshrrev_b32_e32 v0, 6, v145
	v_lshlrev_b32_e32 v0, 10, v0
	s_nop 0
	v_readfirstlane_b32 s46, v0
	s_mov_b32 s43, m0
	s_mov_b32 s4, 128
	s_mov_b32 s5, 0
	v_mov_b32_e32 v2, 0
	v_mov_b32_e32 v3, 0
	v_mov_b32_e32 v4, 0
	v_mov_b32_e32 v5, 0
	v_mov_b32_e32 v6, 0
	v_mov_b32_e32 v7, 0
	v_mov_b32_e32 v8, 0
	v_mov_b32_e32 v9, 0
	v_mov_b32_e32 v10, 0
	v_mov_b32_e32 v11, 0
	v_mov_b32_e32 v12, 0
	v_mov_b32_e32 v13, 0
	v_mov_b32_e32 v14, 0
	v_mov_b32_e32 v15, 0
	v_mov_b32_e32 v16, 0
	v_mov_b32_e32 v17, 0
	v_mov_b32_e32 v18, 0
	v_mov_b32_e32 v19, 0
	v_mov_b32_e32 v20, 0
	v_mov_b32_e32 v21, 0
	v_mov_b32_e32 v22, 0
	v_mov_b32_e32 v23, 0
	v_mov_b32_e32 v24, 0
	v_mov_b32_e32 v25, 0
	v_mov_b32_e32 v26, 0
	v_mov_b32_e32 v27, 0
	v_mov_b32_e32 v28, 0
	v_mov_b32_e32 v29, 0
	v_mov_b32_e32 v30, 0
	v_mov_b32_e32 v31, 0
	v_mov_b32_e32 v32, 0
	v_mov_b32_e32 v33, 0
	v_mov_b32_e32 v34, 0
	v_mov_b32_e32 v35, 0
	v_mov_b32_e32 v36, 0
	v_mov_b32_e32 v37, 0
	v_mov_b32_e32 v38, 0
	v_mov_b32_e32 v39, 0
	v_mov_b32_e32 v40, 0
	v_mov_b32_e32 v41, 0
	v_mov_b32_e32 v42, 0
	v_mov_b32_e32 v43, 0
	v_mov_b32_e32 v44, 0
	v_mov_b32_e32 v45, 0
	v_mov_b32_e32 v46, 0
	v_mov_b32_e32 v47, 0
	v_mov_b32_e32 v48, 0
	v_mov_b32_e32 v49, 0
	v_mov_b32_e32 v50, 0
	v_mov_b32_e32 v51, 0
	v_mov_b32_e32 v52, 0
	v_mov_b32_e32 v53, 0
	v_mov_b32_e32 v54, 0
	v_mov_b32_e32 v55, 0
	v_mov_b32_e32 v56, 0
	v_mov_b32_e32 v57, 0
	v_mov_b32_e32 v58, 0
	v_mov_b32_e32 v59, 0
	v_mov_b32_e32 v60, 0
	v_mov_b32_e32 v61, 0
	v_mov_b32_e32 v62, 0
	v_mov_b32_e32 v63, 0
	v_mov_b32_e32 v64, 0
	v_mov_b32_e32 v65, 0
	v_mov_b32_e32 v66, 0
	v_mov_b32_e32 v67, 0
	v_mov_b32_e32 v68, 0
	v_mov_b32_e32 v69, 0
	v_mov_b32_e32 v70, 0
	v_mov_b32_e32 v71, 0
	v_mov_b32_e32 v72, 0
	v_mov_b32_e32 v73, 0
	v_mov_b32_e32 v74, 0
	v_mov_b32_e32 v75, 0
	v_mov_b32_e32 v76, 0
	v_mov_b32_e32 v77, 0
	v_mov_b32_e32 v78, 0
	v_mov_b32_e32 v79, 0
	v_mov_b32_e32 v80, 0
	v_mov_b32_e32 v81, 0
	v_mov_b32_e32 v82, 0
	v_mov_b32_e32 v83, 0
	v_mov_b32_e32 v84, 0
	v_mov_b32_e32 v85, 0
	v_mov_b32_e32 v86, 0
	v_mov_b32_e32 v87, 0
	v_mov_b32_e32 v88, 0
	v_mov_b32_e32 v89, 0
	v_mov_b32_e32 v90, 0
	v_mov_b32_e32 v91, 0
	v_mov_b32_e32 v92, 0
	v_mov_b32_e32 v93, 0
	v_mov_b32_e32 v94, 0
	v_mov_b32_e32 v95, 0
	v_mov_b32_e32 v96, 0
	v_mov_b32_e32 v97, 0
	v_mov_b32_e32 v98, 0
	v_mov_b32_e32 v99, 0
	v_mov_b32_e32 v100, 0
	v_mov_b32_e32 v101, 0
	v_mov_b32_e32 v102, 0
	v_mov_b32_e32 v103, 0
	v_mov_b32_e32 v104, 0
	v_mov_b32_e32 v105, 0
	v_mov_b32_e32 v106, 0
	v_mov_b32_e32 v107, 0
	v_mov_b32_e32 v108, 0
	v_mov_b32_e32 v109, 0
	v_mov_b32_e32 v110, 0
	v_mov_b32_e32 v111, 0
	v_mov_b32_e32 v112, 0
	v_mov_b32_e32 v113, 0
	v_mov_b32_e32 v114, 0
	v_mov_b32_e32 v115, 0
	v_mov_b32_e32 v116, 0
	v_mov_b32_e32 v117, 0
	v_mov_b32_e32 v118, 0
	v_mov_b32_e32 v119, 0
	v_mov_b32_e32 v120, 0
	v_mov_b32_e32 v121, 0
	v_mov_b32_e32 v122, 0
	v_mov_b32_e32 v123, 0
	v_mov_b32_e32 v124, 0
	v_mov_b32_e32 v125, 0
	v_mov_b32_e32 v126, 0
	v_mov_b32_e32 v127, 0
	v_mov_b32_e32 v128, 0
	v_mov_b32_e32 v129, 0
	s_barrier
	s_add_i32 s42, s46, 0x0
	s_mov_b32 m0, s42
	v_lshl_add_u64 v[142:143], v[132:133], 0, s[2:3]
	global_load_lds_dwordx4 v[132:133], off
	s_addk_i32 m0, 0x1000
	s_nop 0
	global_load_lds_dwordx4 v[142:143], off
	v_lshl_add_u64 v[142:143], v[142:143], 0, s[2:3]
	s_addk_i32 m0, 0x1000
	s_nop 0
	global_load_lds_dwordx4 v[142:143], off
	v_lshl_add_u64 v[142:143], v[142:143], 0, s[2:3]
	s_addk_i32 m0, 0x1000
	s_nop 0
	global_load_lds_dwordx4 v[142:143], off
	s_addk_i32 m0, 0x1000
	v_lshl_add_u64 v[142:143], v[134:135], 0, s[2:3]
	s_nop 0
	global_load_lds_dwordx4 v[134:135], off
	s_addk_i32 m0, 0x1000
	v_lshl_add_u64 v[132:133], v[132:133], 0, s[12:13]
	s_nop 0
	global_load_lds_dwordx4 v[142:143], off
	v_lshl_add_u64 v[134:135], v[134:135], 0, s[4:5]
	s_nop 0
	s_add_i32 s42, s46, 0x6000
	s_mov_b32 m0, s42
	v_lshl_add_u64 v[142:143], v[132:133], 0, s[2:3]
	global_load_lds_dwordx4 v[132:133], off
	s_addk_i32 m0, 0x1000
	s_nop 0
	global_load_lds_dwordx4 v[142:143], off
	v_lshl_add_u64 v[142:143], v[142:143], 0, s[2:3]
	s_addk_i32 m0, 0x1000
	s_nop 0
	global_load_lds_dwordx4 v[142:143], off
	v_lshl_add_u64 v[142:143], v[142:143], 0, s[2:3]
	s_addk_i32 m0, 0x1000
	s_nop 0
	global_load_lds_dwordx4 v[142:143], off
	s_addk_i32 m0, 0x1000
	v_lshl_add_u64 v[142:143], v[134:135], 0, s[2:3]
	s_nop 0
	global_load_lds_dwordx4 v[134:135], off
	s_addk_i32 m0, 0x1000
	v_lshl_add_u64 v[132:133], v[132:133], 0, s[12:13]
	s_nop 0
	global_load_lds_dwordx4 v[142:143], off
	v_lshl_add_u64 v[134:135], v[134:135], 0, s[4:5]
	s_nop 0
	s_add_i32 s42, s46, 0xc000
	s_mov_b32 m0, s42
	v_lshl_add_u64 v[142:143], v[132:133], 0, s[2:3]
	global_load_lds_dwordx4 v[132:133], off
	s_addk_i32 m0, 0x1000
	s_nop 0
	global_load_lds_dwordx4 v[142:143], off
	v_lshl_add_u64 v[142:143], v[142:143], 0, s[2:3]
	s_addk_i32 m0, 0x1000
	s_nop 0
	global_load_lds_dwordx4 v[142:143], off
	v_lshl_add_u64 v[142:143], v[142:143], 0, s[2:3]
	s_addk_i32 m0, 0x1000
	s_nop 0
	global_load_lds_dwordx4 v[142:143], off
	s_addk_i32 m0, 0x1000
	v_lshl_add_u64 v[142:143], v[134:135], 0, s[2:3]
	s_nop 0
	global_load_lds_dwordx4 v[134:135], off
	s_addk_i32 m0, 0x1000
	v_lshl_add_u64 v[132:133], v[132:133], 0, s[12:13]
	s_nop 0
	global_load_lds_dwordx4 v[142:143], off
	v_lshl_add_u64 v[134:135], v[134:135], 0, s[4:5]
	s_nop 0
	s_waitcnt vmcnt(12)
	s_barrier
	ds_read_b128 v[146:149], v136 offset:0
	ds_read_b128 v[152:155], v136 offset:1024
	ds_read_b128 v[156:159], v136 offset:2048
	ds_read_b128 v[162:165], v136 offset:3072
	ds_read_b128 v[166:169], v136 offset:4096
	ds_read_b128 v[170:173], v136 offset:5120
	ds_read_b128 v[176:179], v136 offset:6144
	ds_read_b128 v[180:183], v136 offset:7168
	ds_read_b128 v[184:187], v137 offset:16384
	ds_read_b128 v[188:191], v137 offset:17408
	ds_read_b128 v[192:195], v137 offset:18432
	ds_read_b128 v[196:199], v137 offset:19456
	s_movk_i32 s40, 0x6000
	s_mov_b32 s41, 0
	s_movk_i32 s39, 42
;     ...
;   for (int kt = 0; kt < nk; kt++) {
;     if (kt + 1 < nk) asm volatile("s_waitcnt vmcnt(6)" ::: "memory");
;     else asm volatile("s_waitcnt vmcnt(0)" ::: "memory");
;     __builtin_amdgcn_s_barrier();
;     asm volatile("" ::: "memory");
;     if (kt + 2 < nk) G2_STAGE(kt + 2);
;     const char* cS = smem + (kt % 3) * 24576;
;     bf16x8 xa[8], wb[4];
; #pragma unroll
;     for (int f = 0; f < 8; f++) xa[f] = *(const bf16x8*)(cS + aoff + f * 1024);
; #pragma unroll
;     for (int f = 0; f < 4; f++) wb[f] = *(const bf16x8*)(cS + boff + f * 1024);
; #pragma unroll
;     for (int nf = 0; nf < 4; nf++)
; #pragma unroll
;       for (int mf = 0; mf < 8; mf++)
;         acc[nf][mf] = __builtin_amdgcn_mfma_f32_16x16x32_bf16(wb[nf], xa[mf], acc[nf][mf], 0, 0, 0);
;   }
.Lt11_loop:
	s_waitcnt vmcnt(6) lgkmcnt(0)
	s_barrier
	v_add_u32_e32 v144, s40, v136
	v_mfma_f32_16x16x32_bf16 v[126:129], v[184:187], v[146:149], v[126:129]
	ds_read_b128 v[200:203], v144 offset:0
	v_mfma_f32_16x16x32_bf16 v[122:125], v[184:187], v[152:155], v[122:125]
	ds_read_b128 v[204:207], v144 offset:1024
	v_mfma_f32_16x16x32_bf16 v[118:121], v[184:187], v[156:159], v[118:121]
	ds_read_b128 v[208:211], v144 offset:2048
	v_mfma_f32_16x16x32_bf16 v[114:117], v[184:187], v[162:165], v[114:117]
	ds_read_b128 v[212:215], v144 offset:3072
	v_mfma_f32_16x16x32_bf16 v[110:113], v[184:187], v[166:169], v[110:113]
	ds_read_b128 v[216:219], v144 offset:4096
	v_mfma_f32_16x16x32_bf16 v[106:109], v[184:187], v[170:173], v[106:109]
	ds_read_b128 v[220:223], v144 offset:5120
	v_mfma_f32_16x16x32_bf16 v[102:105], v[184:187], v[176:179], v[102:105]
	ds_read_b128 v[224:227], v144 offset:6144
	v_mfma_f32_16x16x32_bf16 v[98:101], v[184:187], v[180:183], v[98:101]
	ds_read_b128 v[228:231], v144 offset:7168
	v_mfma_f32_16x16x32_bf16 v[94:97], v[188:191], v[146:149], v[94:97]
	v_add_u32_e32 v144, s40, v137
	v_mfma_f32_16x16x32_bf16 v[90:93], v[188:191], v[152:155], v[90:93]
	v_mfma_f32_16x16x32_bf16 v[86:89], v[188:191], v[156:159], v[86:89]
	ds_read_b128 v[232:235], v144 offset:16384
	v_mfma_f32_16x16x32_bf16 v[82:85], v[188:191], v[162:165], v[82:85]
	ds_read_b128 v[236:239], v144 offset:17408
	v_mfma_f32_16x16x32_bf16 v[78:81], v[188:191], v[166:169], v[78:81]
	ds_read_b128 v[240:243], v144 offset:18432
	v_mfma_f32_16x16x32_bf16 v[74:77], v[188:191], v[170:173], v[74:77]
	ds_read_b128 v[244:247], v144 offset:19456
	s_add_i32 s42, s46, s41
	v_mfma_f32_16x16x32_bf16 v[70:73], v[188:191], v[176:179], v[70:73]
	s_mov_b32 m0, s42
	v_lshl_add_u64 v[142:143], v[132:133], 0, s[2:3]
	v_mfma_f32_16x16x32_bf16 v[66:69], v[188:191], v[180:183], v[66:69]
	global_load_lds_dwordx4 v[132:133], off
	s_addk_i32 m0, 0x1000
	v_mfma_f32_16x16x32_bf16 v[62:65], v[192:195], v[146:149], v[62:65]
	v_mfma_f32_16x16x32_bf16 v[58:61], v[192:195], v[152:155], v[58:61]
	v_mfma_f32_16x16x32_bf16 v[54:57], v[192:195], v[156:159], v[54:57]
	global_load_lds_dwordx4 v[142:143], off
	v_lshl_add_u64 v[142:143], v[142:143], 0, s[2:3]
	s_addk_i32 m0, 0x1000
	v_mfma_f32_16x16x32_bf16 v[50:53], v[192:195], v[162:165], v[50:53]
	v_mfma_f32_16x16x32_bf16 v[46:49], v[192:195], v[166:169], v[46:49]
	v_mfma_f32_16x16x32_bf16 v[42:45], v[192:195], v[170:173], v[42:45]
	global_load_lds_dwordx4 v[142:143], off
	v_lshl_add_u64 v[142:143], v[142:143], 0, s[2:3]
	s_addk_i32 m0, 0x1000
	v_mfma_f32_16x16x32_bf16 v[38:41], v[192:195], v[176:179], v[38:41]
	v_mfma_f32_16x16x32_bf16 v[34:37], v[192:195], v[180:183], v[34:37]
	v_mfma_f32_16x16x32_bf16 v[30:33], v[196:199], v[146:149], v[30:33]
	global_load_lds_dwordx4 v[142:143], off
	s_addk_i32 m0, 0x1000
	v_lshl_add_u64 v[142:143], v[134:135], 0, s[2:3]
	v_mfma_f32_16x16x32_bf16 v[26:29], v[196:199], v[152:155], v[26:29]
	v_mfma_f32_16x16x32_bf16 v[22:25], v[196:199], v[156:159], v[22:25]
	v_mfma_f32_16x16x32_bf16 v[18:21], v[196:199], v[162:165], v[18:21]
	global_load_lds_dwordx4 v[134:135], off
	s_addk_i32 m0, 0x1000
	v_lshl_add_u64 v[132:133], v[132:133], 0, s[12:13]
	v_mfma_f32_16x16x32_bf16 v[14:17], v[196:199], v[166:169], v[14:17]
	v_mfma_f32_16x16x32_bf16 v[10:13], v[196:199], v[170:173], v[10:13]
	v_mfma_f32_16x16x32_bf16 v[6:9], v[196:199], v[176:179], v[6:9]
	global_load_lds_dwordx4 v[142:143], off
	v_lshl_add_u64 v[134:135], v[134:135], 0, s[4:5]
	v_mfma_f32_16x16x32_bf16 v[2:5], v[196:199], v[180:183], v[2:5]
	s_mov_b32 s41, s40
	s_add_i32 s40, s40, 0x6000
	s_cmp_eq_u32 s40, 0x12000
	s_cselect_b32 s40, 0, s40
	s_waitcnt vmcnt(6) lgkmcnt(0)
	s_barrier
	v_add_u32_e32 v144, s40, v136
	v_mfma_f32_16x16x32_bf16 v[126:129], v[232:235], v[200:203], v[126:129]
	ds_read_b128 v[146:149], v144 offset:0
	v_mfma_f32_16x16x32_bf16 v[122:125], v[232:235], v[204:207], v[122:125]
	ds_read_b128 v[152:155], v144 offset:1024
	v_mfma_f32_16x16x32_bf16 v[118:121], v[232:235], v[208:211], v[118:121]
	ds_read_b128 v[156:159], v144 offset:2048
	v_mfma_f32_16x16x32_bf16 v[114:117], v[232:235], v[212:215], v[114:117]
	ds_read_b128 v[162:165], v144 offset:3072
	v_mfma_f32_16x16x32_bf16 v[110:113], v[232:235], v[216:219], v[110:113]
	ds_read_b128 v[166:169], v144 offset:4096
	v_mfma_f32_16x16x32_bf16 v[106:109], v[232:235], v[220:223], v[106:109]
	ds_read_b128 v[170:173], v144 offset:5120
	v_mfma_f32_16x16x32_bf16 v[102:105], v[232:235], v[224:227], v[102:105]
	ds_read_b128 v[176:179], v144 offset:6144
	v_mfma_f32_16x16x32_bf16 v[98:101], v[232:235], v[228:231], v[98:101]
	ds_read_b128 v[180:183], v144 offset:7168
	v_mfma_f32_16x16x32_bf16 v[94:97], v[236:239], v[200:203], v[94:97]
	v_add_u32_e32 v144, s40, v137
	v_mfma_f32_16x16x32_bf16 v[90:93], v[236:239], v[204:207], v[90:93]
	v_mfma_f32_16x16x32_bf16 v[86:89], v[236:239], v[208:211], v[86:89]
	ds_read_b128 v[184:187], v144 offset:16384
	v_mfma_f32_16x16x32_bf16 v[82:85], v[236:239], v[212:215], v[82:85]
	ds_read_b128 v[188:191], v144 offset:17408
	v_mfma_f32_16x16x32_bf16 v[78:81], v[236:239], v[216:219], v[78:81]
	ds_read_b128 v[192:195], v144 offset:18432
	v_mfma_f32_16x16x32_bf16 v[74:77], v[236:239], v[220:223], v[74:77]
	ds_read_b128 v[196:199], v144 offset:19456
	s_add_i32 s42, s46, s41
	v_mfma_f32_16x16x32_bf16 v[70:73], v[236:239], v[224:227], v[70:73]
	s_mov_b32 m0, s42
	v_lshl_add_u64 v[142:143], v[132:133], 0, s[2:3]
	v_mfma_f32_16x16x32_bf16 v[66:69], v[236:239], v[228:231], v[66:69]
	global_load_lds_dwordx4 v[132:133], off
	s_addk_i32 m0, 0x1000
	v_mfma_f32_16x16x32_bf16 v[62:65], v[240:243], v[200:203], v[62:65]
;     ...
;   for (int kt = 0; kt < nk; kt++) {
;     if (kt + 1 < nk) asm volatile("s_waitcnt vmcnt(6)" ::: "memory");
;     else asm volatile("s_waitcnt vmcnt(0)" ::: "memory");
;     __builtin_amdgcn_s_barrier();
;     asm volatile("" ::: "memory");
;     if (kt + 2 < nk) G2_STAGE(kt + 2);
;     const char* cS = smem + (kt % 3) * 24576;
;     bf16x8 xa[8], wb[4];
; #pragma unroll
;     for (int f = 0; f < 8; f++) xa[f] = *(const bf16x8*)(cS + aoff + f * 1024);
; #pragma unroll
;     for (int f = 0; f < 4; f++) wb[f] = *(const bf16x8*)(cS + boff + f * 1024);
; #pragma unroll
;     for (int nf = 0; nf < 4; nf++)
; #pragma unroll
;       for (int mf = 0; mf < 8; mf++)
;         acc[nf][mf] = __builtin_amdgcn_mfma_f32_16x16x32_bf16(wb[nf], xa[mf], acc[nf][mf], 0, 0, 0);
;   }
	v_mfma_f32_16x16x32_bf16 v[58:61], v[240:243], v[204:207], v[58:61]
	v_mfma_f32_16x16x32_bf16 v[54:57], v[240:243], v[208:211], v[54:57]
	global_load_lds_dwordx4 v[142:143], off
	v_lshl_add_u64 v[142:143], v[142:143], 0, s[2:3]
	s_addk_i32 m0, 0x1000
	v_mfma_f32_16x16x32_bf16 v[50:53], v[240:243], v[212:215], v[50:53]
	v_mfma_f32_16x16x32_bf16 v[46:49], v[240:243], v[216:219], v[46:49]
	v_mfma_f32_16x16x32_bf16 v[42:45], v[240:243], v[220:223], v[42:45]
	global_load_lds_dwordx4 v[142:143], off
	v_lshl_add_u64 v[142:143], v[142:143], 0, s[2:3]
	s_addk_i32 m0, 0x1000
	v_mfma_f32_16x16x32_bf16 v[38:41], v[240:243], v[224:227], v[38:41]
	v_mfma_f32_16x16x32_bf16 v[34:37], v[240:243], v[228:231], v[34:37]
	v_mfma_f32_16x16x32_bf16 v[30:33], v[244:247], v[200:203], v[30:33]
	global_load_lds_dwordx4 v[142:143], off
	s_addk_i32 m0, 0x1000
	v_lshl_add_u64 v[142:143], v[134:135], 0, s[2:3]
	v_mfma_f32_16x16x32_bf16 v[26:29], v[244:247], v[204:207], v[26:29]
	v_mfma_f32_16x16x32_bf16 v[22:25], v[244:247], v[208:211], v[22:25]
	v_mfma_f32_16x16x32_bf16 v[18:21], v[244:247], v[212:215], v[18:21]
	global_load_lds_dwordx4 v[134:135], off
	s_addk_i32 m0, 0x1000
	v_lshl_add_u64 v[132:133], v[132:133], 0, s[12:13]
	v_mfma_f32_16x16x32_bf16 v[14:17], v[244:247], v[216:219], v[14:17]
	v_mfma_f32_16x16x32_bf16 v[10:13], v[244:247], v[220:223], v[10:13]
	v_mfma_f32_16x16x32_bf16 v[6:9], v[244:247], v[224:227], v[6:9]
	global_load_lds_dwordx4 v[142:143], off
	v_lshl_add_u64 v[134:135], v[134:135], 0, s[4:5]
	v_mfma_f32_16x16x32_bf16 v[2:5], v[244:247], v[228:231], v[2:5]
	s_mov_b32 s41, s40
	s_add_i32 s40, s40, 0x6000
	s_cmp_eq_u32 s40, 0x12000
	s_cselect_b32 s40, 0, s40
	s_sub_i32 s39, s39, 1
	s_cmp_lg_u32 s39, 0
	s_cbranch_scc1 .Lt11_loop
	s_waitcnt vmcnt(6) lgkmcnt(0)
	s_barrier
	v_add_u32_e32 v144, s40, v136
	v_mfma_f32_16x16x32_bf16 v[126:129], v[184:187], v[146:149], v[126:129]
	ds_read_b128 v[200:203], v144 offset:0
	v_mfma_f32_16x16x32_bf16 v[122:125], v[184:187], v[152:155], v[122:125]
	ds_read_b128 v[204:207], v144 offset:1024
	v_mfma_f32_16x16x32_bf16 v[118:121], v[184:187], v[156:159], v[118:121]
	ds_read_b128 v[208:211], v144 offset:2048
	v_mfma_f32_16x16x32_bf16 v[114:117], v[184:187], v[162:165], v[114:117]
	ds_read_b128 v[212:215], v144 offset:3072
	v_mfma_f32_16x16x32_bf16 v[110:113], v[184:187], v[166:169], v[110:113]
	ds_read_b128 v[216:219], v144 offset:4096
	v_mfma_f32_16x16x32_bf16 v[106:109], v[184:187], v[170:173], v[106:109]
	ds_read_b128 v[220:223], v144 offset:5120
	v_mfma_f32_16x16x32_bf16 v[102:105], v[184:187], v[176:179], v[102:105]
	ds_read_b128 v[224:227], v144 offset:6144
	v_mfma_f32_16x16x32_bf16 v[98:101], v[184:187], v[180:183], v[98:101]
	ds_read_b128 v[228:231], v144 offset:7168
	v_mfma_f32_16x16x32_bf16 v[94:97], v[188:191], v[146:149], v[94:97]
	v_add_u32_e32 v144, s40, v137
	v_mfma_f32_16x16x32_bf16 v[90:93], v[188:191], v[152:155], v[90:93]
	v_mfma_f32_16x16x32_bf16 v[86:89], v[188:191], v[156:159], v[86:89]
	ds_read_b128 v[232:235], v144 offset:16384
	v_mfma_f32_16x16x32_bf16 v[82:85], v[188:191], v[162:165], v[82:85]
	ds_read_b128 v[236:239], v144 offset:17408
	v_mfma_f32_16x16x32_bf16 v[78:81], v[188:191], v[166:169], v[78:81]
	ds_read_b128 v[240:243], v144 offset:18432
	v_mfma_f32_16x16x32_bf16 v[74:77], v[188:191], v[170:173], v[74:77]
	ds_read_b128 v[244:247], v144 offset:19456
	s_add_i32 s42, s46, s41
	v_mfma_f32_16x16x32_bf16 v[70:73], v[188:191], v[176:179], v[70:73]
	s_mov_b32 m0, s42
	v_lshl_add_u64 v[142:143], v[132:133], 0, s[2:3]
	v_mfma_f32_16x16x32_bf16 v[66:69], v[188:191], v[180:183], v[66:69]
	global_load_lds_dwordx4 v[132:133], off
	s_addk_i32 m0, 0x1000
	v_mfma_f32_16x16x32_bf16 v[62:65], v[192:195], v[146:149], v[62:65]
	v_mfma_f32_16x16x32_bf16 v[58:61], v[192:195], v[152:155], v[58:61]
	v_mfma_f32_16x16x32_bf16 v[54:57], v[192:195], v[156:159], v[54:57]
	global_load_lds_dwordx4 v[142:143], off
	v_lshl_add_u64 v[142:143], v[142:143], 0, s[2:3]
	s_addk_i32 m0, 0x1000
	v_mfma_f32_16x16x32_bf16 v[50:53], v[192:195], v[162:165], v[50:53]
	v_mfma_f32_16x16x32_bf16 v[46:49], v[192:195], v[166:169], v[46:49]
	v_mfma_f32_16x16x32_bf16 v[42:45], v[192:195], v[170:173], v[42:45]
	global_load_lds_dwordx4 v[142:143], off
	v_lshl_add_u64 v[142:143], v[142:143], 0, s[2:3]
	s_addk_i32 m0, 0x1000
	v_mfma_f32_16x16x32_bf16 v[38:41], v[192:195], v[176:179], v[38:41]
	v_mfma_f32_16x16x32_bf16 v[34:37], v[192:195], v[180:183], v[34:37]
	v_mfma_f32_16x16x32_bf16 v[30:33], v[196:199], v[146:149], v[30:33]
	global_load_lds_dwordx4 v[142:143], off
	s_addk_i32 m0, 0x1000
	v_lshl_add_u64 v[142:143], v[134:135], 0, s[2:3]
	v_mfma_f32_16x16x32_bf16 v[26:29], v[196:199], v[152:155], v[26:29]
	v_mfma_f32_16x16x32_bf16 v[22:25], v[196:199], v[156:159], v[22:25]
	v_mfma_f32_16x16x32_bf16 v[18:21], v[196:199], v[162:165], v[18:21]
	global_load_lds_dwordx4 v[134:135], off
	s_addk_i32 m0, 0x1000
	v_lshl_add_u64 v[132:133], v[132:133], 0, s[12:13]
	v_mfma_f32_16x16x32_bf16 v[14:17], v[196:199], v[166:169], v[14:17]
	v_mfma_f32_16x16x32_bf16 v[10:13], v[196:199], v[170:173], v[10:13]
	v_mfma_f32_16x16x32_bf16 v[6:9], v[196:199], v[176:179], v[6:9]
	global_load_lds_dwordx4 v[142:143], off
	v_lshl_add_u64 v[134:135], v[134:135], 0, s[4:5]
	v_mfma_f32_16x16x32_bf16 v[2:5], v[196:199], v[180:183], v[2:5]
	s_mov_b32 s41, s40
	s_add_i32 s40, s40, 0x6000
	s_cmp_eq_u32 s40, 0x12000
	s_cselect_b32 s40, 0, s40
	s_waitcnt vmcnt(6) lgkmcnt(0)
	s_barrier
;     ...
;   for (int kt = 0; kt < nk; kt++) {
;     if (kt + 1 < nk) asm volatile("s_waitcnt vmcnt(6)" ::: "memory");
;     else asm volatile("s_waitcnt vmcnt(0)" ::: "memory");
;     __builtin_amdgcn_s_barrier();
;     asm volatile("" ::: "memory");
;     if (kt + 2 < nk) G2_STAGE(kt + 2);
;     const char* cS = smem + (kt % 3) * 24576;
;     bf16x8 xa[8], wb[4];
; #pragma unroll
;     for (int f = 0; f < 8; f++) xa[f] = *(const bf16x8*)(cS + aoff + f * 1024);
; #pragma unroll
;     for (int f = 0; f < 4; f++) wb[f] = *(const bf16x8*)(cS + boff + f * 1024);
; #pragma unroll
;     for (int nf = 0; nf < 4; nf++)
; #pragma unroll
;       for (int mf = 0; mf < 8; mf++)
;         acc[nf][mf] = __builtin_amdgcn_mfma_f32_16x16x32_bf16(wb[nf], xa[mf], acc[nf][mf], 0, 0, 0);
;   }
	v_add_u32_e32 v144, s40, v136
	v_mfma_f32_16x16x32_bf16 v[126:129], v[232:235], v[200:203], v[126:129]
	ds_read_b128 v[146:149], v144 offset:0
	v_mfma_f32_16x16x32_bf16 v[122:125], v[232:235], v[204:207], v[122:125]
	ds_read_b128 v[152:155], v144 offset:1024
	v_mfma_f32_16x16x32_bf16 v[118:121], v[232:235], v[208:211], v[118:121]
	ds_read_b128 v[156:159], v144 offset:2048
	v_mfma_f32_16x16x32_bf16 v[114:117], v[232:235], v[212:215], v[114:117]
	ds_read_b128 v[162:165], v144 offset:3072
	v_mfma_f32_16x16x32_bf16 v[110:113], v[232:235], v[216:219], v[110:113]
	ds_read_b128 v[166:169], v144 offset:4096
	v_mfma_f32_16x16x32_bf16 v[106:109], v[232:235], v[220:223], v[106:109]
	ds_read_b128 v[170:173], v144 offset:5120
	v_mfma_f32_16x16x32_bf16 v[102:105], v[232:235], v[224:227], v[102:105]
	ds_read_b128 v[176:179], v144 offset:6144
	v_mfma_f32_16x16x32_bf16 v[98:101], v[232:235], v[228:231], v[98:101]
	ds_read_b128 v[180:183], v144 offset:7168
	v_mfma_f32_16x16x32_bf16 v[94:97], v[236:239], v[200:203], v[94:97]
	v_add_u32_e32 v144, s40, v137
	v_mfma_f32_16x16x32_bf16 v[90:93], v[236:239], v[204:207], v[90:93]
	v_mfma_f32_16x16x32_bf16 v[86:89], v[236:239], v[208:211], v[86:89]
	ds_read_b128 v[184:187], v144 offset:16384
	v_mfma_f32_16x16x32_bf16 v[82:85], v[236:239], v[212:215], v[82:85]
	ds_read_b128 v[188:191], v144 offset:17408
	v_mfma_f32_16x16x32_bf16 v[78:81], v[236:239], v[216:219], v[78:81]
	ds_read_b128 v[192:195], v144 offset:18432
	v_mfma_f32_16x16x32_bf16 v[74:77], v[236:239], v[220:223], v[74:77]
	ds_read_b128 v[196:199], v144 offset:19456
	v_mfma_f32_16x16x32_bf16 v[70:73], v[236:239], v[224:227], v[70:73]
	v_mfma_f32_16x16x32_bf16 v[66:69], v[236:239], v[228:231], v[66:69]
	v_mfma_f32_16x16x32_bf16 v[62:65], v[240:243], v[200:203], v[62:65]
	v_mfma_f32_16x16x32_bf16 v[58:61], v[240:243], v[204:207], v[58:61]
	v_mfma_f32_16x16x32_bf16 v[54:57], v[240:243], v[208:211], v[54:57]
	v_mfma_f32_16x16x32_bf16 v[50:53], v[240:243], v[212:215], v[50:53]
	v_mfma_f32_16x16x32_bf16 v[46:49], v[240:243], v[216:219], v[46:49]
	v_mfma_f32_16x16x32_bf16 v[42:45], v[240:243], v[220:223], v[42:45]
	v_mfma_f32_16x16x32_bf16 v[38:41], v[240:243], v[224:227], v[38:41]
	v_mfma_f32_16x16x32_bf16 v[34:37], v[240:243], v[228:231], v[34:37]
	v_mfma_f32_16x16x32_bf16 v[30:33], v[244:247], v[200:203], v[30:33]
	v_mfma_f32_16x16x32_bf16 v[26:29], v[244:247], v[204:207], v[26:29]
	v_mfma_f32_16x16x32_bf16 v[22:25], v[244:247], v[208:211], v[22:25]
	v_mfma_f32_16x16x32_bf16 v[18:21], v[244:247], v[212:215], v[18:21]
	v_mfma_f32_16x16x32_bf16 v[14:17], v[244:247], v[216:219], v[14:17]
	v_mfma_f32_16x16x32_bf16 v[10:13], v[244:247], v[220:223], v[10:13]
	v_mfma_f32_16x16x32_bf16 v[6:9], v[244:247], v[224:227], v[6:9]
	v_mfma_f32_16x16x32_bf16 v[2:5], v[244:247], v[228:231], v[2:5]
	s_mov_b32 s41, s40
	s_add_i32 s40, s40, 0x6000
	s_cmp_eq_u32 s40, 0x12000
	s_cselect_b32 s40, 0, s40
	s_waitcnt vmcnt(0) lgkmcnt(0)
	s_barrier
	v_add_u32_e32 v144, s40, v136
	v_mfma_f32_16x16x32_bf16 v[126:129], v[184:187], v[146:149], v[126:129]
	ds_read_b128 v[200:203], v144 offset:0
	v_mfma_f32_16x16x32_bf16 v[122:125], v[184:187], v[152:155], v[122:125]
	ds_read_b128 v[204:207], v144 offset:1024
	v_mfma_f32_16x16x32_bf16 v[118:121], v[184:187], v[156:159], v[118:121]
	ds_read_b128 v[208:211], v144 offset:2048
	v_mfma_f32_16x16x32_bf16 v[114:117], v[184:187], v[162:165], v[114:117]
	ds_read_b128 v[212:215], v144 offset:3072
	v_mfma_f32_16x16x32_bf16 v[110:113], v[184:187], v[166:169], v[110:113]
	ds_read_b128 v[216:219], v144 offset:4096
	v_mfma_f32_16x16x32_bf16 v[106:109], v[184:187], v[170:173], v[106:109]
	ds_read_b128 v[220:223], v144 offset:5120
	v_mfma_f32_16x16x32_bf16 v[102:105], v[184:187], v[176:179], v[102:105]
	ds_read_b128 v[224:227], v144 offset:6144
	v_mfma_f32_16x16x32_bf16 v[98:101], v[184:187], v[180:183], v[98:101]
	ds_read_b128 v[228:231], v144 offset:7168
	v_mfma_f32_16x16x32_bf16 v[94:97], v[188:191], v[146:149], v[94:97]
	v_add_u32_e32 v144, s40, v137
	v_mfma_f32_16x16x32_bf16 v[90:93], v[188:191], v[152:155], v[90:93]
	v_mfma_f32_16x16x32_bf16 v[86:89], v[188:191], v[156:159], v[86:89]
	ds_read_b128 v[232:235], v144 offset:16384
	v_mfma_f32_16x16x32_bf16 v[82:85], v[188:191], v[162:165], v[82:85]
	ds_read_b128 v[236:239], v144 offset:17408
	v_mfma_f32_16x16x32_bf16 v[78:81], v[188:191], v[166:169], v[78:81]
	ds_read_b128 v[240:243], v144 offset:18432
	v_mfma_f32_16x16x32_bf16 v[74:77], v[188:191], v[170:173], v[74:77]
	ds_read_b128 v[244:247], v144 offset:19456
	v_mfma_f32_16x16x32_bf16 v[70:73], v[188:191], v[176:179], v[70:73]
	v_mfma_f32_16x16x32_bf16 v[66:69], v[188:191], v[180:183], v[66:69]
	v_mfma_f32_16x16x32_bf16 v[62:65], v[192:195], v[146:149], v[62:65]
	v_mfma_f32_16x16x32_bf16 v[58:61], v[192:195], v[152:155], v[58:61]
	v_mfma_f32_16x16x32_bf16 v[54:57], v[192:195], v[156:159], v[54:57]
	v_mfma_f32_16x16x32_bf16 v[50:53], v[192:195], v[162:165], v[50:53]
	v_mfma_f32_16x16x32_bf16 v[46:49], v[192:195], v[166:169], v[46:49]
	v_mfma_f32_16x16x32_bf16 v[42:45], v[192:195], v[170:173], v[42:45]
	v_mfma_f32_16x16x32_bf16 v[38:41], v[192:195], v[176:179], v[38:41]
	v_mfma_f32_16x16x32_bf16 v[34:37], v[192:195], v[180:183], v[34:37]
	v_mfma_f32_16x16x32_bf16 v[30:33], v[196:199], v[146:149], v[30:33]
	v_mfma_f32_16x16x32_bf16 v[26:29], v[196:199], v[152:155], v[26:29]
	v_mfma_f32_16x16x32_bf16 v[22:25], v[196:199], v[156:159], v[22:25]
	v_mfma_f32_16x16x32_bf16 v[18:21], v[196:199], v[162:165], v[18:21]
	v_mfma_f32_16x16x32_bf16 v[14:17], v[196:199], v[166:169], v[14:17]
	v_mfma_f32_16x16x32_bf16 v[10:13], v[196:199], v[170:173], v[10:13]
	v_mfma_f32_16x16x32_bf16 v[6:9], v[196:199], v[176:179], v[6:9]
	v_mfma_f32_16x16x32_bf16 v[2:5], v[196:199], v[180:183], v[2:5]
	s_mov_b32 s41, s40
	s_add_i32 s40, s40, 0x6000
	s_cmp_eq_u32 s40, 0x12000
	s_cselect_b32 s40, 0, s40
	s_mov_b32 s4, 0x8000
	s_mov_b32 s5, 0
	s_mov_b32 s10, 0x10000
	s_mov_b32 s11, 0
	s_mov_b32 s44, 0x3fd744fd
	s_waitcnt lgkmcnt(0)
; DEVI float blo(unsigned u) { return __uint_as_float(u << 16); }
; DEVI float bhi(unsigned u) { return __uint_as_float(u & 0xffff0000u); }
;     ...
;     for (int nf = 0; nf < 4; nf++)
; #pragma unroll
;       for (int mf = 0; mf < 8; mf++)
;         acc[nf][mf] = __builtin_amdgcn_mfma_f32_16x16x32_bf16(wb[nf], xa[mf], acc[nf][mf], 0, 0, 0);
;     ...
;         if (EPI == EPI_RESID || EPI == EPI_RESID_ATOMIC) {
;           f32x4 x = a;
;           if (EPI == EPI_RESID || kpart == 0) {
;             const u32x2 xr = *(const u32x2*)((const u16*)(p.ws + WS_XB) + (size_t)row * 1024 + col);
;             x[0] += ALPHA * blo(xr[0]); x[1] += ALPHA * bhi(xr[0]); x[2] += ALPHA * blo(xr[1]); x[3] += ALPHA * bhi(xr[1]);
;           }
;           if (EPI == EPI_RESID) *(f32x4*)((float*)(p.ws + WS_XF) + (size_t)row * 1024 + col) = x;
	v_mfma_f32_16x16x32_bf16 v[126:129], v[232:235], v[200:203], v[126:129]
	v_mfma_f32_16x16x32_bf16 v[122:125], v[232:235], v[204:207], v[122:125]
	v_mfma_f32_16x16x32_bf16 v[118:121], v[232:235], v[208:211], v[118:121]
	v_mfma_f32_16x16x32_bf16 v[114:117], v[232:235], v[212:215], v[114:117]
	v_mfma_f32_16x16x32_bf16 v[110:113], v[232:235], v[216:219], v[110:113]
	global_load_dwordx4 v[146:149], v[138:139], off offset:0
	v_mfma_f32_16x16x32_bf16 v[106:109], v[232:235], v[220:223], v[106:109]
	v_mfma_f32_16x16x32_bf16 v[102:105], v[232:235], v[224:227], v[102:105]
	global_load_dwordx4 v[152:155], v[138:139], off offset:128
	v_mfma_f32_16x16x32_bf16 v[98:101], v[232:235], v[228:231], v[98:101]
	v_lshl_add_u64 v[138:139], v[138:139], 0, s[4:5]
	v_mfma_f32_16x16x32_bf16 v[94:97], v[236:239], v[200:203], v[94:97]
	global_load_dwordx4 v[156:159], v[138:139], off offset:0
	v_mfma_f32_16x16x32_bf16 v[90:93], v[236:239], v[204:207], v[90:93]
	v_mfma_f32_16x16x32_bf16 v[86:89], v[236:239], v[208:211], v[86:89]
	global_load_dwordx4 v[162:165], v[138:139], off offset:128
	v_mfma_f32_16x16x32_bf16 v[82:85], v[236:239], v[212:215], v[82:85]
	v_lshl_add_u64 v[138:139], v[138:139], 0, s[4:5]
	v_mfma_f32_16x16x32_bf16 v[78:81], v[236:239], v[216:219], v[78:81]
	global_load_dwordx4 v[166:169], v[138:139], off offset:0
	v_mfma_f32_16x16x32_bf16 v[74:77], v[236:239], v[220:223], v[74:77]
	v_mfma_f32_16x16x32_bf16 v[70:73], v[236:239], v[224:227], v[70:73]
	global_load_dwordx4 v[170:173], v[138:139], off offset:128
	v_mfma_f32_16x16x32_bf16 v[66:69], v[236:239], v[228:231], v[66:69]
	v_lshl_add_u64 v[138:139], v[138:139], 0, s[4:5]
	v_mfma_f32_16x16x32_bf16 v[62:65], v[240:243], v[200:203], v[62:65]
	global_load_dwordx4 v[176:179], v[138:139], off offset:0
	v_mfma_f32_16x16x32_bf16 v[58:61], v[240:243], v[204:207], v[58:61]
	v_mfma_f32_16x16x32_bf16 v[54:57], v[240:243], v[208:211], v[54:57]
	global_load_dwordx4 v[180:183], v[138:139], off offset:128
	v_mfma_f32_16x16x32_bf16 v[50:53], v[240:243], v[212:215], v[50:53]
	v_lshl_add_u64 v[138:139], v[138:139], 0, s[4:5]
	v_mfma_f32_16x16x32_bf16 v[46:49], v[240:243], v[216:219], v[46:49]
	global_load_dwordx4 v[184:187], v[138:139], off offset:0
	v_mfma_f32_16x16x32_bf16 v[42:45], v[240:243], v[220:223], v[42:45]
	v_mfma_f32_16x16x32_bf16 v[38:41], v[240:243], v[224:227], v[38:41]
	global_load_dwordx4 v[188:191], v[138:139], off offset:128
	v_mfma_f32_16x16x32_bf16 v[34:37], v[240:243], v[228:231], v[34:37]
	v_lshl_add_u64 v[138:139], v[138:139], 0, s[4:5]
	v_mfma_f32_16x16x32_bf16 v[30:33], v[244:247], v[200:203], v[30:33]
	global_load_dwordx4 v[192:195], v[138:139], off offset:0
	v_mfma_f32_16x16x32_bf16 v[26:29], v[244:247], v[204:207], v[26:29]
	v_mfma_f32_16x16x32_bf16 v[22:25], v[244:247], v[208:211], v[22:25]
	global_load_dwordx4 v[196:199], v[138:139], off offset:128
	v_mfma_f32_16x16x32_bf16 v[18:21], v[244:247], v[212:215], v[18:21]
	v_lshl_add_u64 v[138:139], v[138:139], 0, s[4:5]
	v_mfma_f32_16x16x32_bf16 v[14:17], v[244:247], v[216:219], v[14:17]
	v_mfma_f32_16x16x32_bf16 v[10:13], v[244:247], v[220:223], v[10:13]
	v_mfma_f32_16x16x32_bf16 v[6:9], v[244:247], v[224:227], v[6:9]
	v_mfma_f32_16x16x32_bf16 v[2:5], v[244:247], v[228:231], v[2:5]
	s_mov_b32 m0, s43
	global_load_dwordx4 v[200:203], v[138:139], off offset:0
	global_load_dwordx4 v[204:207], v[138:139], off offset:128
	v_lshl_add_u64 v[138:139], v[138:139], 0, s[4:5]
	global_load_dwordx4 v[208:211], v[138:139], off offset:0
	global_load_dwordx4 v[212:215], v[138:139], off offset:128
	v_lshl_add_u64 v[138:139], v[138:139], 0, s[4:5]
	s_nop 7
	s_waitcnt vmcnt(15)
	v_permlane16_swap_b32_e32 v146, v148
	v_permlane16_swap_b32_e32 v147, v149
	v_lshlrev_b32_e32 v216, 16, v146
	v_and_b32_e32 v146, 0xffff0000, v146
	v_lshlrev_b32_e32 v217, 16, v147
	v_and_b32_e32 v147, 0xffff0000, v147
	v_fmac_f32_e32 v126, s44, v216
	v_fmac_f32_e32 v127, s44, v146
	v_fmac_f32_e32 v128, s44, v217
	v_fmac_f32_e32 v129, s44, v147
	global_store_dwordx4 v[140:141], v[126:129], off offset:0
	v_lshlrev_b32_e32 v216, 16, v148
	v_and_b32_e32 v148, 0xffff0000, v148
	v_lshlrev_b32_e32 v217, 16, v149
	v_and_b32_e32 v149, 0xffff0000, v149
	v_fmac_f32_e32 v94, s44, v216
	v_fmac_f32_e32 v95, s44, v148
	v_fmac_f32_e32 v96, s44, v217
	v_fmac_f32_e32 v97, s44, v149
	global_store_dwordx4 v[140:141], v[94:97], off offset:64
	s_waitcnt vmcnt(16)
	v_permlane16_swap_b32_e32 v152, v154
	v_permlane16_swap_b32_e32 v153, v155
	v_lshlrev_b32_e32 v216, 16, v152
	v_and_b32_e32 v152, 0xffff0000, v152
	v_lshlrev_b32_e32 v217, 16, v153
	v_and_b32_e32 v153, 0xffff0000, v153
	v_fmac_f32_e32 v62, s44, v216
	v_fmac_f32_e32 v63, s44, v152
	v_fmac_f32_e32 v64, s44, v217
	v_fmac_f32_e32 v65, s44, v153
	global_store_dwordx4 v[140:141], v[62:65], off offset:128
	v_lshlrev_b32_e32 v216, 16, v154
	v_and_b32_e32 v154, 0xffff0000, v154
	v_lshlrev_b32_e32 v217, 16, v155
	v_and_b32_e32 v155, 0xffff0000, v155
	v_fmac_f32_e32 v30, s44, v216
	v_fmac_f32_e32 v31, s44, v154
	v_fmac_f32_e32 v32, s44, v217
	v_fmac_f32_e32 v33, s44, v155
	global_store_dwordx4 v[140:141], v[30:33], off offset:192
	v_lshl_add_u64 v[140:141], v[140:141], 0, s[10:11]
	s_waitcnt vmcnt(17)
	v_permlane16_swap_b32_e32 v156, v158
	v_permlane16_swap_b32_e32 v157, v159
	v_lshlrev_b32_e32 v216, 16, v156
	v_and_b32_e32 v156, 0xffff0000, v156
	v_lshlrev_b32_e32 v217, 16, v157
	v_and_b32_e32 v157, 0xffff0000, v157
	v_fmac_f32_e32 v122, s44, v216
	v_fmac_f32_e32 v123, s44, v156
	v_fmac_f32_e32 v124, s44, v217
	v_fmac_f32_e32 v125, s44, v157
	global_store_dwordx4 v[140:141], v[122:125], off offset:0
	v_lshlrev_b32_e32 v216, 16, v158
	v_and_b32_e32 v158, 0xffff0000, v158
	v_lshlrev_b32_e32 v217, 16, v159
	v_and_b32_e32 v159, 0xffff0000, v159
	v_fmac_f32_e32 v90, s44, v216
	v_fmac_f32_e32 v91, s44, v158
	v_fmac_f32_e32 v92, s44, v217
	v_fmac_f32_e32 v93, s44, v159
	global_store_dwordx4 v[140:141], v[90:93], off offset:64
	s_waitcnt vmcnt(18)
; DEVI float blo(unsigned u) { return __uint_as_float(u << 16); }
; DEVI float bhi(unsigned u) { return __uint_as_float(u & 0xffff0000u); }
;     ...
;         if (EPI == EPI_RESID || EPI == EPI_RESID_ATOMIC) {
;           f32x4 x = a;
;           if (EPI == EPI_RESID || kpart == 0) {
;             const u32x2 xr = *(const u32x2*)((const u16*)(p.ws + WS_XB) + (size_t)row * 1024 + col);
;             x[0] += ALPHA * blo(xr[0]); x[1] += ALPHA * bhi(xr[0]); x[2] += ALPHA * blo(xr[1]); x[3] += ALPHA * bhi(xr[1]);
;           }
;           if (EPI == EPI_RESID) *(f32x4*)((float*)(p.ws + WS_XF) + (size_t)row * 1024 + col) = x;
	v_permlane16_swap_b32_e32 v162, v164
	v_permlane16_swap_b32_e32 v163, v165
	v_lshlrev_b32_e32 v216, 16, v162
	v_and_b32_e32 v162, 0xffff0000, v162
	v_lshlrev_b32_e32 v217, 16, v163
	v_and_b32_e32 v163, 0xffff0000, v163
	v_fmac_f32_e32 v58, s44, v216
	v_fmac_f32_e32 v59, s44, v162
	v_fmac_f32_e32 v60, s44, v217
	v_fmac_f32_e32 v61, s44, v163
	global_store_dwordx4 v[140:141], v[58:61], off offset:128
	v_lshlrev_b32_e32 v216, 16, v164
	v_and_b32_e32 v164, 0xffff0000, v164
	v_lshlrev_b32_e32 v217, 16, v165
	v_and_b32_e32 v165, 0xffff0000, v165
	v_fmac_f32_e32 v26, s44, v216
	v_fmac_f32_e32 v27, s44, v164
	v_fmac_f32_e32 v28, s44, v217
	v_fmac_f32_e32 v29, s44, v165
	global_store_dwordx4 v[140:141], v[26:29], off offset:192
	v_lshl_add_u64 v[140:141], v[140:141], 0, s[10:11]
	s_waitcnt vmcnt(19)
	v_permlane16_swap_b32_e32 v166, v168
	v_permlane16_swap_b32_e32 v167, v169
	v_lshlrev_b32_e32 v216, 16, v166
	v_and_b32_e32 v166, 0xffff0000, v166
	v_lshlrev_b32_e32 v217, 16, v167
	v_and_b32_e32 v167, 0xffff0000, v167
	v_fmac_f32_e32 v118, s44, v216
	v_fmac_f32_e32 v119, s44, v166
	v_fmac_f32_e32 v120, s44, v217
	v_fmac_f32_e32 v121, s44, v167
	global_store_dwordx4 v[140:141], v[118:121], off offset:0
	v_lshlrev_b32_e32 v216, 16, v168
	v_and_b32_e32 v168, 0xffff0000, v168
	v_lshlrev_b32_e32 v217, 16, v169
	v_and_b32_e32 v169, 0xffff0000, v169
	v_fmac_f32_e32 v86, s44, v216
	v_fmac_f32_e32 v87, s44, v168
	v_fmac_f32_e32 v88, s44, v217
	v_fmac_f32_e32 v89, s44, v169
	global_store_dwordx4 v[140:141], v[86:89], off offset:64
	s_waitcnt vmcnt(20)
	v_permlane16_swap_b32_e32 v170, v172
	v_permlane16_swap_b32_e32 v171, v173
	v_lshlrev_b32_e32 v216, 16, v170
	v_and_b32_e32 v170, 0xffff0000, v170
	v_lshlrev_b32_e32 v217, 16, v171
	v_and_b32_e32 v171, 0xffff0000, v171
	v_fmac_f32_e32 v54, s44, v216
	v_fmac_f32_e32 v55, s44, v170
	v_fmac_f32_e32 v56, s44, v217
	v_fmac_f32_e32 v57, s44, v171
	global_store_dwordx4 v[140:141], v[54:57], off offset:128
	v_lshlrev_b32_e32 v216, 16, v172
	v_and_b32_e32 v172, 0xffff0000, v172
	v_lshlrev_b32_e32 v217, 16, v173
	v_and_b32_e32 v173, 0xffff0000, v173
	v_fmac_f32_e32 v22, s44, v216
	v_fmac_f32_e32 v23, s44, v172
	v_fmac_f32_e32 v24, s44, v217
	v_fmac_f32_e32 v25, s44, v173
	global_store_dwordx4 v[140:141], v[22:25], off offset:192
	v_lshl_add_u64 v[140:141], v[140:141], 0, s[10:11]
	s_waitcnt vmcnt(21)
	v_permlane16_swap_b32_e32 v176, v178
	v_permlane16_swap_b32_e32 v177, v179
	v_lshlrev_b32_e32 v216, 16, v176
	v_and_b32_e32 v176, 0xffff0000, v176
	v_lshlrev_b32_e32 v217, 16, v177
	v_and_b32_e32 v177, 0xffff0000, v177
	v_fmac_f32_e32 v114, s44, v216
	v_fmac_f32_e32 v115, s44, v176
	v_fmac_f32_e32 v116, s44, v217
	v_fmac_f32_e32 v117, s44, v177
	global_store_dwordx4 v[140:141], v[114:117], off offset:0
	v_lshlrev_b32_e32 v216, 16, v178
	v_and_b32_e32 v178, 0xffff0000, v178
	v_lshlrev_b32_e32 v217, 16, v179
	v_and_b32_e32 v179, 0xffff0000, v179
	v_fmac_f32_e32 v82, s44, v216
	v_fmac_f32_e32 v83, s44, v178
	v_fmac_f32_e32 v84, s44, v217
	v_fmac_f32_e32 v85, s44, v179
	global_store_dwordx4 v[140:141], v[82:85], off offset:64
	s_waitcnt vmcnt(22)
	v_permlane16_swap_b32_e32 v180, v182
	v_permlane16_swap_b32_e32 v181, v183
	v_lshlrev_b32_e32 v216, 16, v180
	v_and_b32_e32 v180, 0xffff0000, v180
	v_lshlrev_b32_e32 v217, 16, v181
	v_and_b32_e32 v181, 0xffff0000, v181
	v_fmac_f32_e32 v50, s44, v216
	v_fmac_f32_e32 v51, s44, v180
	v_fmac_f32_e32 v52, s44, v217
	v_fmac_f32_e32 v53, s44, v181
	global_store_dwordx4 v[140:141], v[50:53], off offset:128
	v_lshlrev_b32_e32 v216, 16, v182
	v_and_b32_e32 v182, 0xffff0000, v182
	v_lshlrev_b32_e32 v217, 16, v183
	v_and_b32_e32 v183, 0xffff0000, v183
	v_fmac_f32_e32 v18, s44, v216
	v_fmac_f32_e32 v19, s44, v182
	v_fmac_f32_e32 v20, s44, v217
	v_fmac_f32_e32 v21, s44, v183
	global_store_dwordx4 v[140:141], v[18:21], off offset:192
	v_lshl_add_u64 v[140:141], v[140:141], 0, s[10:11]
	s_waitcnt vmcnt(23)
	v_permlane16_swap_b32_e32 v184, v186
	v_permlane16_swap_b32_e32 v185, v187
	v_lshlrev_b32_e32 v216, 16, v184
	v_and_b32_e32 v184, 0xffff0000, v184
	v_lshlrev_b32_e32 v217, 16, v185
	v_and_b32_e32 v185, 0xffff0000, v185
	v_fmac_f32_e32 v110, s44, v216
	v_fmac_f32_e32 v111, s44, v184
	v_fmac_f32_e32 v112, s44, v217
	v_fmac_f32_e32 v113, s44, v185
	global_store_dwordx4 v[140:141], v[110:113], off offset:0
	v_lshlrev_b32_e32 v216, 16, v186
	v_and_b32_e32 v186, 0xffff0000, v186
	v_lshlrev_b32_e32 v217, 16, v187
	v_and_b32_e32 v187, 0xffff0000, v187
	v_fmac_f32_e32 v78, s44, v216
	v_fmac_f32_e32 v79, s44, v186
	v_fmac_f32_e32 v80, s44, v217
	v_fmac_f32_e32 v81, s44, v187
	global_store_dwordx4 v[140:141], v[78:81], off offset:64
	s_waitcnt vmcnt(24)
; DEVI float blo(unsigned u) { return __uint_as_float(u << 16); }
; DEVI float bhi(unsigned u) { return __uint_as_float(u & 0xffff0000u); }
;     ...
;         if (EPI == EPI_RESID || EPI == EPI_RESID_ATOMIC) {
;           f32x4 x = a;
;           if (EPI == EPI_RESID || kpart == 0) {
;             const u32x2 xr = *(const u32x2*)((const u16*)(p.ws + WS_XB) + (size_t)row * 1024 + col);
;             x[0] += ALPHA * blo(xr[0]); x[1] += ALPHA * bhi(xr[0]); x[2] += ALPHA * blo(xr[1]); x[3] += ALPHA * bhi(xr[1]);
;           }
;           if (EPI == EPI_RESID) *(f32x4*)((float*)(p.ws + WS_XF) + (size_t)row * 1024 + col) = x;
	v_permlane16_swap_b32_e32 v188, v190
	v_permlane16_swap_b32_e32 v189, v191
	v_lshlrev_b32_e32 v216, 16, v188
	v_and_b32_e32 v188, 0xffff0000, v188
	v_lshlrev_b32_e32 v217, 16, v189
	v_and_b32_e32 v189, 0xffff0000, v189
	v_fmac_f32_e32 v46, s44, v216
	v_fmac_f32_e32 v47, s44, v188
	v_fmac_f32_e32 v48, s44, v217
	v_fmac_f32_e32 v49, s44, v189
	global_store_dwordx4 v[140:141], v[46:49], off offset:128
	v_lshlrev_b32_e32 v216, 16, v190
	v_and_b32_e32 v190, 0xffff0000, v190
	v_lshlrev_b32_e32 v217, 16, v191
	v_and_b32_e32 v191, 0xffff0000, v191
	v_fmac_f32_e32 v14, s44, v216
	v_fmac_f32_e32 v15, s44, v190
	v_fmac_f32_e32 v16, s44, v217
	v_fmac_f32_e32 v17, s44, v191
	global_store_dwordx4 v[140:141], v[14:17], off offset:192
	v_lshl_add_u64 v[140:141], v[140:141], 0, s[10:11]
	s_waitcnt vmcnt(25)
	v_permlane16_swap_b32_e32 v192, v194
	v_permlane16_swap_b32_e32 v193, v195
	v_lshlrev_b32_e32 v216, 16, v192
	v_and_b32_e32 v192, 0xffff0000, v192
	v_lshlrev_b32_e32 v217, 16, v193
	v_and_b32_e32 v193, 0xffff0000, v193
	v_fmac_f32_e32 v106, s44, v216
	v_fmac_f32_e32 v107, s44, v192
	v_fmac_f32_e32 v108, s44, v217
	v_fmac_f32_e32 v109, s44, v193
	global_store_dwordx4 v[140:141], v[106:109], off offset:0
	v_lshlrev_b32_e32 v216, 16, v194
	v_and_b32_e32 v194, 0xffff0000, v194
	v_lshlrev_b32_e32 v217, 16, v195
	v_and_b32_e32 v195, 0xffff0000, v195
	v_fmac_f32_e32 v74, s44, v216
	v_fmac_f32_e32 v75, s44, v194
	v_fmac_f32_e32 v76, s44, v217
	v_fmac_f32_e32 v77, s44, v195
	global_store_dwordx4 v[140:141], v[74:77], off offset:64
	s_waitcnt vmcnt(26)
	v_permlane16_swap_b32_e32 v196, v198
	v_permlane16_swap_b32_e32 v197, v199
	v_lshlrev_b32_e32 v216, 16, v196
	v_and_b32_e32 v196, 0xffff0000, v196
	v_lshlrev_b32_e32 v217, 16, v197
	v_and_b32_e32 v197, 0xffff0000, v197
	v_fmac_f32_e32 v42, s44, v216
	v_fmac_f32_e32 v43, s44, v196
	v_fmac_f32_e32 v44, s44, v217
	v_fmac_f32_e32 v45, s44, v197
	global_store_dwordx4 v[140:141], v[42:45], off offset:128
	v_lshlrev_b32_e32 v216, 16, v198
	v_and_b32_e32 v198, 0xffff0000, v198
	v_lshlrev_b32_e32 v217, 16, v199
	v_and_b32_e32 v199, 0xffff0000, v199
	v_fmac_f32_e32 v10, s44, v216
	v_fmac_f32_e32 v11, s44, v198
	v_fmac_f32_e32 v12, s44, v217
	v_fmac_f32_e32 v13, s44, v199
	global_store_dwordx4 v[140:141], v[10:13], off offset:192
	v_lshl_add_u64 v[140:141], v[140:141], 0, s[10:11]
	s_waitcnt vmcnt(27)
	v_permlane16_swap_b32_e32 v200, v202
	v_permlane16_swap_b32_e32 v201, v203
	v_lshlrev_b32_e32 v216, 16, v200
	v_and_b32_e32 v200, 0xffff0000, v200
	v_lshlrev_b32_e32 v217, 16, v201
	v_and_b32_e32 v201, 0xffff0000, v201
	v_fmac_f32_e32 v102, s44, v216
	v_fmac_f32_e32 v103, s44, v200
	v_fmac_f32_e32 v104, s44, v217
	v_fmac_f32_e32 v105, s44, v201
	global_store_dwordx4 v[140:141], v[102:105], off offset:0
	v_lshlrev_b32_e32 v216, 16, v202
	v_and_b32_e32 v202, 0xffff0000, v202
	v_lshlrev_b32_e32 v217, 16, v203
	v_and_b32_e32 v203, 0xffff0000, v203
	v_fmac_f32_e32 v70, s44, v216
	v_fmac_f32_e32 v71, s44, v202
	v_fmac_f32_e32 v72, s44, v217
	v_fmac_f32_e32 v73, s44, v203
	global_store_dwordx4 v[140:141], v[70:73], off offset:64
	s_waitcnt vmcnt(28)
	v_permlane16_swap_b32_e32 v204, v206
	v_permlane16_swap_b32_e32 v205, v207
	v_lshlrev_b32_e32 v216, 16, v204
	v_and_b32_e32 v204, 0xffff0000, v204
	v_lshlrev_b32_e32 v217, 16, v205
	v_and_b32_e32 v205, 0xffff0000, v205
	v_fmac_f32_e32 v38, s44, v216
	v_fmac_f32_e32 v39, s44, v204
	v_fmac_f32_e32 v40, s44, v217
	v_fmac_f32_e32 v41, s44, v205
	global_store_dwordx4 v[140:141], v[38:41], off offset:128
	v_lshlrev_b32_e32 v216, 16, v206
	v_and_b32_e32 v206, 0xffff0000, v206
	v_lshlrev_b32_e32 v217, 16, v207
	v_and_b32_e32 v207, 0xffff0000, v207
	v_fmac_f32_e32 v6, s44, v216
	v_fmac_f32_e32 v7, s44, v206
	v_fmac_f32_e32 v8, s44, v217
	v_fmac_f32_e32 v9, s44, v207
	global_store_dwordx4 v[140:141], v[6:9], off offset:192
	v_lshl_add_u64 v[140:141], v[140:141], 0, s[10:11]
	s_waitcnt vmcnt(29)
	v_permlane16_swap_b32_e32 v208, v210
	v_permlane16_swap_b32_e32 v209, v211
	v_lshlrev_b32_e32 v216, 16, v208
	v_and_b32_e32 v208, 0xffff0000, v208
	v_lshlrev_b32_e32 v217, 16, v209
	v_and_b32_e32 v209, 0xffff0000, v209
	v_fmac_f32_e32 v98, s44, v216
	v_fmac_f32_e32 v99, s44, v208
	v_fmac_f32_e32 v100, s44, v217
	v_fmac_f32_e32 v101, s44, v209
	global_store_dwordx4 v[140:141], v[98:101], off offset:0
	v_lshlrev_b32_e32 v216, 16, v210
	v_and_b32_e32 v210, 0xffff0000, v210
	v_lshlrev_b32_e32 v217, 16, v211
	v_and_b32_e32 v211, 0xffff0000, v211
	v_fmac_f32_e32 v66, s44, v216
	v_fmac_f32_e32 v67, s44, v210
	v_fmac_f32_e32 v68, s44, v217
	v_fmac_f32_e32 v69, s44, v211
	global_store_dwordx4 v[140:141], v[66:69], off offset:64
	s_waitcnt vmcnt(30)
	v_permlane16_swap_b32_e32 v212, v214
	v_permlane16_swap_b32_e32 v213, v215
	v_lshlrev_b32_e32 v216, 16, v212
	v_and_b32_e32 v212, 0xffff0000, v212
	v_lshlrev_b32_e32 v217, 16, v213
	v_and_b32_e32 v213, 0xffff0000, v213
	v_fmac_f32_e32 v34, s44, v216
	v_fmac_f32_e32 v35, s44, v212
	v_fmac_f32_e32 v36, s44, v217
	v_fmac_f32_e32 v37, s44, v213
	global_store_dwordx4 v[140:141], v[34:37], off offset:128
	v_lshlrev_b32_e32 v216, 16, v214
	v_and_b32_e32 v214, 0xffff0000, v214
	v_lshlrev_b32_e32 v217, 16, v215
	v_and_b32_e32 v215, 0xffff0000, v215
	v_fmac_f32_e32 v2, s44, v216
	v_fmac_f32_e32 v3, s44, v214
	v_fmac_f32_e32 v4, s44, v217
	v_fmac_f32_e32 v5, s44, v215
	global_store_dwordx4 v[140:141], v[2:5], off offset:192
	s_branch .LBB0_41

; #define LAS __attribute__((address_space(3)))
; DEVI int tidx() { int t = threadIdx.x; asm volatile("" : "+v"(t)); return t; }
;   const int tid = tidx(), lane = tid & 63, wid = tid >> 6;
;   const int wm = wid >> 1, wn = wid & 1, r16 = lane & 15, quad = lane >> 4;
;   f32x4 acc[4][8];
; #pragma unroll
;   for (int i = 0; i < 4; i++)
; #pragma unroll
;     for (int j = 0; j < 8; j++) acc[i][j] = (f32x4){0.f, 0.f, 0.f, 0.f};
;   const int nk = (nk_part < 0) ? (K >> 5) : nk_part;
;   const int lrow = tid >> 2, lpc = tid & 3;
;   const int lch = lpc ^ ((0x78 >> (((lrow >> 2) & 3) * 2)) & 3);
;   const u16* ga = A + (size_t)(m0 + lrow) * lda + kbeg + lch * 8;
;   const u16* gb = Bt + (size_t)(n0 + lrow) * K + kbeg + lch * 8;
;   const size_t ga1 = (size_t)64 * lda, gb1 = (size_t)64 * K;
;   const unsigned lds0 = (unsigned)(uintptr_t)(LAS char*)smem + (unsigned)__builtin_amdgcn_readfirstlane(wid) * 1024u;
; DEVI void run_phase(const Params& p, int ph, char* smem) {
;     ...
;           const int u_ = t - 512, tl_ = u_ / 2, q_ = u_ - tl_ * 2;
;           gemm_tile256<EPI_RESID_ATOMIC>(p, ox, 256, Bt, 256, (64 + (tl_ & 1)) * 256, (tl_ >> 1) * 128, nullptr, 0, smem, q_ * 128, 4, q_);
.LBB0_147:
	s_cmpk_gt_i32 s38, 0x1ff
	s_mov_b64 s[2:3], -1
	s_cbranch_scc0 .LBB0_208
	s_sub_i32 s98, s38, 512
	s_lshr_b32 s41, s98, 1
	s_and_b32 s99, s98, 1
	s_lshr_b32 s13, s41, 1
	s_and_b32 s41, s41, 1
	s_add_i32 s41, s41, 64
	v_readlane_b32 s2, v250, 5
	v_readlane_b32 s3, v250, 6
	v_readlane_b32 s98, v254, 62
	s_mul_i32 s1, s41, 0x20000
	s_add_u32 s4, s2, s1
	s_addc_u32 s5, s3, 0
	s_add_u32 s4, s4, 0xe700000
	s_addc_u32 s5, s5, 0
	s_mul_i32 s1, s98, 0x80000
	s_mul_i32 s12, s13, 0x10000
	s_add_i32 s1, s1, s12
	s_add_u32 s8, s2, s1
	s_addc_u32 s9, s3, 0
	s_add_u32 s8, s8, 0x16c00000
	s_addc_u32 s9, s9, 0
	s_mul_i32 s1, s99, 256
	s_add_u32 s4, s4, s1
	s_addc_u32 s5, s5, 0
	s_mul_i32 s1, s99, 512
	s_add_u32 s8, s8, s1
	s_addc_u32 s9, s9, 0
	s_movk_i32 s0, 0x78
	v_lshrrev_b32_e32 v0, 2, v145
	v_and_b32_e32 v131, 3, v145
	v_bfe_u32 v136, v145, 4, 2
	v_lshlrev_b32_e32 v136, 1, v136
	v_lshrrev_b32_e64 v136, v136, s0
	v_and_b32_e32 v136, 3, v136
	v_xor_b32_e32 v131, v131, v136
	v_lshlrev_b32_e32 v131, 4, v131
	s_movk_i32 s12, 0x200
	v_mad_u32_u24 v0, v0, s12, v131
	v_bfe_u32 v137, v145, 2, 1
	s_movk_i32 s12, 0x1c0
	v_mul_u32_u24_e32 v136, s12, v137
	v_sub_u32_e32 v136, v0, v136
	v_mov_b32_e32 v137, 0
	v_lshl_add_u64 v[134:135], s[8:9], 0, v[136:137]
	v_bfe_u32 v137, v145, 2, 1
	s_mov_b32 s10, 64
	s_mov_b32 s11, 0
	v_lshl_add_u64 v[132:133], s[4:5], 0, v[0:1]
	v_bfe_u32 v136, v145, 2, 2
	v_lshlrev_b32_e32 v136, 1, v136
	v_lshrrev_b32_e64 v136, v136, s0
	v_and_b32_e32 v136, 3, v136
	v_bfe_u32 v137, v145, 4, 2
	v_xor_b32_e32 v136, v136, v137
	v_lshlrev_b32_e32 v136, 4, v136
	v_and_b32_e32 v131, 15, v145
	v_lshl_or_b32 v136, v131, 6, v136
	v_bfe_u32 v137, v145, 6, 1
	v_lshl_or_b32 v137, v137, 12, v136
	v_lshrrev_b32_e32 v0, 7, v145
	v_lshl_or_b32 v136, v0, 13, v136
	v_and_b32_e32 v140, 1, v131
	v_lshl_or_b32 v131, v0, 7, v131
	v_bfe_u32 v0, v145, 4, 2
	v_lshlrev_b32_e32 v0, 3, v0
	v_bfe_u32 v141, v145, 6, 1
	s_lshl_b32 s1, s41, 19
	s_lshl_b32 s12, s13, 8
	s_add_i32 s1, s1, s12
	s_add_u32 s4, s2, s1
	s_addc_u32 s5, s3, 0
	s_add_u32 s4, s4, 0x4200000
	s_addc_u32 s5, s5, 0
	v_lshlrev_b32_e32 v138, 11, v131
	v_lshl_add_u32 v138, v141, 7, v138
	v_bfe_u32 v139, v145, 4, 1
	v_lshl_add_u32 v138, v139, 5, v138
	v_bfe_u32 v139, v145, 5, 1
	v_lshl_add_u32 v138, v139, 4, v138
	v_mov_b32_e32 v139, 0
	v_lshl_add_u64 v[138:139], s[4:5], 0, v[138:139]
	s_and_b32 s1, s41, 1
	s_lshl_b32 s1, s1, 20
	s_lshl_b32 s12, s99, 21
	s_add_i32 s1, s1, s12
	s_lshl_b32 s12, s13, 9
	s_add_i32 s1, s1, s12
	s_add_u32 s8, s2, s1
	s_addc_u32 s9, s3, 0
	s_add_u32 s8, s8, 0x1dcc0000
	s_addc_u32 s9, s9, 0
	v_lshlrev_b32_e32 v140, 12, v131
	v_lshl_add_u32 v140, v141, 8, v140
	v_lshl_add_u32 v140, v0, 1, v140
	v_mov_b32_e32 v141, 0
	v_lshl_add_u64 v[140:141], s[8:9], 0, v[140:141]
	s_mov_b32 s2, 0x8000
	s_mov_b32 s3, 0
	v_lshrrev_b32_e32 v0, 6, v145
	v_lshlrev_b32_e32 v0, 10, v0
	s_nop 0
	v_readfirstlane_b32 s98, v0
	s_mov_b32 s39, m0
	s_mov_b32 s4, 128
	s_mov_b32 s5, 0
	v_mov_b32_e32 v2, 0
	v_mov_b32_e32 v3, 0
	v_mov_b32_e32 v4, 0
	v_mov_b32_e32 v5, 0
	v_mov_b32_e32 v6, 0
	v_mov_b32_e32 v7, 0
	v_mov_b32_e32 v8, 0
	v_mov_b32_e32 v9, 0
	v_mov_b32_e32 v10, 0
	v_mov_b32_e32 v11, 0
	v_mov_b32_e32 v12, 0
	v_mov_b32_e32 v13, 0
	v_mov_b32_e32 v14, 0
	v_mov_b32_e32 v15, 0
	v_mov_b32_e32 v16, 0
	v_mov_b32_e32 v17, 0
	v_mov_b32_e32 v18, 0
	v_mov_b32_e32 v19, 0
	v_mov_b32_e32 v20, 0
	v_mov_b32_e32 v21, 0
	v_mov_b32_e32 v22, 0
	v_mov_b32_e32 v23, 0
	v_mov_b32_e32 v24, 0
	v_mov_b32_e32 v25, 0
	v_mov_b32_e32 v26, 0
	v_mov_b32_e32 v27, 0
	v_mov_b32_e32 v28, 0
	v_mov_b32_e32 v29, 0
	v_mov_b32_e32 v30, 0
	v_mov_b32_e32 v31, 0
	v_mov_b32_e32 v32, 0
	v_mov_b32_e32 v33, 0
	v_mov_b32_e32 v34, 0
	v_mov_b32_e32 v35, 0
	v_mov_b32_e32 v36, 0
	v_mov_b32_e32 v37, 0
	v_mov_b32_e32 v38, 0
	v_mov_b32_e32 v39, 0
	v_mov_b32_e32 v40, 0
	v_mov_b32_e32 v41, 0
	v_mov_b32_e32 v42, 0
	v_mov_b32_e32 v43, 0
	v_mov_b32_e32 v44, 0
	v_mov_b32_e32 v45, 0
	v_mov_b32_e32 v46, 0
	v_mov_b32_e32 v47, 0
	v_mov_b32_e32 v48, 0
	v_mov_b32_e32 v49, 0
	v_mov_b32_e32 v50, 0
	v_mov_b32_e32 v51, 0
	v_mov_b32_e32 v52, 0
	v_mov_b32_e32 v53, 0
	v_mov_b32_e32 v54, 0
	v_mov_b32_e32 v55, 0
	v_mov_b32_e32 v56, 0
	v_mov_b32_e32 v57, 0
	v_mov_b32_e32 v58, 0
	v_mov_b32_e32 v59, 0
	v_mov_b32_e32 v60, 0
	v_mov_b32_e32 v61, 0
	v_mov_b32_e32 v62, 0
	v_mov_b32_e32 v63, 0
	v_mov_b32_e32 v64, 0
	v_mov_b32_e32 v65, 0
	v_mov_b32_e32 v66, 0
	v_mov_b32_e32 v67, 0
	v_mov_b32_e32 v68, 0
	v_mov_b32_e32 v69, 0
	v_mov_b32_e32 v70, 0
	v_mov_b32_e32 v71, 0
	v_mov_b32_e32 v72, 0
	v_mov_b32_e32 v73, 0
	v_mov_b32_e32 v74, 0
	v_mov_b32_e32 v75, 0
	v_mov_b32_e32 v76, 0
	v_mov_b32_e32 v77, 0
	v_mov_b32_e32 v78, 0
	v_mov_b32_e32 v79, 0
	v_mov_b32_e32 v80, 0
	v_mov_b32_e32 v81, 0
	v_mov_b32_e32 v82, 0
	v_mov_b32_e32 v83, 0
	v_mov_b32_e32 v84, 0
	v_mov_b32_e32 v85, 0
	v_mov_b32_e32 v86, 0
	v_mov_b32_e32 v87, 0
	v_mov_b32_e32 v88, 0
	v_mov_b32_e32 v89, 0
	v_mov_b32_e32 v90, 0
	v_mov_b32_e32 v91, 0
	v_mov_b32_e32 v92, 0
	v_mov_b32_e32 v93, 0
	v_mov_b32_e32 v94, 0
	v_mov_b32_e32 v95, 0
	v_mov_b32_e32 v96, 0
	v_mov_b32_e32 v97, 0
	v_mov_b32_e32 v98, 0
	v_mov_b32_e32 v99, 0
	v_mov_b32_e32 v100, 0
	v_mov_b32_e32 v101, 0
	v_mov_b32_e32 v102, 0
	v_mov_b32_e32 v103, 0
	v_mov_b32_e32 v104, 0
	v_mov_b32_e32 v105, 0
	v_mov_b32_e32 v106, 0
	v_mov_b32_e32 v107, 0
	v_mov_b32_e32 v108, 0
	v_mov_b32_e32 v109, 0
	v_mov_b32_e32 v110, 0
	v_mov_b32_e32 v111, 0
	v_mov_b32_e32 v112, 0
	v_mov_b32_e32 v113, 0
	v_mov_b32_e32 v114, 0
	v_mov_b32_e32 v115, 0
	v_mov_b32_e32 v116, 0
	v_mov_b32_e32 v117, 0
	v_mov_b32_e32 v118, 0
	v_mov_b32_e32 v119, 0
	v_mov_b32_e32 v120, 0
	v_mov_b32_e32 v121, 0
	v_mov_b32_e32 v122, 0
	v_mov_b32_e32 v123, 0
	v_mov_b32_e32 v124, 0
	v_mov_b32_e32 v125, 0
	v_mov_b32_e32 v126, 0
	v_mov_b32_e32 v127, 0
	v_mov_b32_e32 v128, 0
	v_mov_b32_e32 v129, 0
	s_barrier
;     ...
;   __syncthreads();
;   G2_STAGE(0); G2_STAGE(1);
;   const int fsw = (0x78 >> (((r16 >> 2) & 3) * 2)) & 3;
;   const int aoff = (wm * 128 + r16) * 64 + ((quad ^ fsw) << 4);
;   const int boff = 16384 + (wn * 64 + r16) * 64 + ((quad ^ fsw) << 4);
;   for (int kt = 0; kt < nk; kt++) {
;     if (kt + 1 < nk) asm volatile("s_waitcnt vmcnt(6)" ::: "memory");
;     else asm volatile("s_waitcnt vmcnt(0)" ::: "memory");
;     __builtin_amdgcn_s_barrier();
;     asm volatile("" ::: "memory");
;     if (kt + 2 < nk) G2_STAGE(kt + 2);
;     const char* cS = smem + (kt % 3) * 24576;
;     bf16x8 xa[8], wb[4];
; #pragma unroll
;     for (int f = 0; f < 8; f++) xa[f] = *(const bf16x8*)(cS + aoff + f * 1024);
; #pragma unroll
;     for (int f = 0; f < 4; f++) wb[f] = *(const bf16x8*)(cS + boff + f * 1024);
; #pragma unroll
;     for (int nf = 0; nf < 4; nf++)
; #pragma unroll
;       for (int mf = 0; mf < 8; mf++)
;         acc[nf][mf] = __builtin_amdgcn_mfma_f32_16x16x32_bf16(wb[nf], xa[mf], acc[nf][mf], 0, 0, 0);
	s_add_i32 s13, s98, 0x0
	s_mov_b32 m0, s13
	v_lshl_add_u64 v[142:143], v[132:133], 0, s[2:3]
	global_load_lds_dwordx4 v[132:133], off
	s_addk_i32 m0, 0x1000
	s_nop 0
	global_load_lds_dwordx4 v[142:143], off
	v_lshl_add_u64 v[142:143], v[142:143], 0, s[2:3]
	s_addk_i32 m0, 0x1000
	s_nop 0
	global_load_lds_dwordx4 v[142:143], off
	v_lshl_add_u64 v[142:143], v[142:143], 0, s[2:3]
	s_addk_i32 m0, 0x1000
	s_nop 0
	global_load_lds_dwordx4 v[142:143], off
	s_addk_i32 m0, 0x1000
	v_lshl_add_u64 v[142:143], v[134:135], 0, s[2:3]
	s_nop 0
	global_load_lds_dwordx4 v[134:135], off
	s_addk_i32 m0, 0x1000
	v_lshl_add_u64 v[132:133], v[132:133], 0, s[10:11]
	s_nop 0
	global_load_lds_dwordx4 v[142:143], off
	v_lshl_add_u64 v[134:135], v[134:135], 0, s[4:5]
	s_nop 0
	s_add_i32 s13, s98, 0x6000
	s_mov_b32 m0, s13
	v_lshl_add_u64 v[142:143], v[132:133], 0, s[2:3]
	global_load_lds_dwordx4 v[132:133], off
	s_addk_i32 m0, 0x1000
	s_nop 0
	global_load_lds_dwordx4 v[142:143], off
	v_lshl_add_u64 v[142:143], v[142:143], 0, s[2:3]
	s_addk_i32 m0, 0x1000
	s_nop 0
	global_load_lds_dwordx4 v[142:143], off
	v_lshl_add_u64 v[142:143], v[142:143], 0, s[2:3]
	s_addk_i32 m0, 0x1000
	s_nop 0
	global_load_lds_dwordx4 v[142:143], off
	s_addk_i32 m0, 0x1000
	v_lshl_add_u64 v[142:143], v[134:135], 0, s[2:3]
	s_nop 0
	global_load_lds_dwordx4 v[134:135], off
	s_addk_i32 m0, 0x1000
	v_lshl_add_u64 v[132:133], v[132:133], 0, s[10:11]
	s_nop 0
	global_load_lds_dwordx4 v[142:143], off
	v_lshl_add_u64 v[134:135], v[134:135], 0, s[4:5]
	s_nop 0
	s_add_i32 s13, s98, 0xc000
	s_mov_b32 m0, s13
	v_lshl_add_u64 v[142:143], v[132:133], 0, s[2:3]
	global_load_lds_dwordx4 v[132:133], off
	s_addk_i32 m0, 0x1000
	s_nop 0
	global_load_lds_dwordx4 v[142:143], off
	v_lshl_add_u64 v[142:143], v[142:143], 0, s[2:3]
	s_addk_i32 m0, 0x1000
	s_nop 0
	global_load_lds_dwordx4 v[142:143], off
	v_lshl_add_u64 v[142:143], v[142:143], 0, s[2:3]
	s_addk_i32 m0, 0x1000
	s_nop 0
	global_load_lds_dwordx4 v[142:143], off
	s_addk_i32 m0, 0x1000
	v_lshl_add_u64 v[142:143], v[134:135], 0, s[2:3]
	s_nop 0
	global_load_lds_dwordx4 v[134:135], off
	s_addk_i32 m0, 0x1000
	v_lshl_add_u64 v[132:133], v[132:133], 0, s[10:11]
	s_nop 0
	global_load_lds_dwordx4 v[142:143], off
	v_lshl_add_u64 v[134:135], v[134:135], 0, s[4:5]
	s_nop 0
	s_waitcnt vmcnt(12)
	s_barrier
	ds_read_b128 v[146:149], v136 offset:0
	ds_read_b128 v[152:155], v136 offset:1024
	ds_read_b128 v[156:159], v136 offset:2048
	ds_read_b128 v[162:165], v136 offset:3072
	ds_read_b128 v[166:169], v136 offset:4096
	ds_read_b128 v[170:173], v136 offset:5120
	ds_read_b128 v[176:179], v136 offset:6144
	ds_read_b128 v[180:183], v136 offset:7168
	ds_read_b128 v[184:187], v137 offset:16384
	ds_read_b128 v[188:191], v137 offset:17408
	ds_read_b128 v[192:195], v137 offset:18432
	ds_read_b128 v[196:199], v137 offset:19456
	s_movk_i32 s1, 0x6000
	s_mov_b32 s12, 0
	s_waitcnt vmcnt(6) lgkmcnt(0)
	s_barrier
	v_add_u32_e32 v144, s1, v136
	v_mfma_f32_16x16x32_bf16 v[126:129], v[184:187], v[146:149], v[126:129]
	ds_read_b128 v[200:203], v144 offset:0
	v_mfma_f32_16x16x32_bf16 v[122:125], v[184:187], v[152:155], v[122:125]
	ds_read_b128 v[204:207], v144 offset:1024
	v_mfma_f32_16x16x32_bf16 v[118:121], v[184:187], v[156:159], v[118:121]
	ds_read_b128 v[208:211], v144 offset:2048
	v_mfma_f32_16x16x32_bf16 v[114:117], v[184:187], v[162:165], v[114:117]
	ds_read_b128 v[212:215], v144 offset:3072
	v_mfma_f32_16x16x32_bf16 v[110:113], v[184:187], v[166:169], v[110:113]
	ds_read_b128 v[216:219], v144 offset:4096
	v_mfma_f32_16x16x32_bf16 v[106:109], v[184:187], v[170:173], v[106:109]
	ds_read_b128 v[220:223], v144 offset:5120
	v_mfma_f32_16x16x32_bf16 v[102:105], v[184:187], v[176:179], v[102:105]
	ds_read_b128 v[224:227], v144 offset:6144
	v_mfma_f32_16x16x32_bf16 v[98:101], v[184:187], v[180:183], v[98:101]
	ds_read_b128 v[228:231], v144 offset:7168
	v_mfma_f32_16x16x32_bf16 v[94:97], v[188:191], v[146:149], v[94:97]
	v_add_u32_e32 v144, s1, v137
	v_mfma_f32_16x16x32_bf16 v[90:93], v[188:191], v[152:155], v[90:93]
	v_mfma_f32_16x16x32_bf16 v[86:89], v[188:191], v[156:159], v[86:89]
	ds_read_b128 v[232:235], v144 offset:16384
	v_mfma_f32_16x16x32_bf16 v[82:85], v[188:191], v[162:165], v[82:85]
	ds_read_b128 v[236:239], v144 offset:17408
	v_mfma_f32_16x16x32_bf16 v[78:81], v[188:191], v[166:169], v[78:81]
	ds_read_b128 v[240:243], v144 offset:18432
	v_mfma_f32_16x16x32_bf16 v[74:77], v[188:191], v[170:173], v[74:77]
	ds_read_b128 v[244:247], v144 offset:19456
	s_add_i32 s13, s98, s12
	v_mfma_f32_16x16x32_bf16 v[70:73], v[188:191], v[176:179], v[70:73]
	s_mov_b32 m0, s13
	v_lshl_add_u64 v[142:143], v[132:133], 0, s[2:3]
	v_mfma_f32_16x16x32_bf16 v[66:69], v[188:191], v[180:183], v[66:69]
	global_load_lds_dwordx4 v[132:133], off
	s_addk_i32 m0, 0x1000
	v_mfma_f32_16x16x32_bf16 v[62:65], v[192:195], v[146:149], v[62:65]
	v_mfma_f32_16x16x32_bf16 v[58:61], v[192:195], v[152:155], v[58:61]
	v_mfma_f32_16x16x32_bf16 v[54:57], v[192:195], v[156:159], v[54:57]
	global_load_lds_dwordx4 v[142:143], off
	v_lshl_add_u64 v[142:143], v[142:143], 0, s[2:3]
	s_addk_i32 m0, 0x1000
	v_mfma_f32_16x16x32_bf16 v[50:53], v[192:195], v[162:165], v[50:53]
	v_mfma_f32_16x16x32_bf16 v[46:49], v[192:195], v[166:169], v[46:49]
	v_mfma_f32_16x16x32_bf16 v[42:45], v[192:195], v[170:173], v[42:45]
	global_load_lds_dwordx4 v[142:143], off
	v_lshl_add_u64 v[142:143], v[142:143], 0, s[2:3]
	s_addk_i32 m0, 0x1000
	v_mfma_f32_16x16x32_bf16 v[38:41], v[192:195], v[176:179], v[38:41]
	v_mfma_f32_16x16x32_bf16 v[34:37], v[192:195], v[180:183], v[34:37]
	v_mfma_f32_16x16x32_bf16 v[30:33], v[196:199], v[146:149], v[30:33]
	global_load_lds_dwordx4 v[142:143], off
	s_addk_i32 m0, 0x1000
	v_lshl_add_u64 v[142:143], v[134:135], 0, s[2:3]
	v_mfma_f32_16x16x32_bf16 v[26:29], v[196:199], v[152:155], v[26:29]
	v_mfma_f32_16x16x32_bf16 v[22:25], v[196:199], v[156:159], v[22:25]
	v_mfma_f32_16x16x32_bf16 v[18:21], v[196:199], v[162:165], v[18:21]
	global_load_lds_dwordx4 v[134:135], off
	s_addk_i32 m0, 0x1000
	v_lshl_add_u64 v[132:133], v[132:133], 0, s[10:11]
	v_mfma_f32_16x16x32_bf16 v[14:17], v[196:199], v[166:169], v[14:17]
	v_mfma_f32_16x16x32_bf16 v[10:13], v[196:199], v[170:173], v[10:13]
	v_mfma_f32_16x16x32_bf16 v[6:9], v[196:199], v[176:179], v[6:9]
	global_load_lds_dwordx4 v[142:143], off
	v_lshl_add_u64 v[134:135], v[134:135], 0, s[4:5]
	v_mfma_f32_16x16x32_bf16 v[2:5], v[196:199], v[180:183], v[2:5]
	s_mov_b32 s12, s1
	s_add_i32 s1, s1, 0x6000
	s_cmp_eq_u32 s1, 0x12000
	s_cselect_b32 s1, 0, s1
	s_waitcnt vmcnt(6) lgkmcnt(0)
	s_barrier
;     ...
;   for (int kt = 0; kt < nk; kt++) {
;     if (kt + 1 < nk) asm volatile("s_waitcnt vmcnt(6)" ::: "memory");
;     else asm volatile("s_waitcnt vmcnt(0)" ::: "memory");
;     __builtin_amdgcn_s_barrier();
;     asm volatile("" ::: "memory");
;     if (kt + 2 < nk) G2_STAGE(kt + 2);
;     const char* cS = smem + (kt % 3) * 24576;
;     bf16x8 xa[8], wb[4];
; #pragma unroll
;     for (int f = 0; f < 8; f++) xa[f] = *(const bf16x8*)(cS + aoff + f * 1024);
; #pragma unroll
;     for (int f = 0; f < 4; f++) wb[f] = *(const bf16x8*)(cS + boff + f * 1024);
; #pragma unroll
;     for (int nf = 0; nf < 4; nf++)
; #pragma unroll
;       for (int mf = 0; mf < 8; mf++)
;         acc[nf][mf] = __builtin_amdgcn_mfma_f32_16x16x32_bf16(wb[nf], xa[mf], acc[nf][mf], 0, 0, 0);
;   }
	v_add_u32_e32 v144, s1, v136
	v_mfma_f32_16x16x32_bf16 v[126:129], v[232:235], v[200:203], v[126:129]
	ds_read_b128 v[146:149], v144 offset:0
	v_mfma_f32_16x16x32_bf16 v[122:125], v[232:235], v[204:207], v[122:125]
	ds_read_b128 v[152:155], v144 offset:1024
	v_mfma_f32_16x16x32_bf16 v[118:121], v[232:235], v[208:211], v[118:121]
	ds_read_b128 v[156:159], v144 offset:2048
	v_mfma_f32_16x16x32_bf16 v[114:117], v[232:235], v[212:215], v[114:117]
	ds_read_b128 v[162:165], v144 offset:3072
	v_mfma_f32_16x16x32_bf16 v[110:113], v[232:235], v[216:219], v[110:113]
	ds_read_b128 v[166:169], v144 offset:4096
	v_mfma_f32_16x16x32_bf16 v[106:109], v[232:235], v[220:223], v[106:109]
	ds_read_b128 v[170:173], v144 offset:5120
	v_mfma_f32_16x16x32_bf16 v[102:105], v[232:235], v[224:227], v[102:105]
	ds_read_b128 v[176:179], v144 offset:6144
	v_mfma_f32_16x16x32_bf16 v[98:101], v[232:235], v[228:231], v[98:101]
	ds_read_b128 v[180:183], v144 offset:7168
	v_mfma_f32_16x16x32_bf16 v[94:97], v[236:239], v[200:203], v[94:97]
	v_add_u32_e32 v144, s1, v137
	v_mfma_f32_16x16x32_bf16 v[90:93], v[236:239], v[204:207], v[90:93]
	v_mfma_f32_16x16x32_bf16 v[86:89], v[236:239], v[208:211], v[86:89]
	ds_read_b128 v[184:187], v144 offset:16384
	v_mfma_f32_16x16x32_bf16 v[82:85], v[236:239], v[212:215], v[82:85]
	ds_read_b128 v[188:191], v144 offset:17408
	v_mfma_f32_16x16x32_bf16 v[78:81], v[236:239], v[216:219], v[78:81]
	ds_read_b128 v[192:195], v144 offset:18432
	v_mfma_f32_16x16x32_bf16 v[74:77], v[236:239], v[220:223], v[74:77]
	ds_read_b128 v[196:199], v144 offset:19456
	v_mfma_f32_16x16x32_bf16 v[70:73], v[236:239], v[224:227], v[70:73]
	v_mfma_f32_16x16x32_bf16 v[66:69], v[236:239], v[228:231], v[66:69]
	v_mfma_f32_16x16x32_bf16 v[62:65], v[240:243], v[200:203], v[62:65]
	v_mfma_f32_16x16x32_bf16 v[58:61], v[240:243], v[204:207], v[58:61]
	v_mfma_f32_16x16x32_bf16 v[54:57], v[240:243], v[208:211], v[54:57]
	v_mfma_f32_16x16x32_bf16 v[50:53], v[240:243], v[212:215], v[50:53]
	v_mfma_f32_16x16x32_bf16 v[46:49], v[240:243], v[216:219], v[46:49]
	v_mfma_f32_16x16x32_bf16 v[42:45], v[240:243], v[220:223], v[42:45]
	v_mfma_f32_16x16x32_bf16 v[38:41], v[240:243], v[224:227], v[38:41]
	v_mfma_f32_16x16x32_bf16 v[34:37], v[240:243], v[228:231], v[34:37]
	v_mfma_f32_16x16x32_bf16 v[30:33], v[244:247], v[200:203], v[30:33]
	v_mfma_f32_16x16x32_bf16 v[26:29], v[244:247], v[204:207], v[26:29]
	v_mfma_f32_16x16x32_bf16 v[22:25], v[244:247], v[208:211], v[22:25]
	v_mfma_f32_16x16x32_bf16 v[18:21], v[244:247], v[212:215], v[18:21]
	v_mfma_f32_16x16x32_bf16 v[14:17], v[244:247], v[216:219], v[14:17]
	v_mfma_f32_16x16x32_bf16 v[10:13], v[244:247], v[220:223], v[10:13]
	v_mfma_f32_16x16x32_bf16 v[6:9], v[244:247], v[224:227], v[6:9]
	v_mfma_f32_16x16x32_bf16 v[2:5], v[244:247], v[228:231], v[2:5]
	s_mov_b32 s12, s1
	s_add_i32 s1, s1, 0x6000
	s_cmp_eq_u32 s1, 0x12000
	s_cselect_b32 s1, 0, s1
	s_waitcnt vmcnt(0) lgkmcnt(0)
	s_barrier
	v_add_u32_e32 v144, s1, v136
	v_mfma_f32_16x16x32_bf16 v[126:129], v[184:187], v[146:149], v[126:129]
	ds_read_b128 v[200:203], v144 offset:0
	v_mfma_f32_16x16x32_bf16 v[122:125], v[184:187], v[152:155], v[122:125]
	ds_read_b128 v[204:207], v144 offset:1024
	v_mfma_f32_16x16x32_bf16 v[118:121], v[184:187], v[156:159], v[118:121]
	ds_read_b128 v[208:211], v144 offset:2048
	v_mfma_f32_16x16x32_bf16 v[114:117], v[184:187], v[162:165], v[114:117]
	ds_read_b128 v[212:215], v144 offset:3072
	v_mfma_f32_16x16x32_bf16 v[110:113], v[184:187], v[166:169], v[110:113]
	ds_read_b128 v[216:219], v144 offset:4096
	v_mfma_f32_16x16x32_bf16 v[106:109], v[184:187], v[170:173], v[106:109]
	ds_read_b128 v[220:223], v144 offset:5120
	v_mfma_f32_16x16x32_bf16 v[102:105], v[184:187], v[176:179], v[102:105]
	ds_read_b128 v[224:227], v144 offset:6144
	v_mfma_f32_16x16x32_bf16 v[98:101], v[184:187], v[180:183], v[98:101]
	ds_read_b128 v[228:231], v144 offset:7168
	v_mfma_f32_16x16x32_bf16 v[94:97], v[188:191], v[146:149], v[94:97]
	v_add_u32_e32 v144, s1, v137
	v_mfma_f32_16x16x32_bf16 v[90:93], v[188:191], v[152:155], v[90:93]
	v_mfma_f32_16x16x32_bf16 v[86:89], v[188:191], v[156:159], v[86:89]
	ds_read_b128 v[232:235], v144 offset:16384
	v_mfma_f32_16x16x32_bf16 v[82:85], v[188:191], v[162:165], v[82:85]
	ds_read_b128 v[236:239], v144 offset:17408
	v_mfma_f32_16x16x32_bf16 v[78:81], v[188:191], v[166:169], v[78:81]
	ds_read_b128 v[240:243], v144 offset:18432
	v_mfma_f32_16x16x32_bf16 v[74:77], v[188:191], v[170:173], v[74:77]
	ds_read_b128 v[244:247], v144 offset:19456
	v_mfma_f32_16x16x32_bf16 v[70:73], v[188:191], v[176:179], v[70:73]
	v_mfma_f32_16x16x32_bf16 v[66:69], v[188:191], v[180:183], v[66:69]
	v_mfma_f32_16x16x32_bf16 v[62:65], v[192:195], v[146:149], v[62:65]
	v_mfma_f32_16x16x32_bf16 v[58:61], v[192:195], v[152:155], v[58:61]
	v_mfma_f32_16x16x32_bf16 v[54:57], v[192:195], v[156:159], v[54:57]
	v_mfma_f32_16x16x32_bf16 v[50:53], v[192:195], v[162:165], v[50:53]
	v_mfma_f32_16x16x32_bf16 v[46:49], v[192:195], v[166:169], v[46:49]
	v_mfma_f32_16x16x32_bf16 v[42:45], v[192:195], v[170:173], v[42:45]
	v_mfma_f32_16x16x32_bf16 v[38:41], v[192:195], v[176:179], v[38:41]
	v_mfma_f32_16x16x32_bf16 v[34:37], v[192:195], v[180:183], v[34:37]
	v_mfma_f32_16x16x32_bf16 v[30:33], v[196:199], v[146:149], v[30:33]
	v_mfma_f32_16x16x32_bf16 v[26:29], v[196:199], v[152:155], v[26:29]
	v_mfma_f32_16x16x32_bf16 v[22:25], v[196:199], v[156:159], v[22:25]
	v_mfma_f32_16x16x32_bf16 v[18:21], v[196:199], v[162:165], v[18:21]
	v_mfma_f32_16x16x32_bf16 v[14:17], v[196:199], v[166:169], v[14:17]
	v_mfma_f32_16x16x32_bf16 v[10:13], v[196:199], v[170:173], v[10:13]
	v_mfma_f32_16x16x32_bf16 v[6:9], v[196:199], v[176:179], v[6:9]
	v_mfma_f32_16x16x32_bf16 v[2:5], v[196:199], v[180:183], v[2:5]
	s_mov_b32 s12, s1
	s_add_i32 s1, s1, 0x6000
	s_cmp_eq_u32 s1, 0x12000
	s_cselect_b32 s1, 0, s1
	s_mov_b32 s4, 0x8000
	s_mov_b32 s5, 0
	s_mov_b32 s8, 0x10000
	s_mov_b32 s9, 0
	s_mov_b32 s40, 0x3fd744fd
	s_waitcnt lgkmcnt(0)
; DEVI float blo(unsigned u) { return __uint_as_float(u << 16); }
; DEVI float bhi(unsigned u) { return __uint_as_float(u & 0xffff0000u); }
;     ...
;     for (int nf = 0; nf < 4; nf++)
; #pragma unroll
;       for (int mf = 0; mf < 8; mf++)
;         acc[nf][mf] = __builtin_amdgcn_mfma_f32_16x16x32_bf16(wb[nf], xa[mf], acc[nf][mf], 0, 0, 0);
;     ...
;         if (EPI == EPI_RESID || EPI == EPI_RESID_ATOMIC) {
;           f32x4 x = a;
;           if (EPI == EPI_RESID || kpart == 0) {
;             const u32x2 xr = *(const u32x2*)((const u16*)(p.ws + WS_XB) + (size_t)row * 1024 + col);
;             x[0] += ALPHA * blo(xr[0]); x[1] += ALPHA * bhi(xr[0]); x[2] += ALPHA * blo(xr[1]); x[3] += ALPHA * bhi(xr[1]);
;           }
;           if (EPI == EPI_RESID) *(f32x4*)((float*)(p.ws + WS_XF) + (size_t)row * 1024 + col) = x;
;           else *(f32x4*)((float*)(p.ws + WS_SLAB) + ((size_t)kpart * 512 + (row - T_P)) * 1024 + col) = x;
	v_mfma_f32_16x16x32_bf16 v[126:129], v[232:235], v[200:203], v[126:129]
	v_mfma_f32_16x16x32_bf16 v[122:125], v[232:235], v[204:207], v[122:125]
	v_mfma_f32_16x16x32_bf16 v[118:121], v[232:235], v[208:211], v[118:121]
	v_mfma_f32_16x16x32_bf16 v[114:117], v[232:235], v[212:215], v[114:117]
	v_mfma_f32_16x16x32_bf16 v[110:113], v[232:235], v[216:219], v[110:113]
	v_mfma_f32_16x16x32_bf16 v[106:109], v[232:235], v[220:223], v[106:109]
	v_mfma_f32_16x16x32_bf16 v[102:105], v[232:235], v[224:227], v[102:105]
	v_mfma_f32_16x16x32_bf16 v[98:101], v[232:235], v[228:231], v[98:101]
	v_mfma_f32_16x16x32_bf16 v[94:97], v[236:239], v[200:203], v[94:97]
	v_mfma_f32_16x16x32_bf16 v[90:93], v[236:239], v[204:207], v[90:93]
	v_mfma_f32_16x16x32_bf16 v[86:89], v[236:239], v[208:211], v[86:89]
	v_mfma_f32_16x16x32_bf16 v[82:85], v[236:239], v[212:215], v[82:85]
	v_mfma_f32_16x16x32_bf16 v[78:81], v[236:239], v[216:219], v[78:81]
	v_mfma_f32_16x16x32_bf16 v[74:77], v[236:239], v[220:223], v[74:77]
	v_mfma_f32_16x16x32_bf16 v[70:73], v[236:239], v[224:227], v[70:73]
	v_mfma_f32_16x16x32_bf16 v[66:69], v[236:239], v[228:231], v[66:69]
	v_mfma_f32_16x16x32_bf16 v[62:65], v[240:243], v[200:203], v[62:65]
	v_mfma_f32_16x16x32_bf16 v[58:61], v[240:243], v[204:207], v[58:61]
	v_mfma_f32_16x16x32_bf16 v[54:57], v[240:243], v[208:211], v[54:57]
	v_mfma_f32_16x16x32_bf16 v[50:53], v[240:243], v[212:215], v[50:53]
	v_mfma_f32_16x16x32_bf16 v[46:49], v[240:243], v[216:219], v[46:49]
	v_mfma_f32_16x16x32_bf16 v[42:45], v[240:243], v[220:223], v[42:45]
	v_mfma_f32_16x16x32_bf16 v[38:41], v[240:243], v[224:227], v[38:41]
	v_mfma_f32_16x16x32_bf16 v[34:37], v[240:243], v[228:231], v[34:37]
	v_mfma_f32_16x16x32_bf16 v[30:33], v[244:247], v[200:203], v[30:33]
	v_mfma_f32_16x16x32_bf16 v[26:29], v[244:247], v[204:207], v[26:29]
	v_mfma_f32_16x16x32_bf16 v[22:25], v[244:247], v[208:211], v[22:25]
	v_mfma_f32_16x16x32_bf16 v[18:21], v[244:247], v[212:215], v[18:21]
	v_mfma_f32_16x16x32_bf16 v[14:17], v[244:247], v[216:219], v[14:17]
	v_mfma_f32_16x16x32_bf16 v[10:13], v[244:247], v[220:223], v[10:13]
	v_mfma_f32_16x16x32_bf16 v[6:9], v[244:247], v[224:227], v[6:9]
	v_mfma_f32_16x16x32_bf16 v[2:5], v[244:247], v[228:231], v[2:5]
	s_mov_b32 m0, s39
	s_cmp_eq_u32 s99, 0
	s_cbranch_scc1 .Lta8_first
	s_nop 7
	global_store_dwordx4 v[140:141], v[126:129], off offset:0
	global_store_dwordx4 v[140:141], v[94:97], off offset:64
	global_store_dwordx4 v[140:141], v[62:65], off offset:128
	global_store_dwordx4 v[140:141], v[30:33], off offset:192
	v_lshl_add_u64 v[140:141], v[140:141], 0, s[8:9]
	global_store_dwordx4 v[140:141], v[122:125], off offset:0
	global_store_dwordx4 v[140:141], v[90:93], off offset:64
	global_store_dwordx4 v[140:141], v[58:61], off offset:128
	global_store_dwordx4 v[140:141], v[26:29], off offset:192
	v_lshl_add_u64 v[140:141], v[140:141], 0, s[8:9]
	global_store_dwordx4 v[140:141], v[118:121], off offset:0
	global_store_dwordx4 v[140:141], v[86:89], off offset:64
	global_store_dwordx4 v[140:141], v[54:57], off offset:128
	global_store_dwordx4 v[140:141], v[22:25], off offset:192
	v_lshl_add_u64 v[140:141], v[140:141], 0, s[8:9]
	global_store_dwordx4 v[140:141], v[114:117], off offset:0
	global_store_dwordx4 v[140:141], v[82:85], off offset:64
	global_store_dwordx4 v[140:141], v[50:53], off offset:128
	global_store_dwordx4 v[140:141], v[18:21], off offset:192
	v_lshl_add_u64 v[140:141], v[140:141], 0, s[8:9]
	global_store_dwordx4 v[140:141], v[110:113], off offset:0
	global_store_dwordx4 v[140:141], v[78:81], off offset:64
	global_store_dwordx4 v[140:141], v[46:49], off offset:128
	global_store_dwordx4 v[140:141], v[14:17], off offset:192
	v_lshl_add_u64 v[140:141], v[140:141], 0, s[8:9]
	global_store_dwordx4 v[140:141], v[106:109], off offset:0
	global_store_dwordx4 v[140:141], v[74:77], off offset:64
	global_store_dwordx4 v[140:141], v[42:45], off offset:128
	global_store_dwordx4 v[140:141], v[10:13], off offset:192
	v_lshl_add_u64 v[140:141], v[140:141], 0, s[8:9]
	global_store_dwordx4 v[140:141], v[102:105], off offset:0
	global_store_dwordx4 v[140:141], v[70:73], off offset:64
	global_store_dwordx4 v[140:141], v[38:41], off offset:128
	global_store_dwordx4 v[140:141], v[6:9], off offset:192
	v_lshl_add_u64 v[140:141], v[140:141], 0, s[8:9]
	global_store_dwordx4 v[140:141], v[98:101], off offset:0
	global_store_dwordx4 v[140:141], v[66:69], off offset:64
	global_store_dwordx4 v[140:141], v[34:37], off offset:128
	global_store_dwordx4 v[140:141], v[2:5], off offset:192
	s_branch .LBB0_146
; DEVI float blo(unsigned u) { return __uint_as_float(u << 16); }
; DEVI float bhi(unsigned u) { return __uint_as_float(u & 0xffff0000u); }
;     ...
;         if (EPI == EPI_RESID || EPI == EPI_RESID_ATOMIC) {
;           f32x4 x = a;
;           if (EPI == EPI_RESID || kpart == 0) {
;             const u32x2 xr = *(const u32x2*)((const u16*)(p.ws + WS_XB) + (size_t)row * 1024 + col);
;             x[0] += ALPHA * blo(xr[0]); x[1] += ALPHA * bhi(xr[0]); x[2] += ALPHA * blo(xr[1]); x[3] += ALPHA * bhi(xr[1]);
;           }
;           if (EPI == EPI_RESID) *(f32x4*)((float*)(p.ws + WS_XF) + (size_t)row * 1024 + col) = x;
;           else *(f32x4*)((float*)(p.ws + WS_SLAB) + ((size_t)kpart * 512 + (row - T_P)) * 1024 + col) = x;
.Lta8_first:
	global_load_dwordx4 v[146:149], v[138:139], off offset:0
	global_load_dwordx4 v[152:155], v[138:139], off offset:64
	v_lshl_add_u64 v[138:139], v[138:139], 0, s[4:5]
	global_load_dwordx4 v[156:159], v[138:139], off offset:0
	global_load_dwordx4 v[162:165], v[138:139], off offset:64
	v_lshl_add_u64 v[138:139], v[138:139], 0, s[4:5]
	global_load_dwordx4 v[166:169], v[138:139], off offset:0
	global_load_dwordx4 v[170:173], v[138:139], off offset:64
	v_lshl_add_u64 v[138:139], v[138:139], 0, s[4:5]
	global_load_dwordx4 v[176:179], v[138:139], off offset:0
	global_load_dwordx4 v[180:183], v[138:139], off offset:64
	v_lshl_add_u64 v[138:139], v[138:139], 0, s[4:5]
	global_load_dwordx4 v[184:187], v[138:139], off offset:0
	global_load_dwordx4 v[188:191], v[138:139], off offset:64
	v_lshl_add_u64 v[138:139], v[138:139], 0, s[4:5]
	global_load_dwordx4 v[192:195], v[138:139], off offset:0
	global_load_dwordx4 v[196:199], v[138:139], off offset:64
	v_lshl_add_u64 v[138:139], v[138:139], 0, s[4:5]
	global_load_dwordx4 v[200:203], v[138:139], off offset:0
	global_load_dwordx4 v[204:207], v[138:139], off offset:64
	v_lshl_add_u64 v[138:139], v[138:139], 0, s[4:5]
	global_load_dwordx4 v[208:211], v[138:139], off offset:0
	global_load_dwordx4 v[212:215], v[138:139], off offset:64
	v_lshl_add_u64 v[138:139], v[138:139], 0, s[4:5]
	s_nop 7
	s_waitcnt vmcnt(15)
	v_permlane16_swap_b32_e32 v146, v148
	v_permlane16_swap_b32_e32 v147, v149
	v_lshlrev_b32_e32 v216, 16, v146
	v_and_b32_e32 v146, 0xffff0000, v146
	v_lshlrev_b32_e32 v217, 16, v147
	v_and_b32_e32 v147, 0xffff0000, v147
	v_fmac_f32_e32 v126, s40, v216
	v_fmac_f32_e32 v127, s40, v146
	v_fmac_f32_e32 v128, s40, v217
	v_fmac_f32_e32 v129, s40, v147
	global_store_dwordx4 v[140:141], v[126:129], off offset:0
	v_lshlrev_b32_e32 v216, 16, v148
	v_and_b32_e32 v148, 0xffff0000, v148
	v_lshlrev_b32_e32 v217, 16, v149
	v_and_b32_e32 v149, 0xffff0000, v149
	v_fmac_f32_e32 v94, s40, v216
	v_fmac_f32_e32 v95, s40, v148
	v_fmac_f32_e32 v96, s40, v217
	v_fmac_f32_e32 v97, s40, v149
	global_store_dwordx4 v[140:141], v[94:97], off offset:64
	s_waitcnt vmcnt(16)
	v_permlane16_swap_b32_e32 v152, v154
	v_permlane16_swap_b32_e32 v153, v155
	v_lshlrev_b32_e32 v216, 16, v152
	v_and_b32_e32 v152, 0xffff0000, v152
	v_lshlrev_b32_e32 v217, 16, v153
	v_and_b32_e32 v153, 0xffff0000, v153
	v_fmac_f32_e32 v62, s40, v216
	v_fmac_f32_e32 v63, s40, v152
	v_fmac_f32_e32 v64, s40, v217
	v_fmac_f32_e32 v65, s40, v153
	global_store_dwordx4 v[140:141], v[62:65], off offset:128
	v_lshlrev_b32_e32 v216, 16, v154
	v_and_b32_e32 v154, 0xffff0000, v154
	v_lshlrev_b32_e32 v217, 16, v155
	v_and_b32_e32 v155, 0xffff0000, v155
	v_fmac_f32_e32 v30, s40, v216
	v_fmac_f32_e32 v31, s40, v154
	v_fmac_f32_e32 v32, s40, v217
	v_fmac_f32_e32 v33, s40, v155
	global_store_dwordx4 v[140:141], v[30:33], off offset:192
	v_lshl_add_u64 v[140:141], v[140:141], 0, s[8:9]
	s_waitcnt vmcnt(17)
	v_permlane16_swap_b32_e32 v156, v158
	v_permlane16_swap_b32_e32 v157, v159
	v_lshlrev_b32_e32 v216, 16, v156
	v_and_b32_e32 v156, 0xffff0000, v156
	v_lshlrev_b32_e32 v217, 16, v157
	v_and_b32_e32 v157, 0xffff0000, v157
	v_fmac_f32_e32 v122, s40, v216
	v_fmac_f32_e32 v123, s40, v156
	v_fmac_f32_e32 v124, s40, v217
	v_fmac_f32_e32 v125, s40, v157
	global_store_dwordx4 v[140:141], v[122:125], off offset:0
	v_lshlrev_b32_e32 v216, 16, v158
	v_and_b32_e32 v158, 0xffff0000, v158
	v_lshlrev_b32_e32 v217, 16, v159
	v_and_b32_e32 v159, 0xffff0000, v159
	v_fmac_f32_e32 v90, s40, v216
	v_fmac_f32_e32 v91, s40, v158
	v_fmac_f32_e32 v92, s40, v217
	v_fmac_f32_e32 v93, s40, v159
	global_store_dwordx4 v[140:141], v[90:93], off offset:64
	s_waitcnt vmcnt(18)
	v_permlane16_swap_b32_e32 v162, v164
	v_permlane16_swap_b32_e32 v163, v165
	v_lshlrev_b32_e32 v216, 16, v162
	v_and_b32_e32 v162, 0xffff0000, v162
	v_lshlrev_b32_e32 v217, 16, v163
	v_and_b32_e32 v163, 0xffff0000, v163
	v_fmac_f32_e32 v58, s40, v216
	v_fmac_f32_e32 v59, s40, v162
	v_fmac_f32_e32 v60, s40, v217
	v_fmac_f32_e32 v61, s40, v163
	global_store_dwordx4 v[140:141], v[58:61], off offset:128
	v_lshlrev_b32_e32 v216, 16, v164
	v_and_b32_e32 v164, 0xffff0000, v164
	v_lshlrev_b32_e32 v217, 16, v165
	v_and_b32_e32 v165, 0xffff0000, v165
	v_fmac_f32_e32 v26, s40, v216
	v_fmac_f32_e32 v27, s40, v164
	v_fmac_f32_e32 v28, s40, v217
	v_fmac_f32_e32 v29, s40, v165
	global_store_dwordx4 v[140:141], v[26:29], off offset:192
	v_lshl_add_u64 v[140:141], v[140:141], 0, s[8:9]
	s_waitcnt vmcnt(19)
	v_permlane16_swap_b32_e32 v166, v168
	v_permlane16_swap_b32_e32 v167, v169
	v_lshlrev_b32_e32 v216, 16, v166
	v_and_b32_e32 v166, 0xffff0000, v166
	v_lshlrev_b32_e32 v217, 16, v167
	v_and_b32_e32 v167, 0xffff0000, v167
	v_fmac_f32_e32 v118, s40, v216
	v_fmac_f32_e32 v119, s40, v166
	v_fmac_f32_e32 v120, s40, v217
	v_fmac_f32_e32 v121, s40, v167
	global_store_dwordx4 v[140:141], v[118:121], off offset:0
	v_lshlrev_b32_e32 v216, 16, v168
	v_and_b32_e32 v168, 0xffff0000, v168
	v_lshlrev_b32_e32 v217, 16, v169
	v_and_b32_e32 v169, 0xffff0000, v169
	v_fmac_f32_e32 v86, s40, v216
	v_fmac_f32_e32 v87, s40, v168
	v_fmac_f32_e32 v88, s40, v217
	v_fmac_f32_e32 v89, s40, v169
	global_store_dwordx4 v[140:141], v[86:89], off offset:64
	s_waitcnt vmcnt(20)
; DEVI float blo(unsigned u) { return __uint_as_float(u << 16); }
; DEVI float bhi(unsigned u) { return __uint_as_float(u & 0xffff0000u); }
;     ...
;         if (EPI == EPI_RESID || EPI == EPI_RESID_ATOMIC) {
;           f32x4 x = a;
;           if (EPI == EPI_RESID || kpart == 0) {
;             const u32x2 xr = *(const u32x2*)((const u16*)(p.ws + WS_XB) + (size_t)row * 1024 + col);
;             x[0] += ALPHA * blo(xr[0]); x[1] += ALPHA * bhi(xr[0]); x[2] += ALPHA * blo(xr[1]); x[3] += ALPHA * bhi(xr[1]);
;           }
;           if (EPI == EPI_RESID) *(f32x4*)((float*)(p.ws + WS_XF) + (size_t)row * 1024 + col) = x;
;           else *(f32x4*)((float*)(p.ws + WS_SLAB) + ((size_t)kpart * 512 + (row - T_P)) * 1024 + col) = x;
	v_permlane16_swap_b32_e32 v170, v172
	v_permlane16_swap_b32_e32 v171, v173
	v_lshlrev_b32_e32 v216, 16, v170
	v_and_b32_e32 v170, 0xffff0000, v170
	v_lshlrev_b32_e32 v217, 16, v171
	v_and_b32_e32 v171, 0xffff0000, v171
	v_fmac_f32_e32 v54, s40, v216
	v_fmac_f32_e32 v55, s40, v170
	v_fmac_f32_e32 v56, s40, v217
	v_fmac_f32_e32 v57, s40, v171
	global_store_dwordx4 v[140:141], v[54:57], off offset:128
	v_lshlrev_b32_e32 v216, 16, v172
	v_and_b32_e32 v172, 0xffff0000, v172
	v_lshlrev_b32_e32 v217, 16, v173
	v_and_b32_e32 v173, 0xffff0000, v173
	v_fmac_f32_e32 v22, s40, v216
	v_fmac_f32_e32 v23, s40, v172
	v_fmac_f32_e32 v24, s40, v217
	v_fmac_f32_e32 v25, s40, v173
	global_store_dwordx4 v[140:141], v[22:25], off offset:192
	v_lshl_add_u64 v[140:141], v[140:141], 0, s[8:9]
	s_waitcnt vmcnt(21)
	v_permlane16_swap_b32_e32 v176, v178
	v_permlane16_swap_b32_e32 v177, v179
	v_lshlrev_b32_e32 v216, 16, v176
	v_and_b32_e32 v176, 0xffff0000, v176
	v_lshlrev_b32_e32 v217, 16, v177
	v_and_b32_e32 v177, 0xffff0000, v177
	v_fmac_f32_e32 v114, s40, v216
	v_fmac_f32_e32 v115, s40, v176
	v_fmac_f32_e32 v116, s40, v217
	v_fmac_f32_e32 v117, s40, v177
	global_store_dwordx4 v[140:141], v[114:117], off offset:0
	v_lshlrev_b32_e32 v216, 16, v178
	v_and_b32_e32 v178, 0xffff0000, v178
	v_lshlrev_b32_e32 v217, 16, v179
	v_and_b32_e32 v179, 0xffff0000, v179
	v_fmac_f32_e32 v82, s40, v216
	v_fmac_f32_e32 v83, s40, v178
	v_fmac_f32_e32 v84, s40, v217
	v_fmac_f32_e32 v85, s40, v179
	global_store_dwordx4 v[140:141], v[82:85], off offset:64
	s_waitcnt vmcnt(22)
	v_permlane16_swap_b32_e32 v180, v182
	v_permlane16_swap_b32_e32 v181, v183
	v_lshlrev_b32_e32 v216, 16, v180
	v_and_b32_e32 v180, 0xffff0000, v180
	v_lshlrev_b32_e32 v217, 16, v181
	v_and_b32_e32 v181, 0xffff0000, v181
	v_fmac_f32_e32 v50, s40, v216
	v_fmac_f32_e32 v51, s40, v180
	v_fmac_f32_e32 v52, s40, v217
	v_fmac_f32_e32 v53, s40, v181
	global_store_dwordx4 v[140:141], v[50:53], off offset:128
	v_lshlrev_b32_e32 v216, 16, v182
	v_and_b32_e32 v182, 0xffff0000, v182
	v_lshlrev_b32_e32 v217, 16, v183
	v_and_b32_e32 v183, 0xffff0000, v183
	v_fmac_f32_e32 v18, s40, v216
	v_fmac_f32_e32 v19, s40, v182
	v_fmac_f32_e32 v20, s40, v217
	v_fmac_f32_e32 v21, s40, v183
	global_store_dwordx4 v[140:141], v[18:21], off offset:192
	v_lshl_add_u64 v[140:141], v[140:141], 0, s[8:9]
	s_waitcnt vmcnt(23)
	v_permlane16_swap_b32_e32 v184, v186
	v_permlane16_swap_b32_e32 v185, v187
	v_lshlrev_b32_e32 v216, 16, v184
	v_and_b32_e32 v184, 0xffff0000, v184
	v_lshlrev_b32_e32 v217, 16, v185
	v_and_b32_e32 v185, 0xffff0000, v185
	v_fmac_f32_e32 v110, s40, v216
	v_fmac_f32_e32 v111, s40, v184
	v_fmac_f32_e32 v112, s40, v217
	v_fmac_f32_e32 v113, s40, v185
	global_store_dwordx4 v[140:141], v[110:113], off offset:0
	v_lshlrev_b32_e32 v216, 16, v186
	v_and_b32_e32 v186, 0xffff0000, v186
	v_lshlrev_b32_e32 v217, 16, v187
	v_and_b32_e32 v187, 0xffff0000, v187
	v_fmac_f32_e32 v78, s40, v216
	v_fmac_f32_e32 v79, s40, v186
	v_fmac_f32_e32 v80, s40, v217
	v_fmac_f32_e32 v81, s40, v187
	global_store_dwordx4 v[140:141], v[78:81], off offset:64
	s_waitcnt vmcnt(24)
	v_permlane16_swap_b32_e32 v188, v190
	v_permlane16_swap_b32_e32 v189, v191
	v_lshlrev_b32_e32 v216, 16, v188
	v_and_b32_e32 v188, 0xffff0000, v188
	v_lshlrev_b32_e32 v217, 16, v189
	v_and_b32_e32 v189, 0xffff0000, v189
	v_fmac_f32_e32 v46, s40, v216
	v_fmac_f32_e32 v47, s40, v188
	v_fmac_f32_e32 v48, s40, v217
	v_fmac_f32_e32 v49, s40, v189
	global_store_dwordx4 v[140:141], v[46:49], off offset:128
	v_lshlrev_b32_e32 v216, 16, v190
	v_and_b32_e32 v190, 0xffff0000, v190
	v_lshlrev_b32_e32 v217, 16, v191
	v_and_b32_e32 v191, 0xffff0000, v191
	v_fmac_f32_e32 v14, s40, v216
	v_fmac_f32_e32 v15, s40, v190
	v_fmac_f32_e32 v16, s40, v217
	v_fmac_f32_e32 v17, s40, v191
	global_store_dwordx4 v[140:141], v[14:17], off offset:192
	v_lshl_add_u64 v[140:141], v[140:141], 0, s[8:9]
	s_waitcnt vmcnt(25)
	v_permlane16_swap_b32_e32 v192, v194
	v_permlane16_swap_b32_e32 v193, v195
	v_lshlrev_b32_e32 v216, 16, v192
	v_and_b32_e32 v192, 0xffff0000, v192
	v_lshlrev_b32_e32 v217, 16, v193
	v_and_b32_e32 v193, 0xffff0000, v193
	v_fmac_f32_e32 v106, s40, v216
	v_fmac_f32_e32 v107, s40, v192
	v_fmac_f32_e32 v108, s40, v217
	v_fmac_f32_e32 v109, s40, v193
	global_store_dwordx4 v[140:141], v[106:109], off offset:0
	v_lshlrev_b32_e32 v216, 16, v194
	v_and_b32_e32 v194, 0xffff0000, v194
	v_lshlrev_b32_e32 v217, 16, v195
	v_and_b32_e32 v195, 0xffff0000, v195
	v_fmac_f32_e32 v74, s40, v216
	v_fmac_f32_e32 v75, s40, v194
	v_fmac_f32_e32 v76, s40, v217
	v_fmac_f32_e32 v77, s40, v195
	global_store_dwordx4 v[140:141], v[74:77], off offset:64
	s_waitcnt vmcnt(26)
	v_permlane16_swap_b32_e32 v196, v198
	v_permlane16_swap_b32_e32 v197, v199
	v_lshlrev_b32_e32 v216, 16, v196
	v_and_b32_e32 v196, 0xffff0000, v196
	v_lshlrev_b32_e32 v217, 16, v197
	v_and_b32_e32 v197, 0xffff0000, v197
	v_fmac_f32_e32 v42, s40, v216
	v_fmac_f32_e32 v43, s40, v196
	v_fmac_f32_e32 v44, s40, v217
	v_fmac_f32_e32 v45, s40, v197
	global_store_dwordx4 v[140:141], v[42:45], off offset:128
	v_lshlrev_b32_e32 v216, 16, v198
	v_and_b32_e32 v198, 0xffff0000, v198
	v_lshlrev_b32_e32 v217, 16, v199
	v_and_b32_e32 v199, 0xffff0000, v199
	v_fmac_f32_e32 v10, s40, v216
	v_fmac_f32_e32 v11, s40, v198
	v_fmac_f32_e32 v12, s40, v217
	v_fmac_f32_e32 v13, s40, v199
	global_store_dwordx4 v[140:141], v[10:13], off offset:192
	v_lshl_add_u64 v[140:141], v[140:141], 0, s[8:9]
	s_waitcnt vmcnt(27)
; DEVI float blo(unsigned u) { return __uint_as_float(u << 16); }
; DEVI float bhi(unsigned u) { return __uint_as_float(u & 0xffff0000u); }
; DEVI int xcd_first_tile() { return (blockIdx.x & 7) * (gridDim.x >> 3) + (blockIdx.x >> 3); }
;     ...
;         if (EPI == EPI_RESID || EPI == EPI_RESID_ATOMIC) {
;           f32x4 x = a;
;           if (EPI == EPI_RESID || kpart == 0) {
;             const u32x2 xr = *(const u32x2*)((const u16*)(p.ws + WS_XB) + (size_t)row * 1024 + col);
;             x[0] += ALPHA * blo(xr[0]); x[1] += ALPHA * bhi(xr[0]); x[2] += ALPHA * blo(xr[1]); x[3] += ALPHA * bhi(xr[1]);
;           }
;           if (EPI == EPI_RESID) *(f32x4*)((float*)(p.ws + WS_XF) + (size_t)row * 1024 + col) = x;
;           else *(f32x4*)((float*)(p.ws + WS_SLAB) + ((size_t)kpart * 512 + (row - T_P)) * 1024 + col) = x;
; DEVI void run_phase(const Params& p, int ph, char* smem) {
;     ...
;       for (int t = xcd_first_tile(); t < 512 + 16 * 2; t += xcd_tile_step()) {
;         if (t < 512) {
;           int mt_, nt_; tile_coords(t, 64, 8, mt_, nt_);
;           gemm_tile256<EPI_RESID>(p, ox, 256, Bt, 256, mt_ * 256, nt_ * 128, nullptr, 0, smem);
	v_permlane16_swap_b32_e32 v200, v202
	v_permlane16_swap_b32_e32 v201, v203
	v_lshlrev_b32_e32 v216, 16, v200
	v_and_b32_e32 v200, 0xffff0000, v200
	v_lshlrev_b32_e32 v217, 16, v201
	v_and_b32_e32 v201, 0xffff0000, v201
	v_fmac_f32_e32 v102, s40, v216
	v_fmac_f32_e32 v103, s40, v200
	v_fmac_f32_e32 v104, s40, v217
	v_fmac_f32_e32 v105, s40, v201
	global_store_dwordx4 v[140:141], v[102:105], off offset:0
	v_lshlrev_b32_e32 v216, 16, v202
	v_and_b32_e32 v202, 0xffff0000, v202
	v_lshlrev_b32_e32 v217, 16, v203
	v_and_b32_e32 v203, 0xffff0000, v203
	v_fmac_f32_e32 v70, s40, v216
	v_fmac_f32_e32 v71, s40, v202
	v_fmac_f32_e32 v72, s40, v217
	v_fmac_f32_e32 v73, s40, v203
	global_store_dwordx4 v[140:141], v[70:73], off offset:64
	s_waitcnt vmcnt(28)
	v_permlane16_swap_b32_e32 v204, v206
	v_permlane16_swap_b32_e32 v205, v207
	v_lshlrev_b32_e32 v216, 16, v204
	v_and_b32_e32 v204, 0xffff0000, v204
	v_lshlrev_b32_e32 v217, 16, v205
	v_and_b32_e32 v205, 0xffff0000, v205
	v_fmac_f32_e32 v38, s40, v216
	v_fmac_f32_e32 v39, s40, v204
	v_fmac_f32_e32 v40, s40, v217
	v_fmac_f32_e32 v41, s40, v205
	global_store_dwordx4 v[140:141], v[38:41], off offset:128
	v_lshlrev_b32_e32 v216, 16, v206
	v_and_b32_e32 v206, 0xffff0000, v206
	v_lshlrev_b32_e32 v217, 16, v207
	v_and_b32_e32 v207, 0xffff0000, v207
	v_fmac_f32_e32 v6, s40, v216
	v_fmac_f32_e32 v7, s40, v206
	v_fmac_f32_e32 v8, s40, v217
	v_fmac_f32_e32 v9, s40, v207
	global_store_dwordx4 v[140:141], v[6:9], off offset:192
	v_lshl_add_u64 v[140:141], v[140:141], 0, s[8:9]
	s_waitcnt vmcnt(29)
	v_permlane16_swap_b32_e32 v208, v210
	v_permlane16_swap_b32_e32 v209, v211
	v_lshlrev_b32_e32 v216, 16, v208
	v_and_b32_e32 v208, 0xffff0000, v208
	v_lshlrev_b32_e32 v217, 16, v209
	v_and_b32_e32 v209, 0xffff0000, v209
	v_fmac_f32_e32 v98, s40, v216
	v_fmac_f32_e32 v99, s40, v208
	v_fmac_f32_e32 v100, s40, v217
	v_fmac_f32_e32 v101, s40, v209
	global_store_dwordx4 v[140:141], v[98:101], off offset:0
	v_lshlrev_b32_e32 v216, 16, v210
	v_and_b32_e32 v210, 0xffff0000, v210
	v_lshlrev_b32_e32 v217, 16, v211
	v_and_b32_e32 v211, 0xffff0000, v211
	v_fmac_f32_e32 v66, s40, v216
	v_fmac_f32_e32 v67, s40, v210
	v_fmac_f32_e32 v68, s40, v217
	v_fmac_f32_e32 v69, s40, v211
	global_store_dwordx4 v[140:141], v[66:69], off offset:64
	s_waitcnt vmcnt(30)
	v_permlane16_swap_b32_e32 v212, v214
	v_permlane16_swap_b32_e32 v213, v215
	v_lshlrev_b32_e32 v216, 16, v212
	v_and_b32_e32 v212, 0xffff0000, v212
	v_lshlrev_b32_e32 v217, 16, v213
	v_and_b32_e32 v213, 0xffff0000, v213
	v_fmac_f32_e32 v34, s40, v216
	v_fmac_f32_e32 v35, s40, v212
	v_fmac_f32_e32 v36, s40, v217
	v_fmac_f32_e32 v37, s40, v213
	global_store_dwordx4 v[140:141], v[34:37], off offset:128
	v_lshlrev_b32_e32 v216, 16, v214
	v_and_b32_e32 v214, 0xffff0000, v214
	v_lshlrev_b32_e32 v217, 16, v215
	v_and_b32_e32 v215, 0xffff0000, v215
	v_fmac_f32_e32 v2, s40, v216
	v_fmac_f32_e32 v3, s40, v214
	v_fmac_f32_e32 v4, s40, v217
	v_fmac_f32_e32 v5, s40, v215
	global_store_dwordx4 v[140:141], v[2:5], off offset:192
	s_branch .LBB0_146
.LBB0_208:
	s_and_b64 vcc, exec, s[2:3]
	s_cbranch_vccz .LBB0_146
	s_lshr_b32 s45, s38, 6
	s_and_b32 s46, s38, 63
	s_lshr_b32 s42, s46, 3
	s_and_b32 s46, s46, 7
	s_lshl_b32 s45, s45, 3
	s_add_i32 s45, s45, s46
	v_readlane_b32 s2, v250, 5
	v_readlane_b32 s3, v250, 6
	v_readlane_b32 s46, v254, 62
	s_mul_i32 s40, s45, 0x20000
	s_add_u32 s4, s2, s40
	s_addc_u32 s5, s3, 0
	s_add_u32 s4, s4, 0xe700000
	s_addc_u32 s5, s5, 0
	s_mul_i32 s40, s46, 0x80000
	s_mul_i32 s41, s42, 0x10000
	s_add_i32 s40, s40, s41
	s_add_u32 s10, s2, s40
	s_addc_u32 s11, s3, 0
	s_add_u32 s10, s10, 0x16c00000
	s_addc_u32 s11, s11, 0
	s_movk_i32 s39, 0x78
	v_lshrrev_b32_e32 v0, 2, v145
	v_and_b32_e32 v131, 3, v145
	v_bfe_u32 v136, v145, 4, 2
	v_lshlrev_b32_e32 v136, 1, v136
	v_lshrrev_b32_e64 v136, v136, s39
	v_and_b32_e32 v136, 3, v136
	v_xor_b32_e32 v131, v131, v136
	v_lshlrev_b32_e32 v131, 4, v131
	s_movk_i32 s41, 0x200
	v_mad_u32_u24 v0, v0, s41, v131
	v_bfe_u32 v137, v145, 2, 1
	s_movk_i32 s41, 0x1c0
	v_mul_u32_u24_e32 v136, s41, v137
	v_sub_u32_e32 v136, v0, v136
	v_mov_b32_e32 v137, 0
	v_lshl_add_u64 v[134:135], s[10:11], 0, v[136:137]
	v_bfe_u32 v137, v145, 2, 1
	s_mov_b32 s12, 64
	s_mov_b32 s13, 0
	v_lshl_add_u64 v[132:133], s[4:5], 0, v[0:1]
	v_bfe_u32 v136, v145, 2, 2
	v_lshlrev_b32_e32 v136, 1, v136
	v_lshrrev_b32_e64 v136, v136, s39
	v_and_b32_e32 v136, 3, v136
	v_bfe_u32 v137, v145, 4, 2
	v_xor_b32_e32 v136, v136, v137
	v_lshlrev_b32_e32 v136, 4, v136
	v_and_b32_e32 v131, 15, v145
	v_lshl_or_b32 v136, v131, 6, v136
	v_bfe_u32 v137, v145, 6, 1
	v_lshl_or_b32 v137, v137, 12, v136
	v_lshrrev_b32_e32 v0, 7, v145
	v_lshl_or_b32 v136, v0, 13, v136
	v_and_b32_e32 v140, 1, v131
	v_lshl_or_b32 v131, v0, 7, v131
	v_bfe_u32 v0, v145, 4, 2
	v_lshlrev_b32_e32 v0, 3, v0
	v_bfe_u32 v141, v145, 6, 1
	s_lshl_b32 s40, s45, 19
	s_lshl_b32 s41, s42, 8
	s_add_i32 s40, s40, s41
	s_add_u32 s4, s2, s40
	s_addc_u32 s5, s3, 0
	s_add_u32 s4, s4, 0x4200000
	s_addc_u32 s5, s5, 0
	v_lshlrev_b32_e32 v138, 11, v131
	v_lshl_add_u32 v138, v141, 7, v138
	v_bfe_u32 v139, v145, 4, 1
	v_lshl_add_u32 v138, v139, 5, v138
	v_bfe_u32 v139, v145, 5, 1
	v_lshl_add_u32 v138, v139, 4, v138
	v_mov_b32_e32 v139, 0
	v_lshl_add_u64 v[138:139], s[4:5], 0, v[138:139]
	s_lshl_b32 s40, s45, 20
	s_lshl_b32 s41, s42, 9
	s_add_i32 s40, s40, s41
	s_add_u32 s10, s2, s40
	s_addc_u32 s11, s3, 0
	v_lshlrev_b32_e32 v140, 12, v131
	v_lshl_add_u32 v140, v141, 8, v140
	v_lshl_add_u32 v140, v0, 1, v140
	v_mov_b32_e32 v141, 0
	v_lshl_add_u64 v[140:141], s[10:11], 0, v[140:141]
	s_mov_b32 s2, 0x8000
	s_mov_b32 s3, 0
	v_lshrrev_b32_e32 v0, 6, v145
; #define LAS __attribute__((address_space(3)))
;     ...
;   f32x4 acc[4][8];
; #pragma unroll
;   for (int i = 0; i < 4; i++)
; #pragma unroll
;     for (int j = 0; j < 8; j++) acc[i][j] = (f32x4){0.f, 0.f, 0.f, 0.f};
;   const int nk = (nk_part < 0) ? (K >> 5) : nk_part;
;   const int lrow = tid >> 2, lpc = tid & 3;
;   const int lch = lpc ^ ((0x78 >> (((lrow >> 2) & 3) * 2)) & 3);
;   const u16* ga = A + (size_t)(m0 + lrow) * lda + kbeg + lch * 8;
;   const u16* gb = Bt + (size_t)(n0 + lrow) * K + kbeg + lch * 8;
;   const size_t ga1 = (size_t)64 * lda, gb1 = (size_t)64 * K;
;   const unsigned lds0 = (unsigned)(uintptr_t)(LAS char*)smem + (unsigned)__builtin_amdgcn_readfirstlane(wid) * 1024u;
;     ...
;   __syncthreads();
;   G2_STAGE(0); G2_STAGE(1);
;   const int fsw = (0x78 >> (((r16 >> 2) & 3) * 2)) & 3;
;   const int aoff = (wm * 128 + r16) * 64 + ((quad ^ fsw) << 4);
;   const int boff = 16384 + (wn * 64 + r16) * 64 + ((quad ^ fsw) << 4);
;     ...
;     for (int f = 0; f < 8; f++) xa[f] = *(const bf16x8*)(cS + aoff + f * 1024);
; #pragma unroll
;     for (int f = 0; f < 4; f++) wb[f] = *(const bf16x8*)(cS + boff + f * 1024);
	v_lshlrev_b32_e32 v0, 10, v0
	s_nop 0
	v_readfirstlane_b32 s46, v0
	s_mov_b32 s43, m0
	s_mov_b32 s4, 128
	s_mov_b32 s5, 0
	v_mov_b32_e32 v2, 0
	v_mov_b32_e32 v3, 0
	v_mov_b32_e32 v4, 0
	v_mov_b32_e32 v5, 0
	v_mov_b32_e32 v6, 0
	v_mov_b32_e32 v7, 0
	v_mov_b32_e32 v8, 0
	v_mov_b32_e32 v9, 0
	v_mov_b32_e32 v10, 0
	v_mov_b32_e32 v11, 0
	v_mov_b32_e32 v12, 0
	v_mov_b32_e32 v13, 0
	v_mov_b32_e32 v14, 0
	v_mov_b32_e32 v15, 0
	v_mov_b32_e32 v16, 0
	v_mov_b32_e32 v17, 0
	v_mov_b32_e32 v18, 0
	v_mov_b32_e32 v19, 0
	v_mov_b32_e32 v20, 0
	v_mov_b32_e32 v21, 0
	v_mov_b32_e32 v22, 0
	v_mov_b32_e32 v23, 0
	v_mov_b32_e32 v24, 0
	v_mov_b32_e32 v25, 0
	v_mov_b32_e32 v26, 0
	v_mov_b32_e32 v27, 0
	v_mov_b32_e32 v28, 0
	v_mov_b32_e32 v29, 0
	v_mov_b32_e32 v30, 0
	v_mov_b32_e32 v31, 0
	v_mov_b32_e32 v32, 0
	v_mov_b32_e32 v33, 0
	v_mov_b32_e32 v34, 0
	v_mov_b32_e32 v35, 0
	v_mov_b32_e32 v36, 0
	v_mov_b32_e32 v37, 0
	v_mov_b32_e32 v38, 0
	v_mov_b32_e32 v39, 0
	v_mov_b32_e32 v40, 0
	v_mov_b32_e32 v41, 0
	v_mov_b32_e32 v42, 0
	v_mov_b32_e32 v43, 0
	v_mov_b32_e32 v44, 0
	v_mov_b32_e32 v45, 0
	v_mov_b32_e32 v46, 0
	v_mov_b32_e32 v47, 0
	v_mov_b32_e32 v48, 0
	v_mov_b32_e32 v49, 0
	v_mov_b32_e32 v50, 0
	v_mov_b32_e32 v51, 0
	v_mov_b32_e32 v52, 0
	v_mov_b32_e32 v53, 0
	v_mov_b32_e32 v54, 0
	v_mov_b32_e32 v55, 0
	v_mov_b32_e32 v56, 0
	v_mov_b32_e32 v57, 0
	v_mov_b32_e32 v58, 0
	v_mov_b32_e32 v59, 0
	v_mov_b32_e32 v60, 0
	v_mov_b32_e32 v61, 0
	v_mov_b32_e32 v62, 0
	v_mov_b32_e32 v63, 0
	v_mov_b32_e32 v64, 0
	v_mov_b32_e32 v65, 0
	v_mov_b32_e32 v66, 0
	v_mov_b32_e32 v67, 0
	v_mov_b32_e32 v68, 0
	v_mov_b32_e32 v69, 0
	v_mov_b32_e32 v70, 0
	v_mov_b32_e32 v71, 0
	v_mov_b32_e32 v72, 0
	v_mov_b32_e32 v73, 0
	v_mov_b32_e32 v74, 0
	v_mov_b32_e32 v75, 0
	v_mov_b32_e32 v76, 0
	v_mov_b32_e32 v77, 0
	v_mov_b32_e32 v78, 0
	v_mov_b32_e32 v79, 0
	v_mov_b32_e32 v80, 0
	v_mov_b32_e32 v81, 0
	v_mov_b32_e32 v82, 0
	v_mov_b32_e32 v83, 0
	v_mov_b32_e32 v84, 0
	v_mov_b32_e32 v85, 0
	v_mov_b32_e32 v86, 0
	v_mov_b32_e32 v87, 0
	v_mov_b32_e32 v88, 0
	v_mov_b32_e32 v89, 0
	v_mov_b32_e32 v90, 0
	v_mov_b32_e32 v91, 0
	v_mov_b32_e32 v92, 0
	v_mov_b32_e32 v93, 0
	v_mov_b32_e32 v94, 0
	v_mov_b32_e32 v95, 0
	v_mov_b32_e32 v96, 0
	v_mov_b32_e32 v97, 0
	v_mov_b32_e32 v98, 0
	v_mov_b32_e32 v99, 0
	v_mov_b32_e32 v100, 0
	v_mov_b32_e32 v101, 0
	v_mov_b32_e32 v102, 0
	v_mov_b32_e32 v103, 0
	v_mov_b32_e32 v104, 0
	v_mov_b32_e32 v105, 0
	v_mov_b32_e32 v106, 0
	v_mov_b32_e32 v107, 0
	v_mov_b32_e32 v108, 0
	v_mov_b32_e32 v109, 0
	v_mov_b32_e32 v110, 0
	v_mov_b32_e32 v111, 0
	v_mov_b32_e32 v112, 0
	v_mov_b32_e32 v113, 0
	v_mov_b32_e32 v114, 0
	v_mov_b32_e32 v115, 0
	v_mov_b32_e32 v116, 0
	v_mov_b32_e32 v117, 0
	v_mov_b32_e32 v118, 0
	v_mov_b32_e32 v119, 0
	v_mov_b32_e32 v120, 0
	v_mov_b32_e32 v121, 0
	v_mov_b32_e32 v122, 0
	v_mov_b32_e32 v123, 0
	v_mov_b32_e32 v124, 0
	v_mov_b32_e32 v125, 0
	v_mov_b32_e32 v126, 0
	v_mov_b32_e32 v127, 0
	v_mov_b32_e32 v128, 0
	v_mov_b32_e32 v129, 0
	s_barrier
	s_add_i32 s42, s46, 0x0
	s_mov_b32 m0, s42
	v_lshl_add_u64 v[142:143], v[132:133], 0, s[2:3]
	global_load_lds_dwordx4 v[132:133], off
	s_addk_i32 m0, 0x1000
	s_nop 0
	global_load_lds_dwordx4 v[142:143], off
	v_lshl_add_u64 v[142:143], v[142:143], 0, s[2:3]
	s_addk_i32 m0, 0x1000
	s_nop 0
	global_load_lds_dwordx4 v[142:143], off
	v_lshl_add_u64 v[142:143], v[142:143], 0, s[2:3]
	s_addk_i32 m0, 0x1000
	s_nop 0
	global_load_lds_dwordx4 v[142:143], off
	s_addk_i32 m0, 0x1000
	v_lshl_add_u64 v[142:143], v[134:135], 0, s[2:3]
	s_nop 0
	global_load_lds_dwordx4 v[134:135], off
	s_addk_i32 m0, 0x1000
	v_lshl_add_u64 v[132:133], v[132:133], 0, s[12:13]
	s_nop 0
	global_load_lds_dwordx4 v[142:143], off
	v_lshl_add_u64 v[134:135], v[134:135], 0, s[4:5]
	s_nop 0
	s_add_i32 s42, s46, 0x6000
	s_mov_b32 m0, s42
	v_lshl_add_u64 v[142:143], v[132:133], 0, s[2:3]
	global_load_lds_dwordx4 v[132:133], off
	s_addk_i32 m0, 0x1000
	s_nop 0
	global_load_lds_dwordx4 v[142:143], off
	v_lshl_add_u64 v[142:143], v[142:143], 0, s[2:3]
	s_addk_i32 m0, 0x1000
	s_nop 0
	global_load_lds_dwordx4 v[142:143], off
	v_lshl_add_u64 v[142:143], v[142:143], 0, s[2:3]
	s_addk_i32 m0, 0x1000
	s_nop 0
	global_load_lds_dwordx4 v[142:143], off
	s_addk_i32 m0, 0x1000
	v_lshl_add_u64 v[142:143], v[134:135], 0, s[2:3]
	s_nop 0
	global_load_lds_dwordx4 v[134:135], off
	s_addk_i32 m0, 0x1000
	v_lshl_add_u64 v[132:133], v[132:133], 0, s[12:13]
	s_nop 0
	global_load_lds_dwordx4 v[142:143], off
	v_lshl_add_u64 v[134:135], v[134:135], 0, s[4:5]
	s_nop 0
	s_add_i32 s42, s46, 0xc000
	s_mov_b32 m0, s42
	v_lshl_add_u64 v[142:143], v[132:133], 0, s[2:3]
	global_load_lds_dwordx4 v[132:133], off
	s_addk_i32 m0, 0x1000
	s_nop 0
	global_load_lds_dwordx4 v[142:143], off
	v_lshl_add_u64 v[142:143], v[142:143], 0, s[2:3]
	s_addk_i32 m0, 0x1000
	s_nop 0
	global_load_lds_dwordx4 v[142:143], off
	v_lshl_add_u64 v[142:143], v[142:143], 0, s[2:3]
	s_addk_i32 m0, 0x1000
	s_nop 0
	global_load_lds_dwordx4 v[142:143], off
	s_addk_i32 m0, 0x1000
	v_lshl_add_u64 v[142:143], v[134:135], 0, s[2:3]
	s_nop 0
	global_load_lds_dwordx4 v[134:135], off
	s_addk_i32 m0, 0x1000
	v_lshl_add_u64 v[132:133], v[132:133], 0, s[12:13]
	s_nop 0
	global_load_lds_dwordx4 v[142:143], off
	v_lshl_add_u64 v[134:135], v[134:135], 0, s[4:5]
	s_nop 0
	s_waitcnt vmcnt(12)
	s_barrier
	ds_read_b128 v[146:149], v136 offset:0
	ds_read_b128 v[152:155], v136 offset:1024
	ds_read_b128 v[156:159], v136 offset:2048
	ds_read_b128 v[162:165], v136 offset:3072
	ds_read_b128 v[166:169], v136 offset:4096
	ds_read_b128 v[170:173], v136 offset:5120
	ds_read_b128 v[176:179], v136 offset:6144
	ds_read_b128 v[180:183], v136 offset:7168
	ds_read_b128 v[184:187], v137 offset:16384
	ds_read_b128 v[188:191], v137 offset:17408
	ds_read_b128 v[192:195], v137 offset:18432
	ds_read_b128 v[196:199], v137 offset:19456
	s_movk_i32 s40, 0x6000
	s_mov_b32 s41, 0
	s_movk_i32 s39, 2
;     ...
;   for (int kt = 0; kt < nk; kt++) {
;     if (kt + 1 < nk) asm volatile("s_waitcnt vmcnt(6)" ::: "memory");
;     else asm volatile("s_waitcnt vmcnt(0)" ::: "memory");
;     __builtin_amdgcn_s_barrier();
;     asm volatile("" ::: "memory");
;     if (kt + 2 < nk) G2_STAGE(kt + 2);
;     const char* cS = smem + (kt % 3) * 24576;
;     bf16x8 xa[8], wb[4];
; #pragma unroll
;     for (int f = 0; f < 8; f++) xa[f] = *(const bf16x8*)(cS + aoff + f * 1024);
; #pragma unroll
;     for (int f = 0; f < 4; f++) wb[f] = *(const bf16x8*)(cS + boff + f * 1024);
; #pragma unroll
;     for (int nf = 0; nf < 4; nf++)
; #pragma unroll
;       for (int mf = 0; mf < 8; mf++)
;         acc[nf][mf] = __builtin_amdgcn_mfma_f32_16x16x32_bf16(wb[nf], xa[mf], acc[nf][mf], 0, 0, 0);
.Lt8_loop:
	s_waitcnt vmcnt(6) lgkmcnt(0)
	s_barrier
	v_add_u32_e32 v144, s40, v136
	v_mfma_f32_16x16x32_bf16 v[126:129], v[184:187], v[146:149], v[126:129]
	ds_read_b128 v[200:203], v144 offset:0
	v_mfma_f32_16x16x32_bf16 v[122:125], v[184:187], v[152:155], v[122:125]
	ds_read_b128 v[204:207], v144 offset:1024
	v_mfma_f32_16x16x32_bf16 v[118:121], v[184:187], v[156:159], v[118:121]
	ds_read_b128 v[208:211], v144 offset:2048
	v_mfma_f32_16x16x32_bf16 v[114:117], v[184:187], v[162:165], v[114:117]
	ds_read_b128 v[212:215], v144 offset:3072
	v_mfma_f32_16x16x32_bf16 v[110:113], v[184:187], v[166:169], v[110:113]
	ds_read_b128 v[216:219], v144 offset:4096
	v_mfma_f32_16x16x32_bf16 v[106:109], v[184:187], v[170:173], v[106:109]
	ds_read_b128 v[220:223], v144 offset:5120
	v_mfma_f32_16x16x32_bf16 v[102:105], v[184:187], v[176:179], v[102:105]
	ds_read_b128 v[224:227], v144 offset:6144
	v_mfma_f32_16x16x32_bf16 v[98:101], v[184:187], v[180:183], v[98:101]
	ds_read_b128 v[228:231], v144 offset:7168
	v_mfma_f32_16x16x32_bf16 v[94:97], v[188:191], v[146:149], v[94:97]
	v_add_u32_e32 v144, s40, v137
	v_mfma_f32_16x16x32_bf16 v[90:93], v[188:191], v[152:155], v[90:93]
	v_mfma_f32_16x16x32_bf16 v[86:89], v[188:191], v[156:159], v[86:89]
	ds_read_b128 v[232:235], v144 offset:16384
	v_mfma_f32_16x16x32_bf16 v[82:85], v[188:191], v[162:165], v[82:85]
	ds_read_b128 v[236:239], v144 offset:17408
	v_mfma_f32_16x16x32_bf16 v[78:81], v[188:191], v[166:169], v[78:81]
	ds_read_b128 v[240:243], v144 offset:18432
	v_mfma_f32_16x16x32_bf16 v[74:77], v[188:191], v[170:173], v[74:77]
	ds_read_b128 v[244:247], v144 offset:19456
	s_add_i32 s42, s46, s41
	v_mfma_f32_16x16x32_bf16 v[70:73], v[188:191], v[176:179], v[70:73]
	s_mov_b32 m0, s42
	v_lshl_add_u64 v[142:143], v[132:133], 0, s[2:3]
	v_mfma_f32_16x16x32_bf16 v[66:69], v[188:191], v[180:183], v[66:69]
	global_load_lds_dwordx4 v[132:133], off
	s_addk_i32 m0, 0x1000
	v_mfma_f32_16x16x32_bf16 v[62:65], v[192:195], v[146:149], v[62:65]
	v_mfma_f32_16x16x32_bf16 v[58:61], v[192:195], v[152:155], v[58:61]
	v_mfma_f32_16x16x32_bf16 v[54:57], v[192:195], v[156:159], v[54:57]
	global_load_lds_dwordx4 v[142:143], off
	v_lshl_add_u64 v[142:143], v[142:143], 0, s[2:3]
	s_addk_i32 m0, 0x1000
	v_mfma_f32_16x16x32_bf16 v[50:53], v[192:195], v[162:165], v[50:53]
	v_mfma_f32_16x16x32_bf16 v[46:49], v[192:195], v[166:169], v[46:49]
	v_mfma_f32_16x16x32_bf16 v[42:45], v[192:195], v[170:173], v[42:45]
	global_load_lds_dwordx4 v[142:143], off
	v_lshl_add_u64 v[142:143], v[142:143], 0, s[2:3]
	s_addk_i32 m0, 0x1000
	v_mfma_f32_16x16x32_bf16 v[38:41], v[192:195], v[176:179], v[38:41]
	v_mfma_f32_16x16x32_bf16 v[34:37], v[192:195], v[180:183], v[34:37]
	v_mfma_f32_16x16x32_bf16 v[30:33], v[196:199], v[146:149], v[30:33]
	global_load_lds_dwordx4 v[142:143], off
	s_addk_i32 m0, 0x1000
	v_lshl_add_u64 v[142:143], v[134:135], 0, s[2:3]
	v_mfma_f32_16x16x32_bf16 v[26:29], v[196:199], v[152:155], v[26:29]
	v_mfma_f32_16x16x32_bf16 v[22:25], v[196:199], v[156:159], v[22:25]
	v_mfma_f32_16x16x32_bf16 v[18:21], v[196:199], v[162:165], v[18:21]
	global_load_lds_dwordx4 v[134:135], off
	s_addk_i32 m0, 0x1000
	v_lshl_add_u64 v[132:133], v[132:133], 0, s[12:13]
	v_mfma_f32_16x16x32_bf16 v[14:17], v[196:199], v[166:169], v[14:17]
	v_mfma_f32_16x16x32_bf16 v[10:13], v[196:199], v[170:173], v[10:13]
	v_mfma_f32_16x16x32_bf16 v[6:9], v[196:199], v[176:179], v[6:9]
	global_load_lds_dwordx4 v[142:143], off
	v_lshl_add_u64 v[134:135], v[134:135], 0, s[4:5]
	v_mfma_f32_16x16x32_bf16 v[2:5], v[196:199], v[180:183], v[2:5]
	s_mov_b32 s41, s40
	s_add_i32 s40, s40, 0x6000
	s_cmp_eq_u32 s40, 0x12000
	s_cselect_b32 s40, 0, s40
	s_waitcnt vmcnt(6) lgkmcnt(0)
	s_barrier
	v_add_u32_e32 v144, s40, v136
	v_mfma_f32_16x16x32_bf16 v[126:129], v[232:235], v[200:203], v[126:129]
	ds_read_b128 v[146:149], v144 offset:0
	v_mfma_f32_16x16x32_bf16 v[122:125], v[232:235], v[204:207], v[122:125]
	ds_read_b128 v[152:155], v144 offset:1024
	v_mfma_f32_16x16x32_bf16 v[118:121], v[232:235], v[208:211], v[118:121]
	ds_read_b128 v[156:159], v144 offset:2048
	v_mfma_f32_16x16x32_bf16 v[114:117], v[232:235], v[212:215], v[114:117]
	ds_read_b128 v[162:165], v144 offset:3072
	v_mfma_f32_16x16x32_bf16 v[110:113], v[232:235], v[216:219], v[110:113]
	ds_read_b128 v[166:169], v144 offset:4096
	v_mfma_f32_16x16x32_bf16 v[106:109], v[232:235], v[220:223], v[106:109]
	ds_read_b128 v[170:173], v144 offset:5120
	v_mfma_f32_16x16x32_bf16 v[102:105], v[232:235], v[224:227], v[102:105]
	ds_read_b128 v[176:179], v144 offset:6144
	v_mfma_f32_16x16x32_bf16 v[98:101], v[232:235], v[228:231], v[98:101]
	ds_read_b128 v[180:183], v144 offset:7168
	v_mfma_f32_16x16x32_bf16 v[94:97], v[236:239], v[200:203], v[94:97]
	v_add_u32_e32 v144, s40, v137
	v_mfma_f32_16x16x32_bf16 v[90:93], v[236:239], v[204:207], v[90:93]
	v_mfma_f32_16x16x32_bf16 v[86:89], v[236:239], v[208:211], v[86:89]
	ds_read_b128 v[184:187], v144 offset:16384
	v_mfma_f32_16x16x32_bf16 v[82:85], v[236:239], v[212:215], v[82:85]
	ds_read_b128 v[188:191], v144 offset:17408
	v_mfma_f32_16x16x32_bf16 v[78:81], v[236:239], v[216:219], v[78:81]
	ds_read_b128 v[192:195], v144 offset:18432
	v_mfma_f32_16x16x32_bf16 v[74:77], v[236:239], v[220:223], v[74:77]
	ds_read_b128 v[196:199], v144 offset:19456
	s_add_i32 s42, s46, s41
	v_mfma_f32_16x16x32_bf16 v[70:73], v[236:239], v[224:227], v[70:73]
	s_mov_b32 m0, s42
	v_lshl_add_u64 v[142:143], v[132:133], 0, s[2:3]
	v_mfma_f32_16x16x32_bf16 v[66:69], v[236:239], v[228:231], v[66:69]
	global_load_lds_dwordx4 v[132:133], off
	s_addk_i32 m0, 0x1000
	v_mfma_f32_16x16x32_bf16 v[62:65], v[240:243], v[200:203], v[62:65]
;     ...
;   for (int kt = 0; kt < nk; kt++) {
;     if (kt + 1 < nk) asm volatile("s_waitcnt vmcnt(6)" ::: "memory");
;     else asm volatile("s_waitcnt vmcnt(0)" ::: "memory");
;     __builtin_amdgcn_s_barrier();
;     asm volatile("" ::: "memory");
;     if (kt + 2 < nk) G2_STAGE(kt + 2);
;     const char* cS = smem + (kt % 3) * 24576;
;     bf16x8 xa[8], wb[4];
; #pragma unroll
;     for (int f = 0; f < 8; f++) xa[f] = *(const bf16x8*)(cS + aoff + f * 1024);
; #pragma unroll
;     for (int f = 0; f < 4; f++) wb[f] = *(const bf16x8*)(cS + boff + f * 1024);
; #pragma unroll
;     for (int nf = 0; nf < 4; nf++)
; #pragma unroll
;       for (int mf = 0; mf < 8; mf++)
;         acc[nf][mf] = __builtin_amdgcn_mfma_f32_16x16x32_bf16(wb[nf], xa[mf], acc[nf][mf], 0, 0, 0);
	v_mfma_f32_16x16x32_bf16 v[58:61], v[240:243], v[204:207], v[58:61]
	v_mfma_f32_16x16x32_bf16 v[54:57], v[240:243], v[208:211], v[54:57]
	global_load_lds_dwordx4 v[142:143], off
	v_lshl_add_u64 v[142:143], v[142:143], 0, s[2:3]
	s_addk_i32 m0, 0x1000
	v_mfma_f32_16x16x32_bf16 v[50:53], v[240:243], v[212:215], v[50:53]
	v_mfma_f32_16x16x32_bf16 v[46:49], v[240:243], v[216:219], v[46:49]
	v_mfma_f32_16x16x32_bf16 v[42:45], v[240:243], v[220:223], v[42:45]
	global_load_lds_dwordx4 v[142:143], off
	v_lshl_add_u64 v[142:143], v[142:143], 0, s[2:3]
	s_addk_i32 m0, 0x1000
	v_mfma_f32_16x16x32_bf16 v[38:41], v[240:243], v[224:227], v[38:41]
	v_mfma_f32_16x16x32_bf16 v[34:37], v[240:243], v[228:231], v[34:37]
	v_mfma_f32_16x16x32_bf16 v[30:33], v[244:247], v[200:203], v[30:33]
	global_load_lds_dwordx4 v[142:143], off
	s_addk_i32 m0, 0x1000
	v_lshl_add_u64 v[142:143], v[134:135], 0, s[2:3]
	v_mfma_f32_16x16x32_bf16 v[26:29], v[244:247], v[204:207], v[26:29]
	v_mfma_f32_16x16x32_bf16 v[22:25], v[244:247], v[208:211], v[22:25]
	v_mfma_f32_16x16x32_bf16 v[18:21], v[244:247], v[212:215], v[18:21]
	global_load_lds_dwordx4 v[134:135], off
	s_addk_i32 m0, 0x1000
	v_lshl_add_u64 v[132:133], v[132:133], 0, s[12:13]
	v_mfma_f32_16x16x32_bf16 v[14:17], v[244:247], v[216:219], v[14:17]
	v_mfma_f32_16x16x32_bf16 v[10:13], v[244:247], v[220:223], v[10:13]
	v_mfma_f32_16x16x32_bf16 v[6:9], v[244:247], v[224:227], v[6:9]
	global_load_lds_dwordx4 v[142:143], off
	v_lshl_add_u64 v[134:135], v[134:135], 0, s[4:5]
	v_mfma_f32_16x16x32_bf16 v[2:5], v[244:247], v[228:231], v[2:5]
	s_mov_b32 s41, s40
	s_add_i32 s40, s40, 0x6000
	s_cmp_eq_u32 s40, 0x12000
	s_cselect_b32 s40, 0, s40
	s_sub_i32 s39, s39, 1
	s_cmp_lg_u32 s39, 0
	s_cbranch_scc1 .Lt8_loop
	s_waitcnt vmcnt(6) lgkmcnt(0)
	s_barrier
	v_add_u32_e32 v144, s40, v136
	v_mfma_f32_16x16x32_bf16 v[126:129], v[184:187], v[146:149], v[126:129]
	ds_read_b128 v[200:203], v144 offset:0
	v_mfma_f32_16x16x32_bf16 v[122:125], v[184:187], v[152:155], v[122:125]
	ds_read_b128 v[204:207], v144 offset:1024
	v_mfma_f32_16x16x32_bf16 v[118:121], v[184:187], v[156:159], v[118:121]
	ds_read_b128 v[208:211], v144 offset:2048
	v_mfma_f32_16x16x32_bf16 v[114:117], v[184:187], v[162:165], v[114:117]
	ds_read_b128 v[212:215], v144 offset:3072
	v_mfma_f32_16x16x32_bf16 v[110:113], v[184:187], v[166:169], v[110:113]
	ds_read_b128 v[216:219], v144 offset:4096
	v_mfma_f32_16x16x32_bf16 v[106:109], v[184:187], v[170:173], v[106:109]
	ds_read_b128 v[220:223], v144 offset:5120
	v_mfma_f32_16x16x32_bf16 v[102:105], v[184:187], v[176:179], v[102:105]
	ds_read_b128 v[224:227], v144 offset:6144
	v_mfma_f32_16x16x32_bf16 v[98:101], v[184:187], v[180:183], v[98:101]
	ds_read_b128 v[228:231], v144 offset:7168
	v_mfma_f32_16x16x32_bf16 v[94:97], v[188:191], v[146:149], v[94:97]
	v_add_u32_e32 v144, s40, v137
	v_mfma_f32_16x16x32_bf16 v[90:93], v[188:191], v[152:155], v[90:93]
	v_mfma_f32_16x16x32_bf16 v[86:89], v[188:191], v[156:159], v[86:89]
	ds_read_b128 v[232:235], v144 offset:16384
	v_mfma_f32_16x16x32_bf16 v[82:85], v[188:191], v[162:165], v[82:85]
	ds_read_b128 v[236:239], v144 offset:17408
	v_mfma_f32_16x16x32_bf16 v[78:81], v[188:191], v[166:169], v[78:81]
	ds_read_b128 v[240:243], v144 offset:18432
	v_mfma_f32_16x16x32_bf16 v[74:77], v[188:191], v[170:173], v[74:77]
	ds_read_b128 v[244:247], v144 offset:19456
	s_add_i32 s42, s46, s41
	v_mfma_f32_16x16x32_bf16 v[70:73], v[188:191], v[176:179], v[70:73]
	s_mov_b32 m0, s42
	v_lshl_add_u64 v[142:143], v[132:133], 0, s[2:3]
	v_mfma_f32_16x16x32_bf16 v[66:69], v[188:191], v[180:183], v[66:69]
	global_load_lds_dwordx4 v[132:133], off
	s_addk_i32 m0, 0x1000
	v_mfma_f32_16x16x32_bf16 v[62:65], v[192:195], v[146:149], v[62:65]
	v_mfma_f32_16x16x32_bf16 v[58:61], v[192:195], v[152:155], v[58:61]
	v_mfma_f32_16x16x32_bf16 v[54:57], v[192:195], v[156:159], v[54:57]
	global_load_lds_dwordx4 v[142:143], off
	v_lshl_add_u64 v[142:143], v[142:143], 0, s[2:3]
	s_addk_i32 m0, 0x1000
	v_mfma_f32_16x16x32_bf16 v[50:53], v[192:195], v[162:165], v[50:53]
	v_mfma_f32_16x16x32_bf16 v[46:49], v[192:195], v[166:169], v[46:49]
	v_mfma_f32_16x16x32_bf16 v[42:45], v[192:195], v[170:173], v[42:45]
	global_load_lds_dwordx4 v[142:143], off
	v_lshl_add_u64 v[142:143], v[142:143], 0, s[2:3]
	s_addk_i32 m0, 0x1000
	v_mfma_f32_16x16x32_bf16 v[38:41], v[192:195], v[176:179], v[38:41]
	v_mfma_f32_16x16x32_bf16 v[34:37], v[192:195], v[180:183], v[34:37]
	v_mfma_f32_16x16x32_bf16 v[30:33], v[196:199], v[146:149], v[30:33]
	global_load_lds_dwordx4 v[142:143], off
	s_addk_i32 m0, 0x1000
	v_lshl_add_u64 v[142:143], v[134:135], 0, s[2:3]
	v_mfma_f32_16x16x32_bf16 v[26:29], v[196:199], v[152:155], v[26:29]
	v_mfma_f32_16x16x32_bf16 v[22:25], v[196:199], v[156:159], v[22:25]
	v_mfma_f32_16x16x32_bf16 v[18:21], v[196:199], v[162:165], v[18:21]
	global_load_lds_dwordx4 v[134:135], off
	s_addk_i32 m0, 0x1000
	v_lshl_add_u64 v[132:133], v[132:133], 0, s[12:13]
	v_mfma_f32_16x16x32_bf16 v[14:17], v[196:199], v[166:169], v[14:17]
	v_mfma_f32_16x16x32_bf16 v[10:13], v[196:199], v[170:173], v[10:13]
	v_mfma_f32_16x16x32_bf16 v[6:9], v[196:199], v[176:179], v[6:9]
	global_load_lds_dwordx4 v[142:143], off
	v_lshl_add_u64 v[134:135], v[134:135], 0, s[4:5]
	v_mfma_f32_16x16x32_bf16 v[2:5], v[196:199], v[180:183], v[2:5]
	s_mov_b32 s41, s40
	s_add_i32 s40, s40, 0x6000
	s_cmp_eq_u32 s40, 0x12000
	s_cselect_b32 s40, 0, s40
	s_waitcnt vmcnt(6) lgkmcnt(0)
	s_barrier
;     ...
;   for (int kt = 0; kt < nk; kt++) {
;     if (kt + 1 < nk) asm volatile("s_waitcnt vmcnt(6)" ::: "memory");
;     else asm volatile("s_waitcnt vmcnt(0)" ::: "memory");
;     __builtin_amdgcn_s_barrier();
;     asm volatile("" ::: "memory");
;     if (kt + 2 < nk) G2_STAGE(kt + 2);
;     const char* cS = smem + (kt % 3) * 24576;
;     bf16x8 xa[8], wb[4];
; #pragma unroll
;     for (int f = 0; f < 8; f++) xa[f] = *(const bf16x8*)(cS + aoff + f * 1024);
; #pragma unroll
;     for (int f = 0; f < 4; f++) wb[f] = *(const bf16x8*)(cS + boff + f * 1024);
; #pragma unroll
;     for (int nf = 0; nf < 4; nf++)
; #pragma unroll
;       for (int mf = 0; mf < 8; mf++)
;         acc[nf][mf] = __builtin_amdgcn_mfma_f32_16x16x32_bf16(wb[nf], xa[mf], acc[nf][mf], 0, 0, 0);
	v_add_u32_e32 v144, s40, v136
	v_mfma_f32_16x16x32_bf16 v[126:129], v[232:235], v[200:203], v[126:129]
	ds_read_b128 v[146:149], v144 offset:0
	v_mfma_f32_16x16x32_bf16 v[122:125], v[232:235], v[204:207], v[122:125]
	ds_read_b128 v[152:155], v144 offset:1024
	v_mfma_f32_16x16x32_bf16 v[118:121], v[232:235], v[208:211], v[118:121]
	ds_read_b128 v[156:159], v144 offset:2048
	v_mfma_f32_16x16x32_bf16 v[114:117], v[232:235], v[212:215], v[114:117]
	ds_read_b128 v[162:165], v144 offset:3072
	v_mfma_f32_16x16x32_bf16 v[110:113], v[232:235], v[216:219], v[110:113]
	ds_read_b128 v[166:169], v144 offset:4096
	v_mfma_f32_16x16x32_bf16 v[106:109], v[232:235], v[220:223], v[106:109]
	ds_read_b128 v[170:173], v144 offset:5120
	v_mfma_f32_16x16x32_bf16 v[102:105], v[232:235], v[224:227], v[102:105]
	ds_read_b128 v[176:179], v144 offset:6144
	v_mfma_f32_16x16x32_bf16 v[98:101], v[232:235], v[228:231], v[98:101]
	ds_read_b128 v[180:183], v144 offset:7168
	v_mfma_f32_16x16x32_bf16 v[94:97], v[236:239], v[200:203], v[94:97]
	v_add_u32_e32 v144, s40, v137
	v_mfma_f32_16x16x32_bf16 v[90:93], v[236:239], v[204:207], v[90:93]
	v_mfma_f32_16x16x32_bf16 v[86:89], v[236:239], v[208:211], v[86:89]
	ds_read_b128 v[184:187], v144 offset:16384
	v_mfma_f32_16x16x32_bf16 v[82:85], v[236:239], v[212:215], v[82:85]
	ds_read_b128 v[188:191], v144 offset:17408
	v_mfma_f32_16x16x32_bf16 v[78:81], v[236:239], v[216:219], v[78:81]
	ds_read_b128 v[192:195], v144 offset:18432
	v_mfma_f32_16x16x32_bf16 v[74:77], v[236:239], v[220:223], v[74:77]
	ds_read_b128 v[196:199], v144 offset:19456
	v_mfma_f32_16x16x32_bf16 v[70:73], v[236:239], v[224:227], v[70:73]
	v_mfma_f32_16x16x32_bf16 v[66:69], v[236:239], v[228:231], v[66:69]
	v_mfma_f32_16x16x32_bf16 v[62:65], v[240:243], v[200:203], v[62:65]
	v_mfma_f32_16x16x32_bf16 v[58:61], v[240:243], v[204:207], v[58:61]
	v_mfma_f32_16x16x32_bf16 v[54:57], v[240:243], v[208:211], v[54:57]
	v_mfma_f32_16x16x32_bf16 v[50:53], v[240:243], v[212:215], v[50:53]
	v_mfma_f32_16x16x32_bf16 v[46:49], v[240:243], v[216:219], v[46:49]
	v_mfma_f32_16x16x32_bf16 v[42:45], v[240:243], v[220:223], v[42:45]
	v_mfma_f32_16x16x32_bf16 v[38:41], v[240:243], v[224:227], v[38:41]
	v_mfma_f32_16x16x32_bf16 v[34:37], v[240:243], v[228:231], v[34:37]
	v_mfma_f32_16x16x32_bf16 v[30:33], v[244:247], v[200:203], v[30:33]
	v_mfma_f32_16x16x32_bf16 v[26:29], v[244:247], v[204:207], v[26:29]
	v_mfma_f32_16x16x32_bf16 v[22:25], v[244:247], v[208:211], v[22:25]
	v_mfma_f32_16x16x32_bf16 v[18:21], v[244:247], v[212:215], v[18:21]
	v_mfma_f32_16x16x32_bf16 v[14:17], v[244:247], v[216:219], v[14:17]
	v_mfma_f32_16x16x32_bf16 v[10:13], v[244:247], v[220:223], v[10:13]
	v_mfma_f32_16x16x32_bf16 v[6:9], v[244:247], v[224:227], v[6:9]
	v_mfma_f32_16x16x32_bf16 v[2:5], v[244:247], v[228:231], v[2:5]
	s_mov_b32 s41, s40
	s_add_i32 s40, s40, 0x6000
	s_cmp_eq_u32 s40, 0x12000
	s_cselect_b32 s40, 0, s40
	s_waitcnt vmcnt(0) lgkmcnt(0)
	s_barrier
	v_add_u32_e32 v144, s40, v136
	v_mfma_f32_16x16x32_bf16 v[126:129], v[184:187], v[146:149], v[126:129]
	ds_read_b128 v[200:203], v144 offset:0
	v_mfma_f32_16x16x32_bf16 v[122:125], v[184:187], v[152:155], v[122:125]
	ds_read_b128 v[204:207], v144 offset:1024
	v_mfma_f32_16x16x32_bf16 v[118:121], v[184:187], v[156:159], v[118:121]
	ds_read_b128 v[208:211], v144 offset:2048
	v_mfma_f32_16x16x32_bf16 v[114:117], v[184:187], v[162:165], v[114:117]
	ds_read_b128 v[212:215], v144 offset:3072
	v_mfma_f32_16x16x32_bf16 v[110:113], v[184:187], v[166:169], v[110:113]
	ds_read_b128 v[216:219], v144 offset:4096
	v_mfma_f32_16x16x32_bf16 v[106:109], v[184:187], v[170:173], v[106:109]
	ds_read_b128 v[220:223], v144 offset:5120
	v_mfma_f32_16x16x32_bf16 v[102:105], v[184:187], v[176:179], v[102:105]
	ds_read_b128 v[224:227], v144 offset:6144
	v_mfma_f32_16x16x32_bf16 v[98:101], v[184:187], v[180:183], v[98:101]
	ds_read_b128 v[228:231], v144 offset:7168
	v_mfma_f32_16x16x32_bf16 v[94:97], v[188:191], v[146:149], v[94:97]
	v_add_u32_e32 v144, s40, v137
	v_mfma_f32_16x16x32_bf16 v[90:93], v[188:191], v[152:155], v[90:93]
	v_mfma_f32_16x16x32_bf16 v[86:89], v[188:191], v[156:159], v[86:89]
	ds_read_b128 v[232:235], v144 offset:16384
	v_mfma_f32_16x16x32_bf16 v[82:85], v[188:191], v[162:165], v[82:85]
	ds_read_b128 v[236:239], v144 offset:17408
	v_mfma_f32_16x16x32_bf16 v[78:81], v[188:191], v[166:169], v[78:81]
	ds_read_b128 v[240:243], v144 offset:18432
	v_mfma_f32_16x16x32_bf16 v[74:77], v[188:191], v[170:173], v[74:77]
	ds_read_b128 v[244:247], v144 offset:19456
	v_mfma_f32_16x16x32_bf16 v[70:73], v[188:191], v[176:179], v[70:73]
	v_mfma_f32_16x16x32_bf16 v[66:69], v[188:191], v[180:183], v[66:69]
	v_mfma_f32_16x16x32_bf16 v[62:65], v[192:195], v[146:149], v[62:65]
	v_mfma_f32_16x16x32_bf16 v[58:61], v[192:195], v[152:155], v[58:61]
	v_mfma_f32_16x16x32_bf16 v[54:57], v[192:195], v[156:159], v[54:57]
	v_mfma_f32_16x16x32_bf16 v[50:53], v[192:195], v[162:165], v[50:53]
	v_mfma_f32_16x16x32_bf16 v[46:49], v[192:195], v[166:169], v[46:49]
	v_mfma_f32_16x16x32_bf16 v[42:45], v[192:195], v[170:173], v[42:45]
	v_mfma_f32_16x16x32_bf16 v[38:41], v[192:195], v[176:179], v[38:41]
	v_mfma_f32_16x16x32_bf16 v[34:37], v[192:195], v[180:183], v[34:37]
	v_mfma_f32_16x16x32_bf16 v[30:33], v[196:199], v[146:149], v[30:33]
	v_mfma_f32_16x16x32_bf16 v[26:29], v[196:199], v[152:155], v[26:29]
	v_mfma_f32_16x16x32_bf16 v[22:25], v[196:199], v[156:159], v[22:25]
	v_mfma_f32_16x16x32_bf16 v[18:21], v[196:199], v[162:165], v[18:21]
	v_mfma_f32_16x16x32_bf16 v[14:17], v[196:199], v[166:169], v[14:17]
	v_mfma_f32_16x16x32_bf16 v[10:13], v[196:199], v[170:173], v[10:13]
	v_mfma_f32_16x16x32_bf16 v[6:9], v[196:199], v[176:179], v[6:9]
	v_mfma_f32_16x16x32_bf16 v[2:5], v[196:199], v[180:183], v[2:5]
	s_mov_b32 s41, s40
	s_add_i32 s40, s40, 0x6000
	s_cmp_eq_u32 s40, 0x12000
	s_cselect_b32 s40, 0, s40
	s_mov_b32 s4, 0x8000
	s_mov_b32 s5, 0
	s_mov_b32 s10, 0x10000
	s_mov_b32 s11, 0
	s_mov_b32 s44, 0x3fd744fd
	s_waitcnt lgkmcnt(0)
; DEVI float blo(unsigned u) { return __uint_as_float(u << 16); }
; DEVI float bhi(unsigned u) { return __uint_as_float(u & 0xffff0000u); }
;     ...
; #pragma unroll
;     for (int nf = 0; nf < 4; nf++)
; #pragma unroll
;       for (int mf = 0; mf < 8; mf++)
;         acc[nf][mf] = __builtin_amdgcn_mfma_f32_16x16x32_bf16(wb[nf], xa[mf], acc[nf][mf], 0, 0, 0);
;     ...
;         if (EPI == EPI_RESID || EPI == EPI_RESID_ATOMIC) {
;           f32x4 x = a;
;           if (EPI == EPI_RESID || kpart == 0) {
;             const u32x2 xr = *(const u32x2*)((const u16*)(p.ws + WS_XB) + (size_t)row * 1024 + col);
;             x[0] += ALPHA * blo(xr[0]); x[1] += ALPHA * bhi(xr[0]); x[2] += ALPHA * blo(xr[1]); x[3] += ALPHA * bhi(xr[1]);
;           }
;           if (EPI == EPI_RESID) *(f32x4*)((float*)(p.ws + WS_XF) + (size_t)row * 1024 + col) = x;
;           else *(f32x4*)((float*)(p.ws + WS_SLAB) + ((size_t)kpart * 512 + (row - T_P)) * 1024 + col) = x;
	v_mfma_f32_16x16x32_bf16 v[126:129], v[232:235], v[200:203], v[126:129]
	v_mfma_f32_16x16x32_bf16 v[122:125], v[232:235], v[204:207], v[122:125]
	v_mfma_f32_16x16x32_bf16 v[118:121], v[232:235], v[208:211], v[118:121]
	v_mfma_f32_16x16x32_bf16 v[114:117], v[232:235], v[212:215], v[114:117]
	v_mfma_f32_16x16x32_bf16 v[110:113], v[232:235], v[216:219], v[110:113]
	global_load_dwordx4 v[146:149], v[138:139], off offset:0
	v_mfma_f32_16x16x32_bf16 v[106:109], v[232:235], v[220:223], v[106:109]
	v_mfma_f32_16x16x32_bf16 v[102:105], v[232:235], v[224:227], v[102:105]
	global_load_dwordx4 v[152:155], v[138:139], off offset:64
	v_mfma_f32_16x16x32_bf16 v[98:101], v[232:235], v[228:231], v[98:101]
	v_lshl_add_u64 v[138:139], v[138:139], 0, s[4:5]
	v_mfma_f32_16x16x32_bf16 v[94:97], v[236:239], v[200:203], v[94:97]
	global_load_dwordx4 v[156:159], v[138:139], off offset:0
	v_mfma_f32_16x16x32_bf16 v[90:93], v[236:239], v[204:207], v[90:93]
	v_mfma_f32_16x16x32_bf16 v[86:89], v[236:239], v[208:211], v[86:89]
	global_load_dwordx4 v[162:165], v[138:139], off offset:64
	v_mfma_f32_16x16x32_bf16 v[82:85], v[236:239], v[212:215], v[82:85]
	v_lshl_add_u64 v[138:139], v[138:139], 0, s[4:5]
	v_mfma_f32_16x16x32_bf16 v[78:81], v[236:239], v[216:219], v[78:81]
	global_load_dwordx4 v[166:169], v[138:139], off offset:0
	v_mfma_f32_16x16x32_bf16 v[74:77], v[236:239], v[220:223], v[74:77]
	v_mfma_f32_16x16x32_bf16 v[70:73], v[236:239], v[224:227], v[70:73]
	global_load_dwordx4 v[170:173], v[138:139], off offset:64
	v_mfma_f32_16x16x32_bf16 v[66:69], v[236:239], v[228:231], v[66:69]
	v_lshl_add_u64 v[138:139], v[138:139], 0, s[4:5]
	v_mfma_f32_16x16x32_bf16 v[62:65], v[240:243], v[200:203], v[62:65]
	global_load_dwordx4 v[176:179], v[138:139], off offset:0
	v_mfma_f32_16x16x32_bf16 v[58:61], v[240:243], v[204:207], v[58:61]
	v_mfma_f32_16x16x32_bf16 v[54:57], v[240:243], v[208:211], v[54:57]
	global_load_dwordx4 v[180:183], v[138:139], off offset:64
	v_mfma_f32_16x16x32_bf16 v[50:53], v[240:243], v[212:215], v[50:53]
	v_lshl_add_u64 v[138:139], v[138:139], 0, s[4:5]
	v_mfma_f32_16x16x32_bf16 v[46:49], v[240:243], v[216:219], v[46:49]
	global_load_dwordx4 v[184:187], v[138:139], off offset:0
	v_mfma_f32_16x16x32_bf16 v[42:45], v[240:243], v[220:223], v[42:45]
	v_mfma_f32_16x16x32_bf16 v[38:41], v[240:243], v[224:227], v[38:41]
	global_load_dwordx4 v[188:191], v[138:139], off offset:64
	v_mfma_f32_16x16x32_bf16 v[34:37], v[240:243], v[228:231], v[34:37]
	v_lshl_add_u64 v[138:139], v[138:139], 0, s[4:5]
	v_mfma_f32_16x16x32_bf16 v[30:33], v[244:247], v[200:203], v[30:33]
	global_load_dwordx4 v[192:195], v[138:139], off offset:0
	v_mfma_f32_16x16x32_bf16 v[26:29], v[244:247], v[204:207], v[26:29]
	v_mfma_f32_16x16x32_bf16 v[22:25], v[244:247], v[208:211], v[22:25]
	global_load_dwordx4 v[196:199], v[138:139], off offset:64
	v_mfma_f32_16x16x32_bf16 v[18:21], v[244:247], v[212:215], v[18:21]
	v_lshl_add_u64 v[138:139], v[138:139], 0, s[4:5]
	v_mfma_f32_16x16x32_bf16 v[14:17], v[244:247], v[216:219], v[14:17]
	v_mfma_f32_16x16x32_bf16 v[10:13], v[244:247], v[220:223], v[10:13]
	v_mfma_f32_16x16x32_bf16 v[6:9], v[244:247], v[224:227], v[6:9]
	v_mfma_f32_16x16x32_bf16 v[2:5], v[244:247], v[228:231], v[2:5]
	s_mov_b32 m0, s43
	global_load_dwordx4 v[200:203], v[138:139], off offset:0
	global_load_dwordx4 v[204:207], v[138:139], off offset:64
	v_lshl_add_u64 v[138:139], v[138:139], 0, s[4:5]
	global_load_dwordx4 v[208:211], v[138:139], off offset:0
	global_load_dwordx4 v[212:215], v[138:139], off offset:64
	v_lshl_add_u64 v[138:139], v[138:139], 0, s[4:5]
	s_nop 7
	s_waitcnt vmcnt(15)
	v_permlane16_swap_b32_e32 v146, v148
	v_permlane16_swap_b32_e32 v147, v149
	v_lshlrev_b32_e32 v216, 16, v146
	v_and_b32_e32 v146, 0xffff0000, v146
	v_lshlrev_b32_e32 v217, 16, v147
	v_and_b32_e32 v147, 0xffff0000, v147
	v_fmac_f32_e32 v126, s44, v216
	v_fmac_f32_e32 v127, s44, v146
	v_fmac_f32_e32 v128, s44, v217
	v_fmac_f32_e32 v129, s44, v147
	global_store_dwordx4 v[140:141], v[126:129], off offset:0
	v_lshlrev_b32_e32 v216, 16, v148
	v_and_b32_e32 v148, 0xffff0000, v148
	v_lshlrev_b32_e32 v217, 16, v149
	v_and_b32_e32 v149, 0xffff0000, v149
	v_fmac_f32_e32 v94, s44, v216
	v_fmac_f32_e32 v95, s44, v148
	v_fmac_f32_e32 v96, s44, v217
	v_fmac_f32_e32 v97, s44, v149
	global_store_dwordx4 v[140:141], v[94:97], off offset:64
	s_waitcnt vmcnt(16)
	v_permlane16_swap_b32_e32 v152, v154
	v_permlane16_swap_b32_e32 v153, v155
	v_lshlrev_b32_e32 v216, 16, v152
	v_and_b32_e32 v152, 0xffff0000, v152
	v_lshlrev_b32_e32 v217, 16, v153
	v_and_b32_e32 v153, 0xffff0000, v153
	v_fmac_f32_e32 v62, s44, v216
	v_fmac_f32_e32 v63, s44, v152
	v_fmac_f32_e32 v64, s44, v217
	v_fmac_f32_e32 v65, s44, v153
	global_store_dwordx4 v[140:141], v[62:65], off offset:128
	v_lshlrev_b32_e32 v216, 16, v154
	v_and_b32_e32 v154, 0xffff0000, v154
	v_lshlrev_b32_e32 v217, 16, v155
	v_and_b32_e32 v155, 0xffff0000, v155
	v_fmac_f32_e32 v30, s44, v216
	v_fmac_f32_e32 v31, s44, v154
	v_fmac_f32_e32 v32, s44, v217
	v_fmac_f32_e32 v33, s44, v155
	global_store_dwordx4 v[140:141], v[30:33], off offset:192
	v_lshl_add_u64 v[140:141], v[140:141], 0, s[10:11]
	s_waitcnt vmcnt(17)
	v_permlane16_swap_b32_e32 v156, v158
	v_permlane16_swap_b32_e32 v157, v159
	v_lshlrev_b32_e32 v216, 16, v156
	v_and_b32_e32 v156, 0xffff0000, v156
	v_lshlrev_b32_e32 v217, 16, v157
	v_and_b32_e32 v157, 0xffff0000, v157
	v_fmac_f32_e32 v122, s44, v216
	v_fmac_f32_e32 v123, s44, v156
	v_fmac_f32_e32 v124, s44, v217
	v_fmac_f32_e32 v125, s44, v157
	global_store_dwordx4 v[140:141], v[122:125], off offset:0
	v_lshlrev_b32_e32 v216, 16, v158
	v_and_b32_e32 v158, 0xffff0000, v158
	v_lshlrev_b32_e32 v217, 16, v159
	v_and_b32_e32 v159, 0xffff0000, v159
	v_fmac_f32_e32 v90, s44, v216
	v_fmac_f32_e32 v91, s44, v158
	v_fmac_f32_e32 v92, s44, v217
	v_fmac_f32_e32 v93, s44, v159
	global_store_dwordx4 v[140:141], v[90:93], off offset:64
	s_waitcnt vmcnt(18)
; DEVI float blo(unsigned u) { return __uint_as_float(u << 16); }
; DEVI float bhi(unsigned u) { return __uint_as_float(u & 0xffff0000u); }
;     ...
;         if (EPI == EPI_RESID || EPI == EPI_RESID_ATOMIC) {
;           f32x4 x = a;
;           if (EPI == EPI_RESID || kpart == 0) {
;             const u32x2 xr = *(const u32x2*)((const u16*)(p.ws + WS_XB) + (size_t)row * 1024 + col);
;             x[0] += ALPHA * blo(xr[0]); x[1] += ALPHA * bhi(xr[0]); x[2] += ALPHA * blo(xr[1]); x[3] += ALPHA * bhi(xr[1]);
;           }
;           if (EPI == EPI_RESID) *(f32x4*)((float*)(p.ws + WS_XF) + (size_t)row * 1024 + col) = x;
;           else *(f32x4*)((float*)(p.ws + WS_SLAB) + ((size_t)kpart * 512 + (row - T_P)) * 1024 + col) = x;
	v_permlane16_swap_b32_e32 v162, v164
	v_permlane16_swap_b32_e32 v163, v165
	v_lshlrev_b32_e32 v216, 16, v162
	v_and_b32_e32 v162, 0xffff0000, v162
	v_lshlrev_b32_e32 v217, 16, v163
	v_and_b32_e32 v163, 0xffff0000, v163
	v_fmac_f32_e32 v58, s44, v216
	v_fmac_f32_e32 v59, s44, v162
	v_fmac_f32_e32 v60, s44, v217
	v_fmac_f32_e32 v61, s44, v163
	global_store_dwordx4 v[140:141], v[58:61], off offset:128
	v_lshlrev_b32_e32 v216, 16, v164
	v_and_b32_e32 v164, 0xffff0000, v164
	v_lshlrev_b32_e32 v217, 16, v165
	v_and_b32_e32 v165, 0xffff0000, v165
	v_fmac_f32_e32 v26, s44, v216
	v_fmac_f32_e32 v27, s44, v164
	v_fmac_f32_e32 v28, s44, v217
	v_fmac_f32_e32 v29, s44, v165
	global_store_dwordx4 v[140:141], v[26:29], off offset:192
	v_lshl_add_u64 v[140:141], v[140:141], 0, s[10:11]
	s_waitcnt vmcnt(19)
	v_permlane16_swap_b32_e32 v166, v168
	v_permlane16_swap_b32_e32 v167, v169
	v_lshlrev_b32_e32 v216, 16, v166
	v_and_b32_e32 v166, 0xffff0000, v166
	v_lshlrev_b32_e32 v217, 16, v167
	v_and_b32_e32 v167, 0xffff0000, v167
	v_fmac_f32_e32 v118, s44, v216
	v_fmac_f32_e32 v119, s44, v166
	v_fmac_f32_e32 v120, s44, v217
	v_fmac_f32_e32 v121, s44, v167
	global_store_dwordx4 v[140:141], v[118:121], off offset:0
	v_lshlrev_b32_e32 v216, 16, v168
	v_and_b32_e32 v168, 0xffff0000, v168
	v_lshlrev_b32_e32 v217, 16, v169
	v_and_b32_e32 v169, 0xffff0000, v169
	v_fmac_f32_e32 v86, s44, v216
	v_fmac_f32_e32 v87, s44, v168
	v_fmac_f32_e32 v88, s44, v217
	v_fmac_f32_e32 v89, s44, v169
	global_store_dwordx4 v[140:141], v[86:89], off offset:64
	s_waitcnt vmcnt(20)
	v_permlane16_swap_b32_e32 v170, v172
	v_permlane16_swap_b32_e32 v171, v173
	v_lshlrev_b32_e32 v216, 16, v170
	v_and_b32_e32 v170, 0xffff0000, v170
	v_lshlrev_b32_e32 v217, 16, v171
	v_and_b32_e32 v171, 0xffff0000, v171
	v_fmac_f32_e32 v54, s44, v216
	v_fmac_f32_e32 v55, s44, v170
	v_fmac_f32_e32 v56, s44, v217
	v_fmac_f32_e32 v57, s44, v171
	global_store_dwordx4 v[140:141], v[54:57], off offset:128
	v_lshlrev_b32_e32 v216, 16, v172
	v_and_b32_e32 v172, 0xffff0000, v172
	v_lshlrev_b32_e32 v217, 16, v173
	v_and_b32_e32 v173, 0xffff0000, v173
	v_fmac_f32_e32 v22, s44, v216
	v_fmac_f32_e32 v23, s44, v172
	v_fmac_f32_e32 v24, s44, v217
	v_fmac_f32_e32 v25, s44, v173
	global_store_dwordx4 v[140:141], v[22:25], off offset:192
	v_lshl_add_u64 v[140:141], v[140:141], 0, s[10:11]
	s_waitcnt vmcnt(21)
	v_permlane16_swap_b32_e32 v176, v178
	v_permlane16_swap_b32_e32 v177, v179
	v_lshlrev_b32_e32 v216, 16, v176
	v_and_b32_e32 v176, 0xffff0000, v176
	v_lshlrev_b32_e32 v217, 16, v177
	v_and_b32_e32 v177, 0xffff0000, v177
	v_fmac_f32_e32 v114, s44, v216
	v_fmac_f32_e32 v115, s44, v176
	v_fmac_f32_e32 v116, s44, v217
	v_fmac_f32_e32 v117, s44, v177
	global_store_dwordx4 v[140:141], v[114:117], off offset:0
	v_lshlrev_b32_e32 v216, 16, v178
	v_and_b32_e32 v178, 0xffff0000, v178
	v_lshlrev_b32_e32 v217, 16, v179
	v_and_b32_e32 v179, 0xffff0000, v179
	v_fmac_f32_e32 v82, s44, v216
	v_fmac_f32_e32 v83, s44, v178
	v_fmac_f32_e32 v84, s44, v217
	v_fmac_f32_e32 v85, s44, v179
	global_store_dwordx4 v[140:141], v[82:85], off offset:64
	s_waitcnt vmcnt(22)
	v_permlane16_swap_b32_e32 v180, v182
	v_permlane16_swap_b32_e32 v181, v183
	v_lshlrev_b32_e32 v216, 16, v180
	v_and_b32_e32 v180, 0xffff0000, v180
	v_lshlrev_b32_e32 v217, 16, v181
	v_and_b32_e32 v181, 0xffff0000, v181
	v_fmac_f32_e32 v50, s44, v216
	v_fmac_f32_e32 v51, s44, v180
	v_fmac_f32_e32 v52, s44, v217
	v_fmac_f32_e32 v53, s44, v181
	global_store_dwordx4 v[140:141], v[50:53], off offset:128
	v_lshlrev_b32_e32 v216, 16, v182
	v_and_b32_e32 v182, 0xffff0000, v182
	v_lshlrev_b32_e32 v217, 16, v183
	v_and_b32_e32 v183, 0xffff0000, v183
	v_fmac_f32_e32 v18, s44, v216
	v_fmac_f32_e32 v19, s44, v182
	v_fmac_f32_e32 v20, s44, v217
	v_fmac_f32_e32 v21, s44, v183
	global_store_dwordx4 v[140:141], v[18:21], off offset:192
	v_lshl_add_u64 v[140:141], v[140:141], 0, s[10:11]
	s_waitcnt vmcnt(23)
	v_permlane16_swap_b32_e32 v184, v186
	v_permlane16_swap_b32_e32 v185, v187
	v_lshlrev_b32_e32 v216, 16, v184
	v_and_b32_e32 v184, 0xffff0000, v184
	v_lshlrev_b32_e32 v217, 16, v185
	v_and_b32_e32 v185, 0xffff0000, v185
	v_fmac_f32_e32 v110, s44, v216
	v_fmac_f32_e32 v111, s44, v184
	v_fmac_f32_e32 v112, s44, v217
	v_fmac_f32_e32 v113, s44, v185
	global_store_dwordx4 v[140:141], v[110:113], off offset:0
	v_lshlrev_b32_e32 v216, 16, v186
	v_and_b32_e32 v186, 0xffff0000, v186
	v_lshlrev_b32_e32 v217, 16, v187
	v_and_b32_e32 v187, 0xffff0000, v187
	v_fmac_f32_e32 v78, s44, v216
	v_fmac_f32_e32 v79, s44, v186
	v_fmac_f32_e32 v80, s44, v217
	v_fmac_f32_e32 v81, s44, v187
	global_store_dwordx4 v[140:141], v[78:81], off offset:64
	s_waitcnt vmcnt(24)
; DEVI float blo(unsigned u) { return __uint_as_float(u << 16); }
; DEVI float bhi(unsigned u) { return __uint_as_float(u & 0xffff0000u); }
;     ...
;         if (EPI == EPI_RESID || EPI == EPI_RESID_ATOMIC) {
;           f32x4 x = a;
;           if (EPI == EPI_RESID || kpart == 0) {
;             const u32x2 xr = *(const u32x2*)((const u16*)(p.ws + WS_XB) + (size_t)row * 1024 + col);
;             x[0] += ALPHA * blo(xr[0]); x[1] += ALPHA * bhi(xr[0]); x[2] += ALPHA * blo(xr[1]); x[3] += ALPHA * bhi(xr[1]);
;           }
;           if (EPI == EPI_RESID) *(f32x4*)((float*)(p.ws + WS_XF) + (size_t)row * 1024 + col) = x;
;           else *(f32x4*)((float*)(p.ws + WS_SLAB) + ((size_t)kpart * 512 + (row - T_P)) * 1024 + col) = x;
	v_permlane16_swap_b32_e32 v188, v190
	v_permlane16_swap_b32_e32 v189, v191
	v_lshlrev_b32_e32 v216, 16, v188
	v_and_b32_e32 v188, 0xffff0000, v188
	v_lshlrev_b32_e32 v217, 16, v189
	v_and_b32_e32 v189, 0xffff0000, v189
	v_fmac_f32_e32 v46, s44, v216
	v_fmac_f32_e32 v47, s44, v188
	v_fmac_f32_e32 v48, s44, v217
	v_fmac_f32_e32 v49, s44, v189
	global_store_dwordx4 v[140:141], v[46:49], off offset:128
	v_lshlrev_b32_e32 v216, 16, v190
	v_and_b32_e32 v190, 0xffff0000, v190
	v_lshlrev_b32_e32 v217, 16, v191
	v_and_b32_e32 v191, 0xffff0000, v191
	v_fmac_f32_e32 v14, s44, v216
	v_fmac_f32_e32 v15, s44, v190
	v_fmac_f32_e32 v16, s44, v217
	v_fmac_f32_e32 v17, s44, v191
	global_store_dwordx4 v[140:141], v[14:17], off offset:192
	v_lshl_add_u64 v[140:141], v[140:141], 0, s[10:11]
	s_waitcnt vmcnt(25)
	v_permlane16_swap_b32_e32 v192, v194
	v_permlane16_swap_b32_e32 v193, v195
	v_lshlrev_b32_e32 v216, 16, v192
	v_and_b32_e32 v192, 0xffff0000, v192
	v_lshlrev_b32_e32 v217, 16, v193
	v_and_b32_e32 v193, 0xffff0000, v193
	v_fmac_f32_e32 v106, s44, v216
	v_fmac_f32_e32 v107, s44, v192
	v_fmac_f32_e32 v108, s44, v217
	v_fmac_f32_e32 v109, s44, v193
	global_store_dwordx4 v[140:141], v[106:109], off offset:0
	v_lshlrev_b32_e32 v216, 16, v194
	v_and_b32_e32 v194, 0xffff0000, v194
	v_lshlrev_b32_e32 v217, 16, v195
	v_and_b32_e32 v195, 0xffff0000, v195
	v_fmac_f32_e32 v74, s44, v216
	v_fmac_f32_e32 v75, s44, v194
	v_fmac_f32_e32 v76, s44, v217
	v_fmac_f32_e32 v77, s44, v195
	global_store_dwordx4 v[140:141], v[74:77], off offset:64
	s_waitcnt vmcnt(26)
	v_permlane16_swap_b32_e32 v196, v198
	v_permlane16_swap_b32_e32 v197, v199
	v_lshlrev_b32_e32 v216, 16, v196
	v_and_b32_e32 v196, 0xffff0000, v196
	v_lshlrev_b32_e32 v217, 16, v197
	v_and_b32_e32 v197, 0xffff0000, v197
	v_fmac_f32_e32 v42, s44, v216
	v_fmac_f32_e32 v43, s44, v196
	v_fmac_f32_e32 v44, s44, v217
	v_fmac_f32_e32 v45, s44, v197
	global_store_dwordx4 v[140:141], v[42:45], off offset:128
	v_lshlrev_b32_e32 v216, 16, v198
	v_and_b32_e32 v198, 0xffff0000, v198
	v_lshlrev_b32_e32 v217, 16, v199
	v_and_b32_e32 v199, 0xffff0000, v199
	v_fmac_f32_e32 v10, s44, v216
	v_fmac_f32_e32 v11, s44, v198
	v_fmac_f32_e32 v12, s44, v217
	v_fmac_f32_e32 v13, s44, v199
	global_store_dwordx4 v[140:141], v[10:13], off offset:192
	v_lshl_add_u64 v[140:141], v[140:141], 0, s[10:11]
	s_waitcnt vmcnt(27)
	v_permlane16_swap_b32_e32 v200, v202
	v_permlane16_swap_b32_e32 v201, v203
	v_lshlrev_b32_e32 v216, 16, v200
	v_and_b32_e32 v200, 0xffff0000, v200
	v_lshlrev_b32_e32 v217, 16, v201
	v_and_b32_e32 v201, 0xffff0000, v201
	v_fmac_f32_e32 v102, s44, v216
	v_fmac_f32_e32 v103, s44, v200
	v_fmac_f32_e32 v104, s44, v217
	v_fmac_f32_e32 v105, s44, v201
	global_store_dwordx4 v[140:141], v[102:105], off offset:0
	v_lshlrev_b32_e32 v216, 16, v202
	v_and_b32_e32 v202, 0xffff0000, v202
	v_lshlrev_b32_e32 v217, 16, v203
	v_and_b32_e32 v203, 0xffff0000, v203
	v_fmac_f32_e32 v70, s44, v216
	v_fmac_f32_e32 v71, s44, v202
	v_fmac_f32_e32 v72, s44, v217
	v_fmac_f32_e32 v73, s44, v203
	global_store_dwordx4 v[140:141], v[70:73], off offset:64
	s_waitcnt vmcnt(28)
	v_permlane16_swap_b32_e32 v204, v206
	v_permlane16_swap_b32_e32 v205, v207
	v_lshlrev_b32_e32 v216, 16, v204
	v_and_b32_e32 v204, 0xffff0000, v204
	v_lshlrev_b32_e32 v217, 16, v205
	v_and_b32_e32 v205, 0xffff0000, v205
	v_fmac_f32_e32 v38, s44, v216
	v_fmac_f32_e32 v39, s44, v204
	v_fmac_f32_e32 v40, s44, v217
	v_fmac_f32_e32 v41, s44, v205
	global_store_dwordx4 v[140:141], v[38:41], off offset:128
	v_lshlrev_b32_e32 v216, 16, v206
	v_and_b32_e32 v206, 0xffff0000, v206
	v_lshlrev_b32_e32 v217, 16, v207
	v_and_b32_e32 v207, 0xffff0000, v207
	v_fmac_f32_e32 v6, s44, v216
	v_fmac_f32_e32 v7, s44, v206
	v_fmac_f32_e32 v8, s44, v217
	v_fmac_f32_e32 v9, s44, v207
	global_store_dwordx4 v[140:141], v[6:9], off offset:192
	v_lshl_add_u64 v[140:141], v[140:141], 0, s[10:11]
	s_waitcnt vmcnt(29)
	v_permlane16_swap_b32_e32 v208, v210
	v_permlane16_swap_b32_e32 v209, v211
	v_lshlrev_b32_e32 v216, 16, v208
	v_and_b32_e32 v208, 0xffff0000, v208
	v_lshlrev_b32_e32 v217, 16, v209
	v_and_b32_e32 v209, 0xffff0000, v209
	v_fmac_f32_e32 v98, s44, v216
	v_fmac_f32_e32 v99, s44, v208
	v_fmac_f32_e32 v100, s44, v217
	v_fmac_f32_e32 v101, s44, v209
	global_store_dwordx4 v[140:141], v[98:101], off offset:0
	v_lshlrev_b32_e32 v216, 16, v210
	v_and_b32_e32 v210, 0xffff0000, v210
	v_lshlrev_b32_e32 v217, 16, v211
	v_and_b32_e32 v211, 0xffff0000, v211
	v_fmac_f32_e32 v66, s44, v216
	v_fmac_f32_e32 v67, s44, v210
	v_fmac_f32_e32 v68, s44, v217
	v_fmac_f32_e32 v69, s44, v211
	global_store_dwordx4 v[140:141], v[66:69], off offset:64
	s_waitcnt vmcnt(30)
	v_permlane16_swap_b32_e32 v212, v214
	v_permlane16_swap_b32_e32 v213, v215
	v_lshlrev_b32_e32 v216, 16, v212
	v_and_b32_e32 v212, 0xffff0000, v212
	v_lshlrev_b32_e32 v217, 16, v213
	v_and_b32_e32 v213, 0xffff0000, v213
	v_fmac_f32_e32 v34, s44, v216
	v_fmac_f32_e32 v35, s44, v212
	v_fmac_f32_e32 v36, s44, v217
	v_fmac_f32_e32 v37, s44, v213
	global_store_dwordx4 v[140:141], v[34:37], off offset:128
	v_lshlrev_b32_e32 v216, 16, v214
	v_and_b32_e32 v214, 0xffff0000, v214
	v_lshlrev_b32_e32 v217, 16, v215
	v_and_b32_e32 v215, 0xffff0000, v215
	v_fmac_f32_e32 v2, s44, v216
	v_fmac_f32_e32 v3, s44, v214
	v_fmac_f32_e32 v4, s44, v217
	v_fmac_f32_e32 v5, s44, v215
	global_store_dwordx4 v[140:141], v[2:5], off offset:192
	s_branch .LBB0_146

; #define LAS __attribute__((address_space(3)))
;     ...
;   const int nk = (nk_part < 0) ? (K >> 5) : nk_part;
;   const int lrow = tid >> 2, lpc = tid & 3;
;   const int lch = lpc ^ ((0x78 >> (((lrow >> 2) & 3) * 2)) & 3);
;   const u16* ga = A + (size_t)(m0 + lrow) * lda + kbeg + lch * 8;
;   const u16* gb = Bt + (size_t)(n0 + lrow) * K + kbeg + lch * 8;
;   const size_t ga1 = (size_t)64 * lda, gb1 = (size_t)64 * K;
;   const unsigned lds0 = (unsigned)(uintptr_t)(LAS char*)smem + (unsigned)__builtin_amdgcn_readfirstlane(wid) * 1024u;
; DEVI void run_phase(const Params& p, int ph, char* smem) {
;     ...
;         } else {
;           const int u_ = t - 512, tl_ = u_ / 8, q_ = u_ - tl_ * 8;
;           gemm_tile256<EPI_RESID_ATOMIC>(p, mix, 1024, Bt, 1024, (64 + (tl_ & 1)) * 256, (tl_ >> 1) * 128, nullptr, 0, smem, q_ * 128, 4, q_);
.LBB0_758:
	s_cmpk_gt_i32 s39, 0x1ff
	s_mov_b64 s[2:3], -1
	s_cbranch_scc0 .LBB0_812
	s_sub_i32 s43, s39, 512
	s_lshr_b32 s42, s43, 3
	s_and_b32 s98, s43, 7
	s_lshr_b32 s15, s42, 1
	s_and_b32 s42, s42, 1
	s_add_i32 s42, s42, 64
	v_readlane_b32 s2, v250, 5
	v_readlane_b32 s3, v250, 6
	v_readlane_b32 s43, v254, 62
	s_mul_i32 s1, s42, 0x80000
	s_add_u32 s4, s2, s1
	s_addc_u32 s5, s3, 0
	s_add_u32 s4, s4, 0xb580000
	s_addc_u32 s5, s5, 0
	s_mul_i32 s1, s43, 0x200000
	s_mul_i32 s14, s15, 0x40000
	s_add_i32 s1, s1, s14
	s_add_u32 s10, s2, s1
	s_addc_u32 s11, s3, 0
	s_add_u32 s10, s10, 0x15e00000
	s_addc_u32 s11, s11, 0
	s_mul_i32 s1, s98, 256
	s_add_u32 s4, s4, s1
	s_addc_u32 s5, s5, 0
	s_mul_i32 s1, s98, 512
	s_add_u32 s10, s10, s1
	s_addc_u32 s11, s11, 0
	s_movk_i32 s0, 0x78
	v_lshrrev_b32_e32 v0, 2, v145
	v_and_b32_e32 v131, 3, v145
	v_bfe_u32 v136, v145, 4, 2
	v_lshlrev_b32_e32 v136, 1, v136
	v_lshrrev_b32_e64 v136, v136, s0
	v_and_b32_e32 v136, 3, v136
	v_xor_b32_e32 v131, v131, v136
	v_lshlrev_b32_e32 v131, 4, v131
	s_movk_i32 s14, 0x800
	v_mad_u32_u24 v0, v0, s14, v131
	v_bfe_u32 v137, v145, 2, 1
	s_movk_i32 s14, 0x7c0
	v_mul_u32_u24_e32 v136, s14, v137
	v_sub_u32_e32 v136, v0, v136
	v_mov_b32_e32 v137, 0
	v_lshl_add_u64 v[134:135], s[10:11], 0, v[136:137]
	v_bfe_u32 v137, v145, 2, 1
	s_mov_b32 s12, 64
	s_mov_b32 s13, 0
	v_lshl_add_u64 v[132:133], s[4:5], 0, v[0:1]
	v_bfe_u32 v136, v145, 2, 2
	v_lshlrev_b32_e32 v136, 1, v136
	v_lshrrev_b32_e64 v136, v136, s0
	v_and_b32_e32 v136, 3, v136
	v_bfe_u32 v137, v145, 4, 2
	v_xor_b32_e32 v136, v136, v137
	v_lshlrev_b32_e32 v136, 4, v136
	v_and_b32_e32 v131, 15, v145
	v_lshl_or_b32 v136, v131, 6, v136
	v_bfe_u32 v137, v145, 6, 1
	v_lshl_or_b32 v137, v137, 12, v136
	v_lshrrev_b32_e32 v0, 7, v145
	v_lshl_or_b32 v136, v0, 13, v136
	v_and_b32_e32 v140, 1, v131
	v_lshl_or_b32 v131, v0, 7, v131
	v_bfe_u32 v0, v145, 4, 2
	v_lshlrev_b32_e32 v0, 3, v0
	v_bfe_u32 v141, v145, 6, 1
	s_lshl_b32 s1, s42, 19
	s_lshl_b32 s14, s15, 8
	s_add_i32 s1, s1, s14
	s_add_u32 s4, s2, s1
	s_addc_u32 s5, s3, 0
	s_add_u32 s4, s4, 0x4200000
	s_addc_u32 s5, s5, 0
	v_lshlrev_b32_e32 v138, 11, v131
	v_lshl_add_u32 v138, v141, 7, v138
	v_bfe_u32 v139, v145, 4, 1
	v_lshl_add_u32 v138, v139, 5, v138
	v_bfe_u32 v139, v145, 5, 1
	v_lshl_add_u32 v138, v139, 4, v138
	v_mov_b32_e32 v139, 0
	v_lshl_add_u64 v[138:139], s[4:5], 0, v[138:139]
	s_and_b32 s1, s42, 1
	s_lshl_b32 s1, s1, 20
	s_lshl_b32 s14, s98, 21
	s_add_i32 s1, s1, s14
	s_lshl_b32 s14, s15, 9
	s_add_i32 s1, s1, s14
	s_add_u32 s10, s2, s1
	s_addc_u32 s11, s3, 0
	s_add_u32 s10, s10, 0x1dcc0000
	s_addc_u32 s11, s11, 0
	v_lshlrev_b32_e32 v140, 12, v131
	v_lshl_add_u32 v140, v141, 8, v140
	v_lshl_add_u32 v140, v0, 1, v140
	v_mov_b32_e32 v141, 0
	v_lshl_add_u64 v[140:141], s[10:11], 0, v[140:141]
	s_mov_b32 s2, 0x20000
	s_mov_b32 s3, 0
	v_lshrrev_b32_e32 v0, 6, v145
	v_lshlrev_b32_e32 v0, 10, v0
	s_nop 0
	v_readfirstlane_b32 s43, v0
	s_mov_b32 s40, m0
	s_mov_b32 s4, 128
	s_mov_b32 s5, 0
	v_mov_b32_e32 v2, 0
	v_mov_b32_e32 v3, 0
	v_mov_b32_e32 v4, 0
	v_mov_b32_e32 v5, 0
	v_mov_b32_e32 v6, 0
	v_mov_b32_e32 v7, 0
	v_mov_b32_e32 v8, 0
	v_mov_b32_e32 v9, 0
	v_mov_b32_e32 v10, 0
	v_mov_b32_e32 v11, 0
	v_mov_b32_e32 v12, 0
	v_mov_b32_e32 v13, 0
	v_mov_b32_e32 v14, 0
	v_mov_b32_e32 v15, 0
	v_mov_b32_e32 v16, 0
	v_mov_b32_e32 v17, 0
	v_mov_b32_e32 v18, 0
	v_mov_b32_e32 v19, 0
	v_mov_b32_e32 v20, 0
	v_mov_b32_e32 v21, 0
	v_mov_b32_e32 v22, 0
	v_mov_b32_e32 v23, 0
	v_mov_b32_e32 v24, 0
	v_mov_b32_e32 v25, 0
	v_mov_b32_e32 v26, 0
	v_mov_b32_e32 v27, 0
	v_mov_b32_e32 v28, 0
	v_mov_b32_e32 v29, 0
	v_mov_b32_e32 v30, 0
	v_mov_b32_e32 v31, 0
	v_mov_b32_e32 v32, 0
	v_mov_b32_e32 v33, 0
	v_mov_b32_e32 v34, 0
	v_mov_b32_e32 v35, 0
	v_mov_b32_e32 v36, 0
	v_mov_b32_e32 v37, 0
	v_mov_b32_e32 v38, 0
	v_mov_b32_e32 v39, 0
	v_mov_b32_e32 v40, 0
	v_mov_b32_e32 v41, 0
	v_mov_b32_e32 v42, 0
	v_mov_b32_e32 v43, 0
	v_mov_b32_e32 v44, 0
	v_mov_b32_e32 v45, 0
	v_mov_b32_e32 v46, 0
	v_mov_b32_e32 v47, 0
	v_mov_b32_e32 v48, 0
	v_mov_b32_e32 v49, 0
	v_mov_b32_e32 v50, 0
	v_mov_b32_e32 v51, 0
	v_mov_b32_e32 v52, 0
	v_mov_b32_e32 v53, 0
	v_mov_b32_e32 v54, 0
	v_mov_b32_e32 v55, 0
	v_mov_b32_e32 v56, 0
	v_mov_b32_e32 v57, 0
	v_mov_b32_e32 v58, 0
	v_mov_b32_e32 v59, 0
	v_mov_b32_e32 v60, 0
	v_mov_b32_e32 v61, 0
	v_mov_b32_e32 v62, 0
	v_mov_b32_e32 v63, 0
	v_mov_b32_e32 v64, 0
	v_mov_b32_e32 v65, 0
	v_mov_b32_e32 v66, 0
	v_mov_b32_e32 v67, 0
	v_mov_b32_e32 v68, 0
	v_mov_b32_e32 v69, 0
	v_mov_b32_e32 v70, 0
	v_mov_b32_e32 v71, 0
	v_mov_b32_e32 v72, 0
	v_mov_b32_e32 v73, 0
	v_mov_b32_e32 v74, 0
	v_mov_b32_e32 v75, 0
	v_mov_b32_e32 v76, 0
	v_mov_b32_e32 v77, 0
	v_mov_b32_e32 v78, 0
	v_mov_b32_e32 v79, 0
	v_mov_b32_e32 v80, 0
	v_mov_b32_e32 v81, 0
	v_mov_b32_e32 v82, 0
	v_mov_b32_e32 v83, 0
	v_mov_b32_e32 v84, 0
	v_mov_b32_e32 v85, 0
	v_mov_b32_e32 v86, 0
	v_mov_b32_e32 v87, 0
	v_mov_b32_e32 v88, 0
	v_mov_b32_e32 v89, 0
	v_mov_b32_e32 v90, 0
	v_mov_b32_e32 v91, 0
	v_mov_b32_e32 v92, 0
	v_mov_b32_e32 v93, 0
	v_mov_b32_e32 v94, 0
	v_mov_b32_e32 v95, 0
	v_mov_b32_e32 v96, 0
	v_mov_b32_e32 v97, 0
	v_mov_b32_e32 v98, 0
	v_mov_b32_e32 v99, 0
	v_mov_b32_e32 v100, 0
	v_mov_b32_e32 v101, 0
	v_mov_b32_e32 v102, 0
	v_mov_b32_e32 v103, 0
	v_mov_b32_e32 v104, 0
	v_mov_b32_e32 v105, 0
	v_mov_b32_e32 v106, 0
	v_mov_b32_e32 v107, 0
	v_mov_b32_e32 v108, 0
	v_mov_b32_e32 v109, 0
	v_mov_b32_e32 v110, 0
	v_mov_b32_e32 v111, 0
	v_mov_b32_e32 v112, 0
	v_mov_b32_e32 v113, 0
	v_mov_b32_e32 v114, 0
	v_mov_b32_e32 v115, 0
	v_mov_b32_e32 v116, 0
	v_mov_b32_e32 v117, 0
	v_mov_b32_e32 v118, 0
	v_mov_b32_e32 v119, 0
	v_mov_b32_e32 v120, 0
	v_mov_b32_e32 v121, 0
	v_mov_b32_e32 v122, 0
	v_mov_b32_e32 v123, 0
	v_mov_b32_e32 v124, 0
	v_mov_b32_e32 v125, 0
	v_mov_b32_e32 v126, 0
	v_mov_b32_e32 v127, 0
	v_mov_b32_e32 v128, 0
	v_mov_b32_e32 v129, 0
	s_barrier
;     ...
;   __syncthreads();
;   G2_STAGE(0); G2_STAGE(1);
;   const int fsw = (0x78 >> (((r16 >> 2) & 3) * 2)) & 3;
;   const int aoff = (wm * 128 + r16) * 64 + ((quad ^ fsw) << 4);
;   const int boff = 16384 + (wn * 64 + r16) * 64 + ((quad ^ fsw) << 4);
;   for (int kt = 0; kt < nk; kt++) {
;     if (kt + 1 < nk) asm volatile("s_waitcnt vmcnt(6)" ::: "memory");
;     else asm volatile("s_waitcnt vmcnt(0)" ::: "memory");
;     __builtin_amdgcn_s_barrier();
;     asm volatile("" ::: "memory");
;     if (kt + 2 < nk) G2_STAGE(kt + 2);
;     const char* cS = smem + (kt % 3) * 24576;
;     bf16x8 xa[8], wb[4];
; #pragma unroll
;     for (int f = 0; f < 8; f++) xa[f] = *(const bf16x8*)(cS + aoff + f * 1024);
; #pragma unroll
;     for (int f = 0; f < 4; f++) wb[f] = *(const bf16x8*)(cS + boff + f * 1024);
; #pragma unroll
;     for (int nf = 0; nf < 4; nf++)
; #pragma unroll
;       for (int mf = 0; mf < 8; mf++)
;         acc[nf][mf] = __builtin_amdgcn_mfma_f32_16x16x32_bf16(wb[nf], xa[mf], acc[nf][mf], 0, 0, 0);
	s_add_i32 s15, s43, 0x0
	s_mov_b32 m0, s15
	v_lshl_add_u64 v[142:143], v[132:133], 0, s[2:3]
	global_load_lds_dwordx4 v[132:133], off
	s_addk_i32 m0, 0x1000
	s_nop 0
	global_load_lds_dwordx4 v[142:143], off
	v_lshl_add_u64 v[142:143], v[142:143], 0, s[2:3]
	s_addk_i32 m0, 0x1000
	s_nop 0
	global_load_lds_dwordx4 v[142:143], off
	v_lshl_add_u64 v[142:143], v[142:143], 0, s[2:3]
	s_addk_i32 m0, 0x1000
	s_nop 0
	global_load_lds_dwordx4 v[142:143], off
	s_addk_i32 m0, 0x1000
	v_lshl_add_u64 v[142:143], v[134:135], 0, s[2:3]
	s_nop 0
	global_load_lds_dwordx4 v[134:135], off
	s_addk_i32 m0, 0x1000
	v_lshl_add_u64 v[132:133], v[132:133], 0, s[12:13]
	s_nop 0
	global_load_lds_dwordx4 v[142:143], off
	v_lshl_add_u64 v[134:135], v[134:135], 0, s[4:5]
	s_nop 0
	s_add_i32 s15, s43, 0x6000
	s_mov_b32 m0, s15
	v_lshl_add_u64 v[142:143], v[132:133], 0, s[2:3]
	global_load_lds_dwordx4 v[132:133], off
	s_addk_i32 m0, 0x1000
	s_nop 0
	global_load_lds_dwordx4 v[142:143], off
	v_lshl_add_u64 v[142:143], v[142:143], 0, s[2:3]
	s_addk_i32 m0, 0x1000
	s_nop 0
	global_load_lds_dwordx4 v[142:143], off
	v_lshl_add_u64 v[142:143], v[142:143], 0, s[2:3]
	s_addk_i32 m0, 0x1000
	s_nop 0
	global_load_lds_dwordx4 v[142:143], off
	s_addk_i32 m0, 0x1000
	v_lshl_add_u64 v[142:143], v[134:135], 0, s[2:3]
	s_nop 0
	global_load_lds_dwordx4 v[134:135], off
	s_addk_i32 m0, 0x1000
	v_lshl_add_u64 v[132:133], v[132:133], 0, s[12:13]
	s_nop 0
	global_load_lds_dwordx4 v[142:143], off
	v_lshl_add_u64 v[134:135], v[134:135], 0, s[4:5]
	s_nop 0
	s_add_i32 s15, s43, 0xc000
	s_mov_b32 m0, s15
	v_lshl_add_u64 v[142:143], v[132:133], 0, s[2:3]
	global_load_lds_dwordx4 v[132:133], off
	s_addk_i32 m0, 0x1000
	s_nop 0
	global_load_lds_dwordx4 v[142:143], off
	v_lshl_add_u64 v[142:143], v[142:143], 0, s[2:3]
	s_addk_i32 m0, 0x1000
	s_nop 0
	global_load_lds_dwordx4 v[142:143], off
	v_lshl_add_u64 v[142:143], v[142:143], 0, s[2:3]
	s_addk_i32 m0, 0x1000
	s_nop 0
	global_load_lds_dwordx4 v[142:143], off
	s_addk_i32 m0, 0x1000
	v_lshl_add_u64 v[142:143], v[134:135], 0, s[2:3]
	s_nop 0
	global_load_lds_dwordx4 v[134:135], off
	s_addk_i32 m0, 0x1000
	v_lshl_add_u64 v[132:133], v[132:133], 0, s[12:13]
	s_nop 0
	global_load_lds_dwordx4 v[142:143], off
	v_lshl_add_u64 v[134:135], v[134:135], 0, s[4:5]
	s_nop 0
	s_waitcnt vmcnt(12)
	s_barrier
	ds_read_b128 v[146:149], v136 offset:0
	ds_read_b128 v[152:155], v136 offset:1024
	ds_read_b128 v[156:159], v136 offset:2048
	ds_read_b128 v[162:165], v136 offset:3072
	ds_read_b128 v[166:169], v136 offset:4096
	ds_read_b128 v[170:173], v136 offset:5120
	ds_read_b128 v[176:179], v136 offset:6144
	ds_read_b128 v[180:183], v136 offset:7168
	ds_read_b128 v[184:187], v137 offset:16384
	ds_read_b128 v[188:191], v137 offset:17408
	ds_read_b128 v[192:195], v137 offset:18432
	ds_read_b128 v[196:199], v137 offset:19456
	s_movk_i32 s1, 0x6000
	s_mov_b32 s14, 0
	s_waitcnt vmcnt(6) lgkmcnt(0)
	s_barrier
	v_add_u32_e32 v144, s1, v136
	v_mfma_f32_16x16x32_bf16 v[126:129], v[184:187], v[146:149], v[126:129]
	ds_read_b128 v[200:203], v144 offset:0
	v_mfma_f32_16x16x32_bf16 v[122:125], v[184:187], v[152:155], v[122:125]
	ds_read_b128 v[204:207], v144 offset:1024
	v_mfma_f32_16x16x32_bf16 v[118:121], v[184:187], v[156:159], v[118:121]
	ds_read_b128 v[208:211], v144 offset:2048
	v_mfma_f32_16x16x32_bf16 v[114:117], v[184:187], v[162:165], v[114:117]
	ds_read_b128 v[212:215], v144 offset:3072
	v_mfma_f32_16x16x32_bf16 v[110:113], v[184:187], v[166:169], v[110:113]
	ds_read_b128 v[216:219], v144 offset:4096
	v_mfma_f32_16x16x32_bf16 v[106:109], v[184:187], v[170:173], v[106:109]
	ds_read_b128 v[220:223], v144 offset:5120
	v_mfma_f32_16x16x32_bf16 v[102:105], v[184:187], v[176:179], v[102:105]
	ds_read_b128 v[224:227], v144 offset:6144
	v_mfma_f32_16x16x32_bf16 v[98:101], v[184:187], v[180:183], v[98:101]
	ds_read_b128 v[228:231], v144 offset:7168
	v_mfma_f32_16x16x32_bf16 v[94:97], v[188:191], v[146:149], v[94:97]
	v_add_u32_e32 v144, s1, v137
	v_mfma_f32_16x16x32_bf16 v[90:93], v[188:191], v[152:155], v[90:93]
	v_mfma_f32_16x16x32_bf16 v[86:89], v[188:191], v[156:159], v[86:89]
	ds_read_b128 v[232:235], v144 offset:16384
	v_mfma_f32_16x16x32_bf16 v[82:85], v[188:191], v[162:165], v[82:85]
	ds_read_b128 v[236:239], v144 offset:17408
	v_mfma_f32_16x16x32_bf16 v[78:81], v[188:191], v[166:169], v[78:81]
	ds_read_b128 v[240:243], v144 offset:18432
	v_mfma_f32_16x16x32_bf16 v[74:77], v[188:191], v[170:173], v[74:77]
	ds_read_b128 v[244:247], v144 offset:19456
	s_add_i32 s15, s43, s14
	v_mfma_f32_16x16x32_bf16 v[70:73], v[188:191], v[176:179], v[70:73]
	s_mov_b32 m0, s15
	v_lshl_add_u64 v[142:143], v[132:133], 0, s[2:3]
	v_mfma_f32_16x16x32_bf16 v[66:69], v[188:191], v[180:183], v[66:69]
	global_load_lds_dwordx4 v[132:133], off
	s_addk_i32 m0, 0x1000
	v_mfma_f32_16x16x32_bf16 v[62:65], v[192:195], v[146:149], v[62:65]
	v_mfma_f32_16x16x32_bf16 v[58:61], v[192:195], v[152:155], v[58:61]
	v_mfma_f32_16x16x32_bf16 v[54:57], v[192:195], v[156:159], v[54:57]
	global_load_lds_dwordx4 v[142:143], off
	v_lshl_add_u64 v[142:143], v[142:143], 0, s[2:3]
	s_addk_i32 m0, 0x1000
	v_mfma_f32_16x16x32_bf16 v[50:53], v[192:195], v[162:165], v[50:53]
	v_mfma_f32_16x16x32_bf16 v[46:49], v[192:195], v[166:169], v[46:49]
	v_mfma_f32_16x16x32_bf16 v[42:45], v[192:195], v[170:173], v[42:45]
	global_load_lds_dwordx4 v[142:143], off
	v_lshl_add_u64 v[142:143], v[142:143], 0, s[2:3]
	s_addk_i32 m0, 0x1000
	v_mfma_f32_16x16x32_bf16 v[38:41], v[192:195], v[176:179], v[38:41]
	v_mfma_f32_16x16x32_bf16 v[34:37], v[192:195], v[180:183], v[34:37]
	v_mfma_f32_16x16x32_bf16 v[30:33], v[196:199], v[146:149], v[30:33]
	global_load_lds_dwordx4 v[142:143], off
	s_addk_i32 m0, 0x1000
	v_lshl_add_u64 v[142:143], v[134:135], 0, s[2:3]
	v_mfma_f32_16x16x32_bf16 v[26:29], v[196:199], v[152:155], v[26:29]
	v_mfma_f32_16x16x32_bf16 v[22:25], v[196:199], v[156:159], v[22:25]
	v_mfma_f32_16x16x32_bf16 v[18:21], v[196:199], v[162:165], v[18:21]
	global_load_lds_dwordx4 v[134:135], off
	s_addk_i32 m0, 0x1000
	v_lshl_add_u64 v[132:133], v[132:133], 0, s[12:13]
	v_mfma_f32_16x16x32_bf16 v[14:17], v[196:199], v[166:169], v[14:17]
	v_mfma_f32_16x16x32_bf16 v[10:13], v[196:199], v[170:173], v[10:13]
	v_mfma_f32_16x16x32_bf16 v[6:9], v[196:199], v[176:179], v[6:9]
	global_load_lds_dwordx4 v[142:143], off
	v_lshl_add_u64 v[134:135], v[134:135], 0, s[4:5]
	v_mfma_f32_16x16x32_bf16 v[2:5], v[196:199], v[180:183], v[2:5]
	s_mov_b32 s14, s1
	s_add_i32 s1, s1, 0x6000
	s_cmp_eq_u32 s1, 0x12000
	s_cselect_b32 s1, 0, s1
	s_waitcnt vmcnt(6) lgkmcnt(0)
	s_barrier
;     ...
;   for (int kt = 0; kt < nk; kt++) {
;     if (kt + 1 < nk) asm volatile("s_waitcnt vmcnt(6)" ::: "memory");
;     else asm volatile("s_waitcnt vmcnt(0)" ::: "memory");
;     __builtin_amdgcn_s_barrier();
;     asm volatile("" ::: "memory");
;     if (kt + 2 < nk) G2_STAGE(kt + 2);
;     const char* cS = smem + (kt % 3) * 24576;
;     bf16x8 xa[8], wb[4];
; #pragma unroll
;     for (int f = 0; f < 8; f++) xa[f] = *(const bf16x8*)(cS + aoff + f * 1024);
; #pragma unroll
;     for (int f = 0; f < 4; f++) wb[f] = *(const bf16x8*)(cS + boff + f * 1024);
; #pragma unroll
;     for (int nf = 0; nf < 4; nf++)
; #pragma unroll
;       for (int mf = 0; mf < 8; mf++)
;         acc[nf][mf] = __builtin_amdgcn_mfma_f32_16x16x32_bf16(wb[nf], xa[mf], acc[nf][mf], 0, 0, 0);
	v_add_u32_e32 v144, s1, v136
	v_mfma_f32_16x16x32_bf16 v[126:129], v[232:235], v[200:203], v[126:129]
	ds_read_b128 v[146:149], v144 offset:0
	v_mfma_f32_16x16x32_bf16 v[122:125], v[232:235], v[204:207], v[122:125]
	ds_read_b128 v[152:155], v144 offset:1024
	v_mfma_f32_16x16x32_bf16 v[118:121], v[232:235], v[208:211], v[118:121]
	ds_read_b128 v[156:159], v144 offset:2048
	v_mfma_f32_16x16x32_bf16 v[114:117], v[232:235], v[212:215], v[114:117]
	ds_read_b128 v[162:165], v144 offset:3072
	v_mfma_f32_16x16x32_bf16 v[110:113], v[232:235], v[216:219], v[110:113]
	ds_read_b128 v[166:169], v144 offset:4096
	v_mfma_f32_16x16x32_bf16 v[106:109], v[232:235], v[220:223], v[106:109]
	ds_read_b128 v[170:173], v144 offset:5120
	v_mfma_f32_16x16x32_bf16 v[102:105], v[232:235], v[224:227], v[102:105]
	ds_read_b128 v[176:179], v144 offset:6144
	v_mfma_f32_16x16x32_bf16 v[98:101], v[232:235], v[228:231], v[98:101]
	ds_read_b128 v[180:183], v144 offset:7168
	v_mfma_f32_16x16x32_bf16 v[94:97], v[236:239], v[200:203], v[94:97]
	v_add_u32_e32 v144, s1, v137
	v_mfma_f32_16x16x32_bf16 v[90:93], v[236:239], v[204:207], v[90:93]
	v_mfma_f32_16x16x32_bf16 v[86:89], v[236:239], v[208:211], v[86:89]
	ds_read_b128 v[184:187], v144 offset:16384
	v_mfma_f32_16x16x32_bf16 v[82:85], v[236:239], v[212:215], v[82:85]
	ds_read_b128 v[188:191], v144 offset:17408
	v_mfma_f32_16x16x32_bf16 v[78:81], v[236:239], v[216:219], v[78:81]
	ds_read_b128 v[192:195], v144 offset:18432
	v_mfma_f32_16x16x32_bf16 v[74:77], v[236:239], v[220:223], v[74:77]
	ds_read_b128 v[196:199], v144 offset:19456
	v_mfma_f32_16x16x32_bf16 v[70:73], v[236:239], v[224:227], v[70:73]
	v_mfma_f32_16x16x32_bf16 v[66:69], v[236:239], v[228:231], v[66:69]
	v_mfma_f32_16x16x32_bf16 v[62:65], v[240:243], v[200:203], v[62:65]
	v_mfma_f32_16x16x32_bf16 v[58:61], v[240:243], v[204:207], v[58:61]
	v_mfma_f32_16x16x32_bf16 v[54:57], v[240:243], v[208:211], v[54:57]
	v_mfma_f32_16x16x32_bf16 v[50:53], v[240:243], v[212:215], v[50:53]
	v_mfma_f32_16x16x32_bf16 v[46:49], v[240:243], v[216:219], v[46:49]
	v_mfma_f32_16x16x32_bf16 v[42:45], v[240:243], v[220:223], v[42:45]
	v_mfma_f32_16x16x32_bf16 v[38:41], v[240:243], v[224:227], v[38:41]
	v_mfma_f32_16x16x32_bf16 v[34:37], v[240:243], v[228:231], v[34:37]
	v_mfma_f32_16x16x32_bf16 v[30:33], v[244:247], v[200:203], v[30:33]
	v_mfma_f32_16x16x32_bf16 v[26:29], v[244:247], v[204:207], v[26:29]
	v_mfma_f32_16x16x32_bf16 v[22:25], v[244:247], v[208:211], v[22:25]
	v_mfma_f32_16x16x32_bf16 v[18:21], v[244:247], v[212:215], v[18:21]
	v_mfma_f32_16x16x32_bf16 v[14:17], v[244:247], v[216:219], v[14:17]
	v_mfma_f32_16x16x32_bf16 v[10:13], v[244:247], v[220:223], v[10:13]
	v_mfma_f32_16x16x32_bf16 v[6:9], v[244:247], v[224:227], v[6:9]
	v_mfma_f32_16x16x32_bf16 v[2:5], v[244:247], v[228:231], v[2:5]
	s_mov_b32 s14, s1
	s_add_i32 s1, s1, 0x6000
	s_cmp_eq_u32 s1, 0x12000
	s_cselect_b32 s1, 0, s1
	s_waitcnt vmcnt(0) lgkmcnt(0)
	s_barrier
	v_add_u32_e32 v144, s1, v136
	v_mfma_f32_16x16x32_bf16 v[126:129], v[184:187], v[146:149], v[126:129]
	ds_read_b128 v[200:203], v144 offset:0
	v_mfma_f32_16x16x32_bf16 v[122:125], v[184:187], v[152:155], v[122:125]
	ds_read_b128 v[204:207], v144 offset:1024
	v_mfma_f32_16x16x32_bf16 v[118:121], v[184:187], v[156:159], v[118:121]
	ds_read_b128 v[208:211], v144 offset:2048
	v_mfma_f32_16x16x32_bf16 v[114:117], v[184:187], v[162:165], v[114:117]
	ds_read_b128 v[212:215], v144 offset:3072
	v_mfma_f32_16x16x32_bf16 v[110:113], v[184:187], v[166:169], v[110:113]
	ds_read_b128 v[216:219], v144 offset:4096
	v_mfma_f32_16x16x32_bf16 v[106:109], v[184:187], v[170:173], v[106:109]
	ds_read_b128 v[220:223], v144 offset:5120
	v_mfma_f32_16x16x32_bf16 v[102:105], v[184:187], v[176:179], v[102:105]
	ds_read_b128 v[224:227], v144 offset:6144
	v_mfma_f32_16x16x32_bf16 v[98:101], v[184:187], v[180:183], v[98:101]
	ds_read_b128 v[228:231], v144 offset:7168
	v_mfma_f32_16x16x32_bf16 v[94:97], v[188:191], v[146:149], v[94:97]
	v_add_u32_e32 v144, s1, v137
	v_mfma_f32_16x16x32_bf16 v[90:93], v[188:191], v[152:155], v[90:93]
	v_mfma_f32_16x16x32_bf16 v[86:89], v[188:191], v[156:159], v[86:89]
	ds_read_b128 v[232:235], v144 offset:16384
	v_mfma_f32_16x16x32_bf16 v[82:85], v[188:191], v[162:165], v[82:85]
	ds_read_b128 v[236:239], v144 offset:17408
	v_mfma_f32_16x16x32_bf16 v[78:81], v[188:191], v[166:169], v[78:81]
	ds_read_b128 v[240:243], v144 offset:18432
	v_mfma_f32_16x16x32_bf16 v[74:77], v[188:191], v[170:173], v[74:77]
	ds_read_b128 v[244:247], v144 offset:19456
	v_mfma_f32_16x16x32_bf16 v[70:73], v[188:191], v[176:179], v[70:73]
	v_mfma_f32_16x16x32_bf16 v[66:69], v[188:191], v[180:183], v[66:69]
	v_mfma_f32_16x16x32_bf16 v[62:65], v[192:195], v[146:149], v[62:65]
	v_mfma_f32_16x16x32_bf16 v[58:61], v[192:195], v[152:155], v[58:61]
	v_mfma_f32_16x16x32_bf16 v[54:57], v[192:195], v[156:159], v[54:57]
	v_mfma_f32_16x16x32_bf16 v[50:53], v[192:195], v[162:165], v[50:53]
	v_mfma_f32_16x16x32_bf16 v[46:49], v[192:195], v[166:169], v[46:49]
	v_mfma_f32_16x16x32_bf16 v[42:45], v[192:195], v[170:173], v[42:45]
	v_mfma_f32_16x16x32_bf16 v[38:41], v[192:195], v[176:179], v[38:41]
	v_mfma_f32_16x16x32_bf16 v[34:37], v[192:195], v[180:183], v[34:37]
	v_mfma_f32_16x16x32_bf16 v[30:33], v[196:199], v[146:149], v[30:33]
	v_mfma_f32_16x16x32_bf16 v[26:29], v[196:199], v[152:155], v[26:29]
	v_mfma_f32_16x16x32_bf16 v[22:25], v[196:199], v[156:159], v[22:25]
	v_mfma_f32_16x16x32_bf16 v[18:21], v[196:199], v[162:165], v[18:21]
	v_mfma_f32_16x16x32_bf16 v[14:17], v[196:199], v[166:169], v[14:17]
	v_mfma_f32_16x16x32_bf16 v[10:13], v[196:199], v[170:173], v[10:13]
	v_mfma_f32_16x16x32_bf16 v[6:9], v[196:199], v[176:179], v[6:9]
	v_mfma_f32_16x16x32_bf16 v[2:5], v[196:199], v[180:183], v[2:5]
	s_mov_b32 s14, s1
	s_add_i32 s1, s1, 0x6000
	s_cmp_eq_u32 s1, 0x12000
	s_cselect_b32 s1, 0, s1
	s_mov_b32 s4, 0x8000
	s_mov_b32 s5, 0
	s_mov_b32 s10, 0x10000
	s_mov_b32 s11, 0
	s_mov_b32 s41, 0x3fd744fd
	s_waitcnt lgkmcnt(0)
; DEVI float blo(unsigned u) { return __uint_as_float(u << 16); }
; DEVI float bhi(unsigned u) { return __uint_as_float(u & 0xffff0000u); }
;     ...
;         acc[nf][mf] = __builtin_amdgcn_mfma_f32_16x16x32_bf16(wb[nf], xa[mf], acc[nf][mf], 0, 0, 0);
;     ...
;         if (EPI == EPI_RESID || EPI == EPI_RESID_ATOMIC) {
;           f32x4 x = a;
;           if (EPI == EPI_RESID || kpart == 0) {
;             const u32x2 xr = *(const u32x2*)((const u16*)(p.ws + WS_XB) + (size_t)row * 1024 + col);
;             x[0] += ALPHA * blo(xr[0]); x[1] += ALPHA * bhi(xr[0]); x[2] += ALPHA * blo(xr[1]); x[3] += ALPHA * bhi(xr[1]);
;           }
;           if (EPI == EPI_RESID) *(f32x4*)((float*)(p.ws + WS_XF) + (size_t)row * 1024 + col) = x;
;           else *(f32x4*)((float*)(p.ws + WS_SLAB) + ((size_t)kpart * 512 + (row - T_P)) * 1024 + col) = x;
	v_mfma_f32_16x16x32_bf16 v[126:129], v[232:235], v[200:203], v[126:129]
	v_mfma_f32_16x16x32_bf16 v[122:125], v[232:235], v[204:207], v[122:125]
	v_mfma_f32_16x16x32_bf16 v[118:121], v[232:235], v[208:211], v[118:121]
	v_mfma_f32_16x16x32_bf16 v[114:117], v[232:235], v[212:215], v[114:117]
	v_mfma_f32_16x16x32_bf16 v[110:113], v[232:235], v[216:219], v[110:113]
	v_mfma_f32_16x16x32_bf16 v[106:109], v[232:235], v[220:223], v[106:109]
	v_mfma_f32_16x16x32_bf16 v[102:105], v[232:235], v[224:227], v[102:105]
	v_mfma_f32_16x16x32_bf16 v[98:101], v[232:235], v[228:231], v[98:101]
	v_mfma_f32_16x16x32_bf16 v[94:97], v[236:239], v[200:203], v[94:97]
	v_mfma_f32_16x16x32_bf16 v[90:93], v[236:239], v[204:207], v[90:93]
	v_mfma_f32_16x16x32_bf16 v[86:89], v[236:239], v[208:211], v[86:89]
	v_mfma_f32_16x16x32_bf16 v[82:85], v[236:239], v[212:215], v[82:85]
	v_mfma_f32_16x16x32_bf16 v[78:81], v[236:239], v[216:219], v[78:81]
	v_mfma_f32_16x16x32_bf16 v[74:77], v[236:239], v[220:223], v[74:77]
	v_mfma_f32_16x16x32_bf16 v[70:73], v[236:239], v[224:227], v[70:73]
	v_mfma_f32_16x16x32_bf16 v[66:69], v[236:239], v[228:231], v[66:69]
	v_mfma_f32_16x16x32_bf16 v[62:65], v[240:243], v[200:203], v[62:65]
	v_mfma_f32_16x16x32_bf16 v[58:61], v[240:243], v[204:207], v[58:61]
	v_mfma_f32_16x16x32_bf16 v[54:57], v[240:243], v[208:211], v[54:57]
	v_mfma_f32_16x16x32_bf16 v[50:53], v[240:243], v[212:215], v[50:53]
	v_mfma_f32_16x16x32_bf16 v[46:49], v[240:243], v[216:219], v[46:49]
	v_mfma_f32_16x16x32_bf16 v[42:45], v[240:243], v[220:223], v[42:45]
	v_mfma_f32_16x16x32_bf16 v[38:41], v[240:243], v[224:227], v[38:41]
	v_mfma_f32_16x16x32_bf16 v[34:37], v[240:243], v[228:231], v[34:37]
	v_mfma_f32_16x16x32_bf16 v[30:33], v[244:247], v[200:203], v[30:33]
	v_mfma_f32_16x16x32_bf16 v[26:29], v[244:247], v[204:207], v[26:29]
	v_mfma_f32_16x16x32_bf16 v[22:25], v[244:247], v[208:211], v[22:25]
	v_mfma_f32_16x16x32_bf16 v[18:21], v[244:247], v[212:215], v[18:21]
	v_mfma_f32_16x16x32_bf16 v[14:17], v[244:247], v[216:219], v[14:17]
	v_mfma_f32_16x16x32_bf16 v[10:13], v[244:247], v[220:223], v[10:13]
	v_mfma_f32_16x16x32_bf16 v[6:9], v[244:247], v[224:227], v[6:9]
	v_mfma_f32_16x16x32_bf16 v[2:5], v[244:247], v[228:231], v[2:5]
	s_mov_b32 m0, s40
	s_cmp_eq_u32 s98, 0
	s_cbranch_scc1 .Lta4_first
	s_nop 7
	global_store_dwordx4 v[140:141], v[126:129], off offset:0
	global_store_dwordx4 v[140:141], v[94:97], off offset:64
	global_store_dwordx4 v[140:141], v[62:65], off offset:128
	global_store_dwordx4 v[140:141], v[30:33], off offset:192
	v_lshl_add_u64 v[140:141], v[140:141], 0, s[10:11]
	global_store_dwordx4 v[140:141], v[122:125], off offset:0
	global_store_dwordx4 v[140:141], v[90:93], off offset:64
	global_store_dwordx4 v[140:141], v[58:61], off offset:128
	global_store_dwordx4 v[140:141], v[26:29], off offset:192
	v_lshl_add_u64 v[140:141], v[140:141], 0, s[10:11]
	global_store_dwordx4 v[140:141], v[118:121], off offset:0
	global_store_dwordx4 v[140:141], v[86:89], off offset:64
	global_store_dwordx4 v[140:141], v[54:57], off offset:128
	global_store_dwordx4 v[140:141], v[22:25], off offset:192
	v_lshl_add_u64 v[140:141], v[140:141], 0, s[10:11]
	global_store_dwordx4 v[140:141], v[114:117], off offset:0
	global_store_dwordx4 v[140:141], v[82:85], off offset:64
	global_store_dwordx4 v[140:141], v[50:53], off offset:128
	global_store_dwordx4 v[140:141], v[18:21], off offset:192
	v_lshl_add_u64 v[140:141], v[140:141], 0, s[10:11]
	global_store_dwordx4 v[140:141], v[110:113], off offset:0
	global_store_dwordx4 v[140:141], v[78:81], off offset:64
	global_store_dwordx4 v[140:141], v[46:49], off offset:128
	global_store_dwordx4 v[140:141], v[14:17], off offset:192
	v_lshl_add_u64 v[140:141], v[140:141], 0, s[10:11]
	global_store_dwordx4 v[140:141], v[106:109], off offset:0
	global_store_dwordx4 v[140:141], v[74:77], off offset:64
	global_store_dwordx4 v[140:141], v[42:45], off offset:128
	global_store_dwordx4 v[140:141], v[10:13], off offset:192
	v_lshl_add_u64 v[140:141], v[140:141], 0, s[10:11]
	global_store_dwordx4 v[140:141], v[102:105], off offset:0
	global_store_dwordx4 v[140:141], v[70:73], off offset:64
	global_store_dwordx4 v[140:141], v[38:41], off offset:128
	global_store_dwordx4 v[140:141], v[6:9], off offset:192
	v_lshl_add_u64 v[140:141], v[140:141], 0, s[10:11]
	global_store_dwordx4 v[140:141], v[98:101], off offset:0
	global_store_dwordx4 v[140:141], v[66:69], off offset:64
	global_store_dwordx4 v[140:141], v[34:37], off offset:128
	global_store_dwordx4 v[140:141], v[2:5], off offset:192
	s_branch .LBB0_757
; DEVI float blo(unsigned u) { return __uint_as_float(u << 16); }
; DEVI float bhi(unsigned u) { return __uint_as_float(u & 0xffff0000u); }
;     ...
;           if (EPI == EPI_RESID || kpart == 0) {
;             const u32x2 xr = *(const u32x2*)((const u16*)(p.ws + WS_XB) + (size_t)row * 1024 + col);
;             x[0] += ALPHA * blo(xr[0]); x[1] += ALPHA * bhi(xr[0]); x[2] += ALPHA * blo(xr[1]); x[3] += ALPHA * bhi(xr[1]);
;           }
;           if (EPI == EPI_RESID) *(f32x4*)((float*)(p.ws + WS_XF) + (size_t)row * 1024 + col) = x;
;           else *(f32x4*)((float*)(p.ws + WS_SLAB) + ((size_t)kpart * 512 + (row - T_P)) * 1024 + col) = x;
.Lta4_first:
	global_load_dwordx4 v[146:149], v[138:139], off offset:0
	global_load_dwordx4 v[152:155], v[138:139], off offset:64
	v_lshl_add_u64 v[138:139], v[138:139], 0, s[4:5]
	global_load_dwordx4 v[156:159], v[138:139], off offset:0
	global_load_dwordx4 v[162:165], v[138:139], off offset:64
	v_lshl_add_u64 v[138:139], v[138:139], 0, s[4:5]
	global_load_dwordx4 v[166:169], v[138:139], off offset:0
	global_load_dwordx4 v[170:173], v[138:139], off offset:64
	v_lshl_add_u64 v[138:139], v[138:139], 0, s[4:5]
	global_load_dwordx4 v[176:179], v[138:139], off offset:0
	global_load_dwordx4 v[180:183], v[138:139], off offset:64
	v_lshl_add_u64 v[138:139], v[138:139], 0, s[4:5]
	global_load_dwordx4 v[184:187], v[138:139], off offset:0
	global_load_dwordx4 v[188:191], v[138:139], off offset:64
	v_lshl_add_u64 v[138:139], v[138:139], 0, s[4:5]
	global_load_dwordx4 v[192:195], v[138:139], off offset:0
	global_load_dwordx4 v[196:199], v[138:139], off offset:64
	v_lshl_add_u64 v[138:139], v[138:139], 0, s[4:5]
	global_load_dwordx4 v[200:203], v[138:139], off offset:0
	global_load_dwordx4 v[204:207], v[138:139], off offset:64
	v_lshl_add_u64 v[138:139], v[138:139], 0, s[4:5]
	global_load_dwordx4 v[208:211], v[138:139], off offset:0
	global_load_dwordx4 v[212:215], v[138:139], off offset:64
	v_lshl_add_u64 v[138:139], v[138:139], 0, s[4:5]
	s_nop 7
	s_waitcnt vmcnt(15)
	v_permlane16_swap_b32_e32 v146, v148
	v_permlane16_swap_b32_e32 v147, v149
	v_lshlrev_b32_e32 v216, 16, v146
	v_and_b32_e32 v146, 0xffff0000, v146
	v_lshlrev_b32_e32 v217, 16, v147
	v_and_b32_e32 v147, 0xffff0000, v147
	v_fmac_f32_e32 v126, s41, v216
	v_fmac_f32_e32 v127, s41, v146
	v_fmac_f32_e32 v128, s41, v217
	v_fmac_f32_e32 v129, s41, v147
	global_store_dwordx4 v[140:141], v[126:129], off offset:0
	v_lshlrev_b32_e32 v216, 16, v148
	v_and_b32_e32 v148, 0xffff0000, v148
	v_lshlrev_b32_e32 v217, 16, v149
	v_and_b32_e32 v149, 0xffff0000, v149
	v_fmac_f32_e32 v94, s41, v216
	v_fmac_f32_e32 v95, s41, v148
	v_fmac_f32_e32 v96, s41, v217
	v_fmac_f32_e32 v97, s41, v149
	global_store_dwordx4 v[140:141], v[94:97], off offset:64
	s_waitcnt vmcnt(16)
	v_permlane16_swap_b32_e32 v152, v154
	v_permlane16_swap_b32_e32 v153, v155
	v_lshlrev_b32_e32 v216, 16, v152
	v_and_b32_e32 v152, 0xffff0000, v152
	v_lshlrev_b32_e32 v217, 16, v153
	v_and_b32_e32 v153, 0xffff0000, v153
	v_fmac_f32_e32 v62, s41, v216
	v_fmac_f32_e32 v63, s41, v152
	v_fmac_f32_e32 v64, s41, v217
	v_fmac_f32_e32 v65, s41, v153
	global_store_dwordx4 v[140:141], v[62:65], off offset:128
	v_lshlrev_b32_e32 v216, 16, v154
	v_and_b32_e32 v154, 0xffff0000, v154
	v_lshlrev_b32_e32 v217, 16, v155
	v_and_b32_e32 v155, 0xffff0000, v155
	v_fmac_f32_e32 v30, s41, v216
	v_fmac_f32_e32 v31, s41, v154
	v_fmac_f32_e32 v32, s41, v217
	v_fmac_f32_e32 v33, s41, v155
	global_store_dwordx4 v[140:141], v[30:33], off offset:192
	v_lshl_add_u64 v[140:141], v[140:141], 0, s[10:11]
	s_waitcnt vmcnt(17)
	v_permlane16_swap_b32_e32 v156, v158
	v_permlane16_swap_b32_e32 v157, v159
	v_lshlrev_b32_e32 v216, 16, v156
	v_and_b32_e32 v156, 0xffff0000, v156
	v_lshlrev_b32_e32 v217, 16, v157
	v_and_b32_e32 v157, 0xffff0000, v157
	v_fmac_f32_e32 v122, s41, v216
	v_fmac_f32_e32 v123, s41, v156
	v_fmac_f32_e32 v124, s41, v217
	v_fmac_f32_e32 v125, s41, v157
	global_store_dwordx4 v[140:141], v[122:125], off offset:0
	v_lshlrev_b32_e32 v216, 16, v158
	v_and_b32_e32 v158, 0xffff0000, v158
	v_lshlrev_b32_e32 v217, 16, v159
	v_and_b32_e32 v159, 0xffff0000, v159
	v_fmac_f32_e32 v90, s41, v216
	v_fmac_f32_e32 v91, s41, v158
	v_fmac_f32_e32 v92, s41, v217
	v_fmac_f32_e32 v93, s41, v159
	global_store_dwordx4 v[140:141], v[90:93], off offset:64
	s_waitcnt vmcnt(18)
	v_permlane16_swap_b32_e32 v162, v164
	v_permlane16_swap_b32_e32 v163, v165
	v_lshlrev_b32_e32 v216, 16, v162
	v_and_b32_e32 v162, 0xffff0000, v162
	v_lshlrev_b32_e32 v217, 16, v163
	v_and_b32_e32 v163, 0xffff0000, v163
	v_fmac_f32_e32 v58, s41, v216
	v_fmac_f32_e32 v59, s41, v162
	v_fmac_f32_e32 v60, s41, v217
	v_fmac_f32_e32 v61, s41, v163
	global_store_dwordx4 v[140:141], v[58:61], off offset:128
	v_lshlrev_b32_e32 v216, 16, v164
	v_and_b32_e32 v164, 0xffff0000, v164
	v_lshlrev_b32_e32 v217, 16, v165
	v_and_b32_e32 v165, 0xffff0000, v165
	v_fmac_f32_e32 v26, s41, v216
	v_fmac_f32_e32 v27, s41, v164
	v_fmac_f32_e32 v28, s41, v217
	v_fmac_f32_e32 v29, s41, v165
	global_store_dwordx4 v[140:141], v[26:29], off offset:192
	v_lshl_add_u64 v[140:141], v[140:141], 0, s[10:11]
	s_waitcnt vmcnt(19)
	v_permlane16_swap_b32_e32 v166, v168
	v_permlane16_swap_b32_e32 v167, v169
	v_lshlrev_b32_e32 v216, 16, v166
	v_and_b32_e32 v166, 0xffff0000, v166
	v_lshlrev_b32_e32 v217, 16, v167
	v_and_b32_e32 v167, 0xffff0000, v167
	v_fmac_f32_e32 v118, s41, v216
	v_fmac_f32_e32 v119, s41, v166
	v_fmac_f32_e32 v120, s41, v217
	v_fmac_f32_e32 v121, s41, v167
	global_store_dwordx4 v[140:141], v[118:121], off offset:0
	v_lshlrev_b32_e32 v216, 16, v168
	v_and_b32_e32 v168, 0xffff0000, v168
	v_lshlrev_b32_e32 v217, 16, v169
	v_and_b32_e32 v169, 0xffff0000, v169
	v_fmac_f32_e32 v86, s41, v216
	v_fmac_f32_e32 v87, s41, v168
	v_fmac_f32_e32 v88, s41, v217
	v_fmac_f32_e32 v89, s41, v169
	global_store_dwordx4 v[140:141], v[86:89], off offset:64
	s_waitcnt vmcnt(20)
; DEVI float blo(unsigned u) { return __uint_as_float(u << 16); }
; DEVI float bhi(unsigned u) { return __uint_as_float(u & 0xffff0000u); }
;     ...
;           if (EPI == EPI_RESID || kpart == 0) {
;             const u32x2 xr = *(const u32x2*)((const u16*)(p.ws + WS_XB) + (size_t)row * 1024 + col);
;             x[0] += ALPHA * blo(xr[0]); x[1] += ALPHA * bhi(xr[0]); x[2] += ALPHA * blo(xr[1]); x[3] += ALPHA * bhi(xr[1]);
;           }
;           if (EPI == EPI_RESID) *(f32x4*)((float*)(p.ws + WS_XF) + (size_t)row * 1024 + col) = x;
;           else *(f32x4*)((float*)(p.ws + WS_SLAB) + ((size_t)kpart * 512 + (row - T_P)) * 1024 + col) = x;
	v_permlane16_swap_b32_e32 v170, v172
	v_permlane16_swap_b32_e32 v171, v173
	v_lshlrev_b32_e32 v216, 16, v170
	v_and_b32_e32 v170, 0xffff0000, v170
	v_lshlrev_b32_e32 v217, 16, v171
	v_and_b32_e32 v171, 0xffff0000, v171
	v_fmac_f32_e32 v54, s41, v216
	v_fmac_f32_e32 v55, s41, v170
	v_fmac_f32_e32 v56, s41, v217
	v_fmac_f32_e32 v57, s41, v171
	global_store_dwordx4 v[140:141], v[54:57], off offset:128
	v_lshlrev_b32_e32 v216, 16, v172
	v_and_b32_e32 v172, 0xffff0000, v172
	v_lshlrev_b32_e32 v217, 16, v173
	v_and_b32_e32 v173, 0xffff0000, v173
	v_fmac_f32_e32 v22, s41, v216
	v_fmac_f32_e32 v23, s41, v172
	v_fmac_f32_e32 v24, s41, v217
	v_fmac_f32_e32 v25, s41, v173
	global_store_dwordx4 v[140:141], v[22:25], off offset:192
	v_lshl_add_u64 v[140:141], v[140:141], 0, s[10:11]
	s_waitcnt vmcnt(21)
	v_permlane16_swap_b32_e32 v176, v178
	v_permlane16_swap_b32_e32 v177, v179
	v_lshlrev_b32_e32 v216, 16, v176
	v_and_b32_e32 v176, 0xffff0000, v176
	v_lshlrev_b32_e32 v217, 16, v177
	v_and_b32_e32 v177, 0xffff0000, v177
	v_fmac_f32_e32 v114, s41, v216
	v_fmac_f32_e32 v115, s41, v176
	v_fmac_f32_e32 v116, s41, v217
	v_fmac_f32_e32 v117, s41, v177
	global_store_dwordx4 v[140:141], v[114:117], off offset:0
	v_lshlrev_b32_e32 v216, 16, v178
	v_and_b32_e32 v178, 0xffff0000, v178
	v_lshlrev_b32_e32 v217, 16, v179
	v_and_b32_e32 v179, 0xffff0000, v179
	v_fmac_f32_e32 v82, s41, v216
	v_fmac_f32_e32 v83, s41, v178
	v_fmac_f32_e32 v84, s41, v217
	v_fmac_f32_e32 v85, s41, v179
	global_store_dwordx4 v[140:141], v[82:85], off offset:64
	s_waitcnt vmcnt(22)
	v_permlane16_swap_b32_e32 v180, v182
	v_permlane16_swap_b32_e32 v181, v183
	v_lshlrev_b32_e32 v216, 16, v180
	v_and_b32_e32 v180, 0xffff0000, v180
	v_lshlrev_b32_e32 v217, 16, v181
	v_and_b32_e32 v181, 0xffff0000, v181
	v_fmac_f32_e32 v50, s41, v216
	v_fmac_f32_e32 v51, s41, v180
	v_fmac_f32_e32 v52, s41, v217
	v_fmac_f32_e32 v53, s41, v181
	global_store_dwordx4 v[140:141], v[50:53], off offset:128
	v_lshlrev_b32_e32 v216, 16, v182
	v_and_b32_e32 v182, 0xffff0000, v182
	v_lshlrev_b32_e32 v217, 16, v183
	v_and_b32_e32 v183, 0xffff0000, v183
	v_fmac_f32_e32 v18, s41, v216
	v_fmac_f32_e32 v19, s41, v182
	v_fmac_f32_e32 v20, s41, v217
	v_fmac_f32_e32 v21, s41, v183
	global_store_dwordx4 v[140:141], v[18:21], off offset:192
	v_lshl_add_u64 v[140:141], v[140:141], 0, s[10:11]
	s_waitcnt vmcnt(23)
	v_permlane16_swap_b32_e32 v184, v186
	v_permlane16_swap_b32_e32 v185, v187
	v_lshlrev_b32_e32 v216, 16, v184
	v_and_b32_e32 v184, 0xffff0000, v184
	v_lshlrev_b32_e32 v217, 16, v185
	v_and_b32_e32 v185, 0xffff0000, v185
	v_fmac_f32_e32 v110, s41, v216
	v_fmac_f32_e32 v111, s41, v184
	v_fmac_f32_e32 v112, s41, v217
	v_fmac_f32_e32 v113, s41, v185
	global_store_dwordx4 v[140:141], v[110:113], off offset:0
	v_lshlrev_b32_e32 v216, 16, v186
	v_and_b32_e32 v186, 0xffff0000, v186
	v_lshlrev_b32_e32 v217, 16, v187
	v_and_b32_e32 v187, 0xffff0000, v187
	v_fmac_f32_e32 v78, s41, v216
	v_fmac_f32_e32 v79, s41, v186
	v_fmac_f32_e32 v80, s41, v217
	v_fmac_f32_e32 v81, s41, v187
	global_store_dwordx4 v[140:141], v[78:81], off offset:64
	s_waitcnt vmcnt(24)
	v_permlane16_swap_b32_e32 v188, v190
	v_permlane16_swap_b32_e32 v189, v191
	v_lshlrev_b32_e32 v216, 16, v188
	v_and_b32_e32 v188, 0xffff0000, v188
	v_lshlrev_b32_e32 v217, 16, v189
	v_and_b32_e32 v189, 0xffff0000, v189
	v_fmac_f32_e32 v46, s41, v216
	v_fmac_f32_e32 v47, s41, v188
	v_fmac_f32_e32 v48, s41, v217
	v_fmac_f32_e32 v49, s41, v189
	global_store_dwordx4 v[140:141], v[46:49], off offset:128
	v_lshlrev_b32_e32 v216, 16, v190
	v_and_b32_e32 v190, 0xffff0000, v190
	v_lshlrev_b32_e32 v217, 16, v191
	v_and_b32_e32 v191, 0xffff0000, v191
	v_fmac_f32_e32 v14, s41, v216
	v_fmac_f32_e32 v15, s41, v190
	v_fmac_f32_e32 v16, s41, v217
	v_fmac_f32_e32 v17, s41, v191
	global_store_dwordx4 v[140:141], v[14:17], off offset:192
	v_lshl_add_u64 v[140:141], v[140:141], 0, s[10:11]
	s_waitcnt vmcnt(25)
	v_permlane16_swap_b32_e32 v192, v194
	v_permlane16_swap_b32_e32 v193, v195
	v_lshlrev_b32_e32 v216, 16, v192
	v_and_b32_e32 v192, 0xffff0000, v192
	v_lshlrev_b32_e32 v217, 16, v193
	v_and_b32_e32 v193, 0xffff0000, v193
	v_fmac_f32_e32 v106, s41, v216
	v_fmac_f32_e32 v107, s41, v192
	v_fmac_f32_e32 v108, s41, v217
	v_fmac_f32_e32 v109, s41, v193
	global_store_dwordx4 v[140:141], v[106:109], off offset:0
	v_lshlrev_b32_e32 v216, 16, v194
	v_and_b32_e32 v194, 0xffff0000, v194
	v_lshlrev_b32_e32 v217, 16, v195
	v_and_b32_e32 v195, 0xffff0000, v195
	v_fmac_f32_e32 v74, s41, v216
	v_fmac_f32_e32 v75, s41, v194
	v_fmac_f32_e32 v76, s41, v217
	v_fmac_f32_e32 v77, s41, v195
	global_store_dwordx4 v[140:141], v[74:77], off offset:64
	s_waitcnt vmcnt(26)
	v_permlane16_swap_b32_e32 v196, v198
	v_permlane16_swap_b32_e32 v197, v199
	v_lshlrev_b32_e32 v216, 16, v196
	v_and_b32_e32 v196, 0xffff0000, v196
	v_lshlrev_b32_e32 v217, 16, v197
	v_and_b32_e32 v197, 0xffff0000, v197
	v_fmac_f32_e32 v42, s41, v216
	v_fmac_f32_e32 v43, s41, v196
	v_fmac_f32_e32 v44, s41, v217
	v_fmac_f32_e32 v45, s41, v197
	global_store_dwordx4 v[140:141], v[42:45], off offset:128
	v_lshlrev_b32_e32 v216, 16, v198
	v_and_b32_e32 v198, 0xffff0000, v198
	v_lshlrev_b32_e32 v217, 16, v199
	v_and_b32_e32 v199, 0xffff0000, v199
	v_fmac_f32_e32 v10, s41, v216
	v_fmac_f32_e32 v11, s41, v198
	v_fmac_f32_e32 v12, s41, v217
	v_fmac_f32_e32 v13, s41, v199
	global_store_dwordx4 v[140:141], v[10:13], off offset:192
	v_lshl_add_u64 v[140:141], v[140:141], 0, s[10:11]
	s_waitcnt vmcnt(27)
; DEVI float blo(unsigned u) { return __uint_as_float(u << 16); }
; DEVI float bhi(unsigned u) { return __uint_as_float(u & 0xffff0000u); }
; DEVI int xcd_first_tile() { return (blockIdx.x & 7) * (gridDim.x >> 3) + (blockIdx.x >> 3); }
;     ...
;           if (EPI == EPI_RESID || kpart == 0) {
;             const u32x2 xr = *(const u32x2*)((const u16*)(p.ws + WS_XB) + (size_t)row * 1024 + col);
;             x[0] += ALPHA * blo(xr[0]); x[1] += ALPHA * bhi(xr[0]); x[2] += ALPHA * blo(xr[1]); x[3] += ALPHA * bhi(xr[1]);
;           }
;           if (EPI == EPI_RESID) *(f32x4*)((float*)(p.ws + WS_XF) + (size_t)row * 1024 + col) = x;
;           else *(f32x4*)((float*)(p.ws + WS_SLAB) + ((size_t)kpart * 512 + (row - T_P)) * 1024 + col) = x;
; DEVI void run_phase(const Params& p, int ph, char* smem) {
;     ...
;       for (int t = xcd_first_tile(); t < 512 + 16 * 8; t += xcd_tile_step()) {
;         if (t < 512) {
;           int mt_, nt_; tile_coords(t, 64, 8, mt_, nt_);
;           gemm_tile256<EPI_RESID>(p, mix, 1024, Bt, 1024, mt_ * 256, nt_ * 128, nullptr, 0, smem);
	v_permlane16_swap_b32_e32 v200, v202
	v_permlane16_swap_b32_e32 v201, v203
	v_lshlrev_b32_e32 v216, 16, v200
	v_and_b32_e32 v200, 0xffff0000, v200
	v_lshlrev_b32_e32 v217, 16, v201
	v_and_b32_e32 v201, 0xffff0000, v201
	v_fmac_f32_e32 v102, s41, v216
	v_fmac_f32_e32 v103, s41, v200
	v_fmac_f32_e32 v104, s41, v217
	v_fmac_f32_e32 v105, s41, v201
	global_store_dwordx4 v[140:141], v[102:105], off offset:0
	v_lshlrev_b32_e32 v216, 16, v202
	v_and_b32_e32 v202, 0xffff0000, v202
	v_lshlrev_b32_e32 v217, 16, v203
	v_and_b32_e32 v203, 0xffff0000, v203
	v_fmac_f32_e32 v70, s41, v216
	v_fmac_f32_e32 v71, s41, v202
	v_fmac_f32_e32 v72, s41, v217
	v_fmac_f32_e32 v73, s41, v203
	global_store_dwordx4 v[140:141], v[70:73], off offset:64
	s_waitcnt vmcnt(28)
	v_permlane16_swap_b32_e32 v204, v206
	v_permlane16_swap_b32_e32 v205, v207
	v_lshlrev_b32_e32 v216, 16, v204
	v_and_b32_e32 v204, 0xffff0000, v204
	v_lshlrev_b32_e32 v217, 16, v205
	v_and_b32_e32 v205, 0xffff0000, v205
	v_fmac_f32_e32 v38, s41, v216
	v_fmac_f32_e32 v39, s41, v204
	v_fmac_f32_e32 v40, s41, v217
	v_fmac_f32_e32 v41, s41, v205
	global_store_dwordx4 v[140:141], v[38:41], off offset:128
	v_lshlrev_b32_e32 v216, 16, v206
	v_and_b32_e32 v206, 0xffff0000, v206
	v_lshlrev_b32_e32 v217, 16, v207
	v_and_b32_e32 v207, 0xffff0000, v207
	v_fmac_f32_e32 v6, s41, v216
	v_fmac_f32_e32 v7, s41, v206
	v_fmac_f32_e32 v8, s41, v217
	v_fmac_f32_e32 v9, s41, v207
	global_store_dwordx4 v[140:141], v[6:9], off offset:192
	v_lshl_add_u64 v[140:141], v[140:141], 0, s[10:11]
	s_waitcnt vmcnt(29)
	v_permlane16_swap_b32_e32 v208, v210
	v_permlane16_swap_b32_e32 v209, v211
	v_lshlrev_b32_e32 v216, 16, v208
	v_and_b32_e32 v208, 0xffff0000, v208
	v_lshlrev_b32_e32 v217, 16, v209
	v_and_b32_e32 v209, 0xffff0000, v209
	v_fmac_f32_e32 v98, s41, v216
	v_fmac_f32_e32 v99, s41, v208
	v_fmac_f32_e32 v100, s41, v217
	v_fmac_f32_e32 v101, s41, v209
	global_store_dwordx4 v[140:141], v[98:101], off offset:0
	v_lshlrev_b32_e32 v216, 16, v210
	v_and_b32_e32 v210, 0xffff0000, v210
	v_lshlrev_b32_e32 v217, 16, v211
	v_and_b32_e32 v211, 0xffff0000, v211
	v_fmac_f32_e32 v66, s41, v216
	v_fmac_f32_e32 v67, s41, v210
	v_fmac_f32_e32 v68, s41, v217
	v_fmac_f32_e32 v69, s41, v211
	global_store_dwordx4 v[140:141], v[66:69], off offset:64
	s_waitcnt vmcnt(30)
	v_permlane16_swap_b32_e32 v212, v214
	v_permlane16_swap_b32_e32 v213, v215
	v_lshlrev_b32_e32 v216, 16, v212
	v_and_b32_e32 v212, 0xffff0000, v212
	v_lshlrev_b32_e32 v217, 16, v213
	v_and_b32_e32 v213, 0xffff0000, v213
	v_fmac_f32_e32 v34, s41, v216
	v_fmac_f32_e32 v35, s41, v212
	v_fmac_f32_e32 v36, s41, v217
	v_fmac_f32_e32 v37, s41, v213
	global_store_dwordx4 v[140:141], v[34:37], off offset:128
	v_lshlrev_b32_e32 v216, 16, v214
	v_and_b32_e32 v214, 0xffff0000, v214
	v_lshlrev_b32_e32 v217, 16, v215
	v_and_b32_e32 v215, 0xffff0000, v215
	v_fmac_f32_e32 v2, s41, v216
	v_fmac_f32_e32 v3, s41, v214
	v_fmac_f32_e32 v4, s41, v217
	v_fmac_f32_e32 v5, s41, v215
	global_store_dwordx4 v[140:141], v[2:5], off offset:192
	s_branch .LBB0_757
.LBB0_812:
	s_and_b64 vcc, exec, s[2:3]
	s_cbranch_vccz .LBB0_757
	s_lshr_b32 s46, s39, 6
	s_and_b32 s47, s39, 63
	s_lshr_b32 s43, s47, 3
	s_and_b32 s47, s47, 7
	s_lshl_b32 s46, s46, 3
	s_add_i32 s46, s46, s47
	v_readlane_b32 s2, v250, 5
	v_readlane_b32 s3, v250, 6
	v_readlane_b32 s47, v254, 62
	s_mul_i32 s41, s46, 0x80000
	s_add_u32 s4, s2, s41
	s_addc_u32 s5, s3, 0
	s_add_u32 s4, s4, 0xb580000
	s_addc_u32 s5, s5, 0
	s_mul_i32 s41, s47, 0x200000
	s_mul_i32 s42, s43, 0x40000
	s_add_i32 s41, s41, s42
	s_add_u32 s10, s2, s41
	s_addc_u32 s11, s3, 0
	s_add_u32 s10, s10, 0x15e00000
	s_addc_u32 s11, s11, 0
	s_movk_i32 s40, 0x78
	v_lshrrev_b32_e32 v0, 2, v145
	v_and_b32_e32 v131, 3, v145
	v_bfe_u32 v136, v145, 4, 2
	v_lshlrev_b32_e32 v136, 1, v136
	v_lshrrev_b32_e64 v136, v136, s40
	v_and_b32_e32 v136, 3, v136
	v_xor_b32_e32 v131, v131, v136
	v_lshlrev_b32_e32 v131, 4, v131
	s_movk_i32 s42, 0x800
	v_mad_u32_u24 v0, v0, s42, v131
	v_bfe_u32 v137, v145, 2, 1
	s_movk_i32 s42, 0x7c0
	v_mul_u32_u24_e32 v136, s42, v137
	v_sub_u32_e32 v136, v0, v136
	v_mov_b32_e32 v137, 0
	v_lshl_add_u64 v[134:135], s[10:11], 0, v[136:137]
	v_bfe_u32 v137, v145, 2, 1
	s_mov_b32 s12, 64
	s_mov_b32 s13, 0
	v_lshl_add_u64 v[132:133], s[4:5], 0, v[0:1]
	v_bfe_u32 v136, v145, 2, 2
	v_lshlrev_b32_e32 v136, 1, v136
	v_lshrrev_b32_e64 v136, v136, s40
	v_and_b32_e32 v136, 3, v136
	v_bfe_u32 v137, v145, 4, 2
	v_xor_b32_e32 v136, v136, v137
	v_lshlrev_b32_e32 v136, 4, v136
	v_and_b32_e32 v131, 15, v145
	v_lshl_or_b32 v136, v131, 6, v136
	v_bfe_u32 v137, v145, 6, 1
	v_lshl_or_b32 v137, v137, 12, v136
	v_lshrrev_b32_e32 v0, 7, v145
	v_lshl_or_b32 v136, v0, 13, v136
	v_and_b32_e32 v140, 1, v131
	v_lshl_or_b32 v131, v0, 7, v131
	v_bfe_u32 v0, v145, 4, 2
	v_lshlrev_b32_e32 v0, 3, v0
	v_bfe_u32 v141, v145, 6, 1
	s_lshl_b32 s41, s46, 19
	s_lshl_b32 s42, s43, 9
	s_add_i32 s41, s41, s42
	s_add_u32 s4, s2, s41
	s_addc_u32 s5, s3, 0
	s_add_u32 s4, s4, 0x4200000
	s_addc_u32 s5, s5, 0
	v_lshlrev_b32_e32 v138, 11, v131
	v_lshl_add_u32 v138, v141, 8, v138
	v_bfe_u32 v139, v145, 4, 1
	v_lshl_add_u32 v138, v139, 5, v138
	v_bfe_u32 v139, v145, 5, 1
	v_lshl_add_u32 v138, v139, 4, v138
	s_movk_i32 s42, 1984
	v_mul_u32_u24_e32 v139, s42, v140
	v_sub_u32_e32 v138, v138, v139
	v_mov_b32_e32 v139, 0
	v_lshl_add_u64 v[138:139], s[4:5], 0, v[138:139]
	s_lshl_b32 s41, s46, 20
	s_lshl_b32 s42, s43, 9
	s_add_i32 s41, s41, s42
	s_add_u32 s10, s2, s41
	s_addc_u32 s11, s3, 0
	v_lshlrev_b32_e32 v140, 12, v131
	v_lshl_add_u32 v140, v141, 8, v140
	v_lshl_add_u32 v140, v0, 1, v140
	v_mov_b32_e32 v141, 0
; #define LAS __attribute__((address_space(3)))
;     ...
;   f32x4 acc[4][8];
; #pragma unroll
;   for (int i = 0; i < 4; i++)
; #pragma unroll
;     for (int j = 0; j < 8; j++) acc[i][j] = (f32x4){0.f, 0.f, 0.f, 0.f};
;   const int nk = (nk_part < 0) ? (K >> 5) : nk_part;
;   const int lrow = tid >> 2, lpc = tid & 3;
;   const int lch = lpc ^ ((0x78 >> (((lrow >> 2) & 3) * 2)) & 3);
;   const u16* ga = A + (size_t)(m0 + lrow) * lda + kbeg + lch * 8;
;   const u16* gb = Bt + (size_t)(n0 + lrow) * K + kbeg + lch * 8;
;   const size_t ga1 = (size_t)64 * lda, gb1 = (size_t)64 * K;
;   const unsigned lds0 = (unsigned)(uintptr_t)(LAS char*)smem + (unsigned)__builtin_amdgcn_readfirstlane(wid) * 1024u;
;     ...
;   __syncthreads();
;   G2_STAGE(0); G2_STAGE(1);
;   const int fsw = (0x78 >> (((r16 >> 2) & 3) * 2)) & 3;
;   const int aoff = (wm * 128 + r16) * 64 + ((quad ^ fsw) << 4);
;   const int boff = 16384 + (wn * 64 + r16) * 64 + ((quad ^ fsw) << 4);
;     ...
;     for (int f = 0; f < 8; f++) xa[f] = *(const bf16x8*)(cS + aoff + f * 1024);
; #pragma unroll
;     for (int f = 0; f < 4; f++) wb[f] = *(const bf16x8*)(cS + boff + f * 1024);
	v_lshl_add_u64 v[140:141], s[10:11], 0, v[140:141]
	s_mov_b32 s2, 0x20000
	s_mov_b32 s3, 0
	v_lshrrev_b32_e32 v0, 6, v145
	v_lshlrev_b32_e32 v0, 10, v0
	s_nop 0
	v_readfirstlane_b32 s47, v0
	s_mov_b32 s44, m0
	s_mov_b32 s4, 128
	s_mov_b32 s5, 0
	v_mov_b32_e32 v2, 0
	v_mov_b32_e32 v3, 0
	v_mov_b32_e32 v4, 0
	v_mov_b32_e32 v5, 0
	v_mov_b32_e32 v6, 0
	v_mov_b32_e32 v7, 0
	v_mov_b32_e32 v8, 0
	v_mov_b32_e32 v9, 0
	v_mov_b32_e32 v10, 0
	v_mov_b32_e32 v11, 0
	v_mov_b32_e32 v12, 0
	v_mov_b32_e32 v13, 0
	v_mov_b32_e32 v14, 0
	v_mov_b32_e32 v15, 0
	v_mov_b32_e32 v16, 0
	v_mov_b32_e32 v17, 0
	v_mov_b32_e32 v18, 0
	v_mov_b32_e32 v19, 0
	v_mov_b32_e32 v20, 0
	v_mov_b32_e32 v21, 0
	v_mov_b32_e32 v22, 0
	v_mov_b32_e32 v23, 0
	v_mov_b32_e32 v24, 0
	v_mov_b32_e32 v25, 0
	v_mov_b32_e32 v26, 0
	v_mov_b32_e32 v27, 0
	v_mov_b32_e32 v28, 0
	v_mov_b32_e32 v29, 0
	v_mov_b32_e32 v30, 0
	v_mov_b32_e32 v31, 0
	v_mov_b32_e32 v32, 0
	v_mov_b32_e32 v33, 0
	v_mov_b32_e32 v34, 0
	v_mov_b32_e32 v35, 0
	v_mov_b32_e32 v36, 0
	v_mov_b32_e32 v37, 0
	v_mov_b32_e32 v38, 0
	v_mov_b32_e32 v39, 0
	v_mov_b32_e32 v40, 0
	v_mov_b32_e32 v41, 0
	v_mov_b32_e32 v42, 0
	v_mov_b32_e32 v43, 0
	v_mov_b32_e32 v44, 0
	v_mov_b32_e32 v45, 0
	v_mov_b32_e32 v46, 0
	v_mov_b32_e32 v47, 0
	v_mov_b32_e32 v48, 0
	v_mov_b32_e32 v49, 0
	v_mov_b32_e32 v50, 0
	v_mov_b32_e32 v51, 0
	v_mov_b32_e32 v52, 0
	v_mov_b32_e32 v53, 0
	v_mov_b32_e32 v54, 0
	v_mov_b32_e32 v55, 0
	v_mov_b32_e32 v56, 0
	v_mov_b32_e32 v57, 0
	v_mov_b32_e32 v58, 0
	v_mov_b32_e32 v59, 0
	v_mov_b32_e32 v60, 0
	v_mov_b32_e32 v61, 0
	v_mov_b32_e32 v62, 0
	v_mov_b32_e32 v63, 0
	v_mov_b32_e32 v64, 0
	v_mov_b32_e32 v65, 0
	v_mov_b32_e32 v66, 0
	v_mov_b32_e32 v67, 0
	v_mov_b32_e32 v68, 0
	v_mov_b32_e32 v69, 0
	v_mov_b32_e32 v70, 0
	v_mov_b32_e32 v71, 0
	v_mov_b32_e32 v72, 0
	v_mov_b32_e32 v73, 0
	v_mov_b32_e32 v74, 0
	v_mov_b32_e32 v75, 0
	v_mov_b32_e32 v76, 0
	v_mov_b32_e32 v77, 0
	v_mov_b32_e32 v78, 0
	v_mov_b32_e32 v79, 0
	v_mov_b32_e32 v80, 0
	v_mov_b32_e32 v81, 0
	v_mov_b32_e32 v82, 0
	v_mov_b32_e32 v83, 0
	v_mov_b32_e32 v84, 0
	v_mov_b32_e32 v85, 0
	v_mov_b32_e32 v86, 0
	v_mov_b32_e32 v87, 0
	v_mov_b32_e32 v88, 0
	v_mov_b32_e32 v89, 0
	v_mov_b32_e32 v90, 0
	v_mov_b32_e32 v91, 0
	v_mov_b32_e32 v92, 0
	v_mov_b32_e32 v93, 0
	v_mov_b32_e32 v94, 0
	v_mov_b32_e32 v95, 0
	v_mov_b32_e32 v96, 0
	v_mov_b32_e32 v97, 0
	v_mov_b32_e32 v98, 0
	v_mov_b32_e32 v99, 0
	v_mov_b32_e32 v100, 0
	v_mov_b32_e32 v101, 0
	v_mov_b32_e32 v102, 0
	v_mov_b32_e32 v103, 0
	v_mov_b32_e32 v104, 0
	v_mov_b32_e32 v105, 0
	v_mov_b32_e32 v106, 0
	v_mov_b32_e32 v107, 0
	v_mov_b32_e32 v108, 0
	v_mov_b32_e32 v109, 0
	v_mov_b32_e32 v110, 0
	v_mov_b32_e32 v111, 0
	v_mov_b32_e32 v112, 0
	v_mov_b32_e32 v113, 0
	v_mov_b32_e32 v114, 0
	v_mov_b32_e32 v115, 0
	v_mov_b32_e32 v116, 0
	v_mov_b32_e32 v117, 0
	v_mov_b32_e32 v118, 0
	v_mov_b32_e32 v119, 0
	v_mov_b32_e32 v120, 0
	v_mov_b32_e32 v121, 0
	v_mov_b32_e32 v122, 0
	v_mov_b32_e32 v123, 0
	v_mov_b32_e32 v124, 0
	v_mov_b32_e32 v125, 0
	v_mov_b32_e32 v126, 0
	v_mov_b32_e32 v127, 0
	v_mov_b32_e32 v128, 0
	v_mov_b32_e32 v129, 0
	s_barrier
	s_add_i32 s43, s47, 0x0
	s_mov_b32 m0, s43
	v_lshl_add_u64 v[142:143], v[132:133], 0, s[2:3]
	global_load_lds_dwordx4 v[132:133], off
	s_addk_i32 m0, 0x1000
	s_nop 0
	global_load_lds_dwordx4 v[142:143], off
	v_lshl_add_u64 v[142:143], v[142:143], 0, s[2:3]
	s_addk_i32 m0, 0x1000
	s_nop 0
	global_load_lds_dwordx4 v[142:143], off
	v_lshl_add_u64 v[142:143], v[142:143], 0, s[2:3]
	s_addk_i32 m0, 0x1000
	s_nop 0
	global_load_lds_dwordx4 v[142:143], off
	s_addk_i32 m0, 0x1000
	v_lshl_add_u64 v[142:143], v[134:135], 0, s[2:3]
	s_nop 0
	global_load_lds_dwordx4 v[134:135], off
	s_addk_i32 m0, 0x1000
	v_lshl_add_u64 v[132:133], v[132:133], 0, s[12:13]
	s_nop 0
	global_load_lds_dwordx4 v[142:143], off
	v_lshl_add_u64 v[134:135], v[134:135], 0, s[4:5]
	s_nop 0
	s_add_i32 s43, s47, 0x6000
	s_mov_b32 m0, s43
	v_lshl_add_u64 v[142:143], v[132:133], 0, s[2:3]
	global_load_lds_dwordx4 v[132:133], off
	s_addk_i32 m0, 0x1000
	s_nop 0
	global_load_lds_dwordx4 v[142:143], off
	v_lshl_add_u64 v[142:143], v[142:143], 0, s[2:3]
	s_addk_i32 m0, 0x1000
	s_nop 0
	global_load_lds_dwordx4 v[142:143], off
	v_lshl_add_u64 v[142:143], v[142:143], 0, s[2:3]
	s_addk_i32 m0, 0x1000
	s_nop 0
	global_load_lds_dwordx4 v[142:143], off
	s_addk_i32 m0, 0x1000
	v_lshl_add_u64 v[142:143], v[134:135], 0, s[2:3]
	s_nop 0
	global_load_lds_dwordx4 v[134:135], off
	s_addk_i32 m0, 0x1000
	v_lshl_add_u64 v[132:133], v[132:133], 0, s[12:13]
	s_nop 0
	global_load_lds_dwordx4 v[142:143], off
	v_lshl_add_u64 v[134:135], v[134:135], 0, s[4:5]
	s_nop 0
	s_add_i32 s43, s47, 0xc000
	s_mov_b32 m0, s43
	v_lshl_add_u64 v[142:143], v[132:133], 0, s[2:3]
	global_load_lds_dwordx4 v[132:133], off
	s_addk_i32 m0, 0x1000
	s_nop 0
	global_load_lds_dwordx4 v[142:143], off
	v_lshl_add_u64 v[142:143], v[142:143], 0, s[2:3]
	s_addk_i32 m0, 0x1000
	s_nop 0
	global_load_lds_dwordx4 v[142:143], off
	v_lshl_add_u64 v[142:143], v[142:143], 0, s[2:3]
	s_addk_i32 m0, 0x1000
	s_nop 0
	global_load_lds_dwordx4 v[142:143], off
	s_addk_i32 m0, 0x1000
	v_lshl_add_u64 v[142:143], v[134:135], 0, s[2:3]
	s_nop 0
	global_load_lds_dwordx4 v[134:135], off
	s_addk_i32 m0, 0x1000
	v_lshl_add_u64 v[132:133], v[132:133], 0, s[12:13]
	s_nop 0
	global_load_lds_dwordx4 v[142:143], off
	v_lshl_add_u64 v[134:135], v[134:135], 0, s[4:5]
	s_nop 0
	s_waitcnt vmcnt(12)
	s_barrier
	ds_read_b128 v[146:149], v136 offset:0
	ds_read_b128 v[152:155], v136 offset:1024
	ds_read_b128 v[156:159], v136 offset:2048
	ds_read_b128 v[162:165], v136 offset:3072
	ds_read_b128 v[166:169], v136 offset:4096
	ds_read_b128 v[170:173], v136 offset:5120
	ds_read_b128 v[176:179], v136 offset:6144
	ds_read_b128 v[180:183], v136 offset:7168
	ds_read_b128 v[184:187], v137 offset:16384
	ds_read_b128 v[188:191], v137 offset:17408
	ds_read_b128 v[192:195], v137 offset:18432
	ds_read_b128 v[196:199], v137 offset:19456
	s_movk_i32 s41, 0x6000
	s_mov_b32 s42, 0
	s_movk_i32 s40, 14
;     ...
;   for (int kt = 0; kt < nk; kt++) {
;     if (kt + 1 < nk) asm volatile("s_waitcnt vmcnt(6)" ::: "memory");
;     else asm volatile("s_waitcnt vmcnt(0)" ::: "memory");
;     __builtin_amdgcn_s_barrier();
;     asm volatile("" ::: "memory");
;     if (kt + 2 < nk) G2_STAGE(kt + 2);
;     const char* cS = smem + (kt % 3) * 24576;
;     bf16x8 xa[8], wb[4];
; #pragma unroll
;     for (int f = 0; f < 8; f++) xa[f] = *(const bf16x8*)(cS + aoff + f * 1024);
; #pragma unroll
;     for (int f = 0; f < 4; f++) wb[f] = *(const bf16x8*)(cS + boff + f * 1024);
; #pragma unroll
;     for (int nf = 0; nf < 4; nf++)
; #pragma unroll
;       for (int mf = 0; mf < 8; mf++)
;         acc[nf][mf] = __builtin_amdgcn_mfma_f32_16x16x32_bf16(wb[nf], xa[mf], acc[nf][mf], 0, 0, 0);
.Lt4_loop:
	s_waitcnt vmcnt(6) lgkmcnt(0)
	s_barrier
	v_add_u32_e32 v144, s41, v136
	v_mfma_f32_16x16x32_bf16 v[126:129], v[184:187], v[146:149], v[126:129]
	ds_read_b128 v[200:203], v144 offset:0
	v_mfma_f32_16x16x32_bf16 v[122:125], v[184:187], v[152:155], v[122:125]
	ds_read_b128 v[204:207], v144 offset:1024
	v_mfma_f32_16x16x32_bf16 v[118:121], v[184:187], v[156:159], v[118:121]
	ds_read_b128 v[208:211], v144 offset:2048
	v_mfma_f32_16x16x32_bf16 v[114:117], v[184:187], v[162:165], v[114:117]
	ds_read_b128 v[212:215], v144 offset:3072
	v_mfma_f32_16x16x32_bf16 v[110:113], v[184:187], v[166:169], v[110:113]
	ds_read_b128 v[216:219], v144 offset:4096
	v_mfma_f32_16x16x32_bf16 v[106:109], v[184:187], v[170:173], v[106:109]
	ds_read_b128 v[220:223], v144 offset:5120
	v_mfma_f32_16x16x32_bf16 v[102:105], v[184:187], v[176:179], v[102:105]
	ds_read_b128 v[224:227], v144 offset:6144
	v_mfma_f32_16x16x32_bf16 v[98:101], v[184:187], v[180:183], v[98:101]
	ds_read_b128 v[228:231], v144 offset:7168
	v_mfma_f32_16x16x32_bf16 v[94:97], v[188:191], v[146:149], v[94:97]
	v_add_u32_e32 v144, s41, v137
	v_mfma_f32_16x16x32_bf16 v[90:93], v[188:191], v[152:155], v[90:93]
	v_mfma_f32_16x16x32_bf16 v[86:89], v[188:191], v[156:159], v[86:89]
	ds_read_b128 v[232:235], v144 offset:16384
	v_mfma_f32_16x16x32_bf16 v[82:85], v[188:191], v[162:165], v[82:85]
	ds_read_b128 v[236:239], v144 offset:17408
	v_mfma_f32_16x16x32_bf16 v[78:81], v[188:191], v[166:169], v[78:81]
	ds_read_b128 v[240:243], v144 offset:18432
	v_mfma_f32_16x16x32_bf16 v[74:77], v[188:191], v[170:173], v[74:77]
	ds_read_b128 v[244:247], v144 offset:19456
	s_add_i32 s43, s47, s42
	v_mfma_f32_16x16x32_bf16 v[70:73], v[188:191], v[176:179], v[70:73]
	s_mov_b32 m0, s43
	v_lshl_add_u64 v[142:143], v[132:133], 0, s[2:3]
	v_mfma_f32_16x16x32_bf16 v[66:69], v[188:191], v[180:183], v[66:69]
	global_load_lds_dwordx4 v[132:133], off
	s_addk_i32 m0, 0x1000
	v_mfma_f32_16x16x32_bf16 v[62:65], v[192:195], v[146:149], v[62:65]
	v_mfma_f32_16x16x32_bf16 v[58:61], v[192:195], v[152:155], v[58:61]
	v_mfma_f32_16x16x32_bf16 v[54:57], v[192:195], v[156:159], v[54:57]
	global_load_lds_dwordx4 v[142:143], off
	v_lshl_add_u64 v[142:143], v[142:143], 0, s[2:3]
	s_addk_i32 m0, 0x1000
	v_mfma_f32_16x16x32_bf16 v[50:53], v[192:195], v[162:165], v[50:53]
	v_mfma_f32_16x16x32_bf16 v[46:49], v[192:195], v[166:169], v[46:49]
	v_mfma_f32_16x16x32_bf16 v[42:45], v[192:195], v[170:173], v[42:45]
	global_load_lds_dwordx4 v[142:143], off
	v_lshl_add_u64 v[142:143], v[142:143], 0, s[2:3]
	s_addk_i32 m0, 0x1000
	v_mfma_f32_16x16x32_bf16 v[38:41], v[192:195], v[176:179], v[38:41]
	v_mfma_f32_16x16x32_bf16 v[34:37], v[192:195], v[180:183], v[34:37]
	v_mfma_f32_16x16x32_bf16 v[30:33], v[196:199], v[146:149], v[30:33]
	global_load_lds_dwordx4 v[142:143], off
	s_addk_i32 m0, 0x1000
	v_lshl_add_u64 v[142:143], v[134:135], 0, s[2:3]
	v_mfma_f32_16x16x32_bf16 v[26:29], v[196:199], v[152:155], v[26:29]
	v_mfma_f32_16x16x32_bf16 v[22:25], v[196:199], v[156:159], v[22:25]
	v_mfma_f32_16x16x32_bf16 v[18:21], v[196:199], v[162:165], v[18:21]
	global_load_lds_dwordx4 v[134:135], off
	s_addk_i32 m0, 0x1000
	v_lshl_add_u64 v[132:133], v[132:133], 0, s[12:13]
	v_mfma_f32_16x16x32_bf16 v[14:17], v[196:199], v[166:169], v[14:17]
	v_mfma_f32_16x16x32_bf16 v[10:13], v[196:199], v[170:173], v[10:13]
	v_mfma_f32_16x16x32_bf16 v[6:9], v[196:199], v[176:179], v[6:9]
	global_load_lds_dwordx4 v[142:143], off
	v_lshl_add_u64 v[134:135], v[134:135], 0, s[4:5]
	v_mfma_f32_16x16x32_bf16 v[2:5], v[196:199], v[180:183], v[2:5]
	s_mov_b32 s42, s41
	s_add_i32 s41, s41, 0x6000
	s_cmp_eq_u32 s41, 0x12000
	s_cselect_b32 s41, 0, s41
	s_waitcnt vmcnt(6) lgkmcnt(0)
	s_barrier
	v_add_u32_e32 v144, s41, v136
	v_mfma_f32_16x16x32_bf16 v[126:129], v[232:235], v[200:203], v[126:129]
	ds_read_b128 v[146:149], v144 offset:0
	v_mfma_f32_16x16x32_bf16 v[122:125], v[232:235], v[204:207], v[122:125]
	ds_read_b128 v[152:155], v144 offset:1024
	v_mfma_f32_16x16x32_bf16 v[118:121], v[232:235], v[208:211], v[118:121]
	ds_read_b128 v[156:159], v144 offset:2048
	v_mfma_f32_16x16x32_bf16 v[114:117], v[232:235], v[212:215], v[114:117]
	ds_read_b128 v[162:165], v144 offset:3072
	v_mfma_f32_16x16x32_bf16 v[110:113], v[232:235], v[216:219], v[110:113]
	ds_read_b128 v[166:169], v144 offset:4096
	v_mfma_f32_16x16x32_bf16 v[106:109], v[232:235], v[220:223], v[106:109]
	ds_read_b128 v[170:173], v144 offset:5120
	v_mfma_f32_16x16x32_bf16 v[102:105], v[232:235], v[224:227], v[102:105]
	ds_read_b128 v[176:179], v144 offset:6144
	v_mfma_f32_16x16x32_bf16 v[98:101], v[232:235], v[228:231], v[98:101]
	ds_read_b128 v[180:183], v144 offset:7168
	v_mfma_f32_16x16x32_bf16 v[94:97], v[236:239], v[200:203], v[94:97]
	v_add_u32_e32 v144, s41, v137
	v_mfma_f32_16x16x32_bf16 v[90:93], v[236:239], v[204:207], v[90:93]
	v_mfma_f32_16x16x32_bf16 v[86:89], v[236:239], v[208:211], v[86:89]
	ds_read_b128 v[184:187], v144 offset:16384
	v_mfma_f32_16x16x32_bf16 v[82:85], v[236:239], v[212:215], v[82:85]
	ds_read_b128 v[188:191], v144 offset:17408
	v_mfma_f32_16x16x32_bf16 v[78:81], v[236:239], v[216:219], v[78:81]
	ds_read_b128 v[192:195], v144 offset:18432
	v_mfma_f32_16x16x32_bf16 v[74:77], v[236:239], v[220:223], v[74:77]
	ds_read_b128 v[196:199], v144 offset:19456
	s_add_i32 s43, s47, s42
	v_mfma_f32_16x16x32_bf16 v[70:73], v[236:239], v[224:227], v[70:73]
	s_mov_b32 m0, s43
	v_lshl_add_u64 v[142:143], v[132:133], 0, s[2:3]
	v_mfma_f32_16x16x32_bf16 v[66:69], v[236:239], v[228:231], v[66:69]
	global_load_lds_dwordx4 v[132:133], off
	s_addk_i32 m0, 0x1000
	v_mfma_f32_16x16x32_bf16 v[62:65], v[240:243], v[200:203], v[62:65]
;     ...
;   for (int kt = 0; kt < nk; kt++) {
;     if (kt + 1 < nk) asm volatile("s_waitcnt vmcnt(6)" ::: "memory");
;     else asm volatile("s_waitcnt vmcnt(0)" ::: "memory");
;     __builtin_amdgcn_s_barrier();
;     asm volatile("" ::: "memory");
;     if (kt + 2 < nk) G2_STAGE(kt + 2);
;     const char* cS = smem + (kt % 3) * 24576;
;     bf16x8 xa[8], wb[4];
; #pragma unroll
;     for (int f = 0; f < 8; f++) xa[f] = *(const bf16x8*)(cS + aoff + f * 1024);
; #pragma unroll
;     for (int f = 0; f < 4; f++) wb[f] = *(const bf16x8*)(cS + boff + f * 1024);
; #pragma unroll
;     for (int nf = 0; nf < 4; nf++)
; #pragma unroll
;       for (int mf = 0; mf < 8; mf++)
;         acc[nf][mf] = __builtin_amdgcn_mfma_f32_16x16x32_bf16(wb[nf], xa[mf], acc[nf][mf], 0, 0, 0);
	v_mfma_f32_16x16x32_bf16 v[58:61], v[240:243], v[204:207], v[58:61]
	v_mfma_f32_16x16x32_bf16 v[54:57], v[240:243], v[208:211], v[54:57]
	global_load_lds_dwordx4 v[142:143], off
	v_lshl_add_u64 v[142:143], v[142:143], 0, s[2:3]
	s_addk_i32 m0, 0x1000
	v_mfma_f32_16x16x32_bf16 v[50:53], v[240:243], v[212:215], v[50:53]
	v_mfma_f32_16x16x32_bf16 v[46:49], v[240:243], v[216:219], v[46:49]
	v_mfma_f32_16x16x32_bf16 v[42:45], v[240:243], v[220:223], v[42:45]
	global_load_lds_dwordx4 v[142:143], off
	v_lshl_add_u64 v[142:143], v[142:143], 0, s[2:3]
	s_addk_i32 m0, 0x1000
	v_mfma_f32_16x16x32_bf16 v[38:41], v[240:243], v[224:227], v[38:41]
	v_mfma_f32_16x16x32_bf16 v[34:37], v[240:243], v[228:231], v[34:37]
	v_mfma_f32_16x16x32_bf16 v[30:33], v[244:247], v[200:203], v[30:33]
	global_load_lds_dwordx4 v[142:143], off
	s_addk_i32 m0, 0x1000
	v_lshl_add_u64 v[142:143], v[134:135], 0, s[2:3]
	v_mfma_f32_16x16x32_bf16 v[26:29], v[244:247], v[204:207], v[26:29]
	v_mfma_f32_16x16x32_bf16 v[22:25], v[244:247], v[208:211], v[22:25]
	v_mfma_f32_16x16x32_bf16 v[18:21], v[244:247], v[212:215], v[18:21]
	global_load_lds_dwordx4 v[134:135], off
	s_addk_i32 m0, 0x1000
	v_lshl_add_u64 v[132:133], v[132:133], 0, s[12:13]
	v_mfma_f32_16x16x32_bf16 v[14:17], v[244:247], v[216:219], v[14:17]
	v_mfma_f32_16x16x32_bf16 v[10:13], v[244:247], v[220:223], v[10:13]
	v_mfma_f32_16x16x32_bf16 v[6:9], v[244:247], v[224:227], v[6:9]
	global_load_lds_dwordx4 v[142:143], off
	v_lshl_add_u64 v[134:135], v[134:135], 0, s[4:5]
	v_mfma_f32_16x16x32_bf16 v[2:5], v[244:247], v[228:231], v[2:5]
	s_mov_b32 s42, s41
	s_add_i32 s41, s41, 0x6000
	s_cmp_eq_u32 s41, 0x12000
	s_cselect_b32 s41, 0, s41
	s_sub_i32 s40, s40, 1
	s_cmp_lg_u32 s40, 0
	s_cbranch_scc1 .Lt4_loop
	s_waitcnt vmcnt(6) lgkmcnt(0)
	s_barrier
	v_add_u32_e32 v144, s41, v136
	v_mfma_f32_16x16x32_bf16 v[126:129], v[184:187], v[146:149], v[126:129]
	ds_read_b128 v[200:203], v144 offset:0
	v_mfma_f32_16x16x32_bf16 v[122:125], v[184:187], v[152:155], v[122:125]
	ds_read_b128 v[204:207], v144 offset:1024
	v_mfma_f32_16x16x32_bf16 v[118:121], v[184:187], v[156:159], v[118:121]
	ds_read_b128 v[208:211], v144 offset:2048
	v_mfma_f32_16x16x32_bf16 v[114:117], v[184:187], v[162:165], v[114:117]
	ds_read_b128 v[212:215], v144 offset:3072
	v_mfma_f32_16x16x32_bf16 v[110:113], v[184:187], v[166:169], v[110:113]
	ds_read_b128 v[216:219], v144 offset:4096
	v_mfma_f32_16x16x32_bf16 v[106:109], v[184:187], v[170:173], v[106:109]
	ds_read_b128 v[220:223], v144 offset:5120
	v_mfma_f32_16x16x32_bf16 v[102:105], v[184:187], v[176:179], v[102:105]
	ds_read_b128 v[224:227], v144 offset:6144
	v_mfma_f32_16x16x32_bf16 v[98:101], v[184:187], v[180:183], v[98:101]
	ds_read_b128 v[228:231], v144 offset:7168
	v_mfma_f32_16x16x32_bf16 v[94:97], v[188:191], v[146:149], v[94:97]
	v_add_u32_e32 v144, s41, v137
	v_mfma_f32_16x16x32_bf16 v[90:93], v[188:191], v[152:155], v[90:93]
	v_mfma_f32_16x16x32_bf16 v[86:89], v[188:191], v[156:159], v[86:89]
	ds_read_b128 v[232:235], v144 offset:16384
	v_mfma_f32_16x16x32_bf16 v[82:85], v[188:191], v[162:165], v[82:85]
	ds_read_b128 v[236:239], v144 offset:17408
	v_mfma_f32_16x16x32_bf16 v[78:81], v[188:191], v[166:169], v[78:81]
	ds_read_b128 v[240:243], v144 offset:18432
	v_mfma_f32_16x16x32_bf16 v[74:77], v[188:191], v[170:173], v[74:77]
	ds_read_b128 v[244:247], v144 offset:19456
	s_add_i32 s43, s47, s42
	v_mfma_f32_16x16x32_bf16 v[70:73], v[188:191], v[176:179], v[70:73]
	s_mov_b32 m0, s43
	v_lshl_add_u64 v[142:143], v[132:133], 0, s[2:3]
	v_mfma_f32_16x16x32_bf16 v[66:69], v[188:191], v[180:183], v[66:69]
	global_load_lds_dwordx4 v[132:133], off
	s_addk_i32 m0, 0x1000
	v_mfma_f32_16x16x32_bf16 v[62:65], v[192:195], v[146:149], v[62:65]
	v_mfma_f32_16x16x32_bf16 v[58:61], v[192:195], v[152:155], v[58:61]
	v_mfma_f32_16x16x32_bf16 v[54:57], v[192:195], v[156:159], v[54:57]
	global_load_lds_dwordx4 v[142:143], off
	v_lshl_add_u64 v[142:143], v[142:143], 0, s[2:3]
	s_addk_i32 m0, 0x1000
	v_mfma_f32_16x16x32_bf16 v[50:53], v[192:195], v[162:165], v[50:53]
	v_mfma_f32_16x16x32_bf16 v[46:49], v[192:195], v[166:169], v[46:49]
	v_mfma_f32_16x16x32_bf16 v[42:45], v[192:195], v[170:173], v[42:45]
	global_load_lds_dwordx4 v[142:143], off
	v_lshl_add_u64 v[142:143], v[142:143], 0, s[2:3]
	s_addk_i32 m0, 0x1000
	v_mfma_f32_16x16x32_bf16 v[38:41], v[192:195], v[176:179], v[38:41]
	v_mfma_f32_16x16x32_bf16 v[34:37], v[192:195], v[180:183], v[34:37]
	v_mfma_f32_16x16x32_bf16 v[30:33], v[196:199], v[146:149], v[30:33]
	global_load_lds_dwordx4 v[142:143], off
	s_addk_i32 m0, 0x1000
	v_lshl_add_u64 v[142:143], v[134:135], 0, s[2:3]
	v_mfma_f32_16x16x32_bf16 v[26:29], v[196:199], v[152:155], v[26:29]
	v_mfma_f32_16x16x32_bf16 v[22:25], v[196:199], v[156:159], v[22:25]
	v_mfma_f32_16x16x32_bf16 v[18:21], v[196:199], v[162:165], v[18:21]
	global_load_lds_dwordx4 v[134:135], off
	s_addk_i32 m0, 0x1000
	v_lshl_add_u64 v[132:133], v[132:133], 0, s[12:13]
	v_mfma_f32_16x16x32_bf16 v[14:17], v[196:199], v[166:169], v[14:17]
	v_mfma_f32_16x16x32_bf16 v[10:13], v[196:199], v[170:173], v[10:13]
	v_mfma_f32_16x16x32_bf16 v[6:9], v[196:199], v[176:179], v[6:9]
	global_load_lds_dwordx4 v[142:143], off
	v_lshl_add_u64 v[134:135], v[134:135], 0, s[4:5]
	v_mfma_f32_16x16x32_bf16 v[2:5], v[196:199], v[180:183], v[2:5]
	s_mov_b32 s42, s41
	s_add_i32 s41, s41, 0x6000
	s_cmp_eq_u32 s41, 0x12000
	s_cselect_b32 s41, 0, s41
	s_waitcnt vmcnt(6) lgkmcnt(0)
	s_barrier
;     ...
;   for (int kt = 0; kt < nk; kt++) {
;     if (kt + 1 < nk) asm volatile("s_waitcnt vmcnt(6)" ::: "memory");
;     else asm volatile("s_waitcnt vmcnt(0)" ::: "memory");
;     __builtin_amdgcn_s_barrier();
;     asm volatile("" ::: "memory");
;     if (kt + 2 < nk) G2_STAGE(kt + 2);
;     const char* cS = smem + (kt % 3) * 24576;
;     bf16x8 xa[8], wb[4];
; #pragma unroll
;     for (int f = 0; f < 8; f++) xa[f] = *(const bf16x8*)(cS + aoff + f * 1024);
; #pragma unroll
;     for (int f = 0; f < 4; f++) wb[f] = *(const bf16x8*)(cS + boff + f * 1024);
; #pragma unroll
;     for (int nf = 0; nf < 4; nf++)
; #pragma unroll
;       for (int mf = 0; mf < 8; mf++)
;         acc[nf][mf] = __builtin_amdgcn_mfma_f32_16x16x32_bf16(wb[nf], xa[mf], acc[nf][mf], 0, 0, 0);
	v_add_u32_e32 v144, s41, v136
	v_mfma_f32_16x16x32_bf16 v[126:129], v[232:235], v[200:203], v[126:129]
	ds_read_b128 v[146:149], v144 offset:0
	v_mfma_f32_16x16x32_bf16 v[122:125], v[232:235], v[204:207], v[122:125]
	ds_read_b128 v[152:155], v144 offset:1024
	v_mfma_f32_16x16x32_bf16 v[118:121], v[232:235], v[208:211], v[118:121]
	ds_read_b128 v[156:159], v144 offset:2048
	v_mfma_f32_16x16x32_bf16 v[114:117], v[232:235], v[212:215], v[114:117]
	ds_read_b128 v[162:165], v144 offset:3072
	v_mfma_f32_16x16x32_bf16 v[110:113], v[232:235], v[216:219], v[110:113]
	ds_read_b128 v[166:169], v144 offset:4096
	v_mfma_f32_16x16x32_bf16 v[106:109], v[232:235], v[220:223], v[106:109]
	ds_read_b128 v[170:173], v144 offset:5120
	v_mfma_f32_16x16x32_bf16 v[102:105], v[232:235], v[224:227], v[102:105]
	ds_read_b128 v[176:179], v144 offset:6144
	v_mfma_f32_16x16x32_bf16 v[98:101], v[232:235], v[228:231], v[98:101]
	ds_read_b128 v[180:183], v144 offset:7168
	v_mfma_f32_16x16x32_bf16 v[94:97], v[236:239], v[200:203], v[94:97]
	v_add_u32_e32 v144, s41, v137
	v_mfma_f32_16x16x32_bf16 v[90:93], v[236:239], v[204:207], v[90:93]
	v_mfma_f32_16x16x32_bf16 v[86:89], v[236:239], v[208:211], v[86:89]
	ds_read_b128 v[184:187], v144 offset:16384
	v_mfma_f32_16x16x32_bf16 v[82:85], v[236:239], v[212:215], v[82:85]
	ds_read_b128 v[188:191], v144 offset:17408
	v_mfma_f32_16x16x32_bf16 v[78:81], v[236:239], v[216:219], v[78:81]
	ds_read_b128 v[192:195], v144 offset:18432
	v_mfma_f32_16x16x32_bf16 v[74:77], v[236:239], v[220:223], v[74:77]
	ds_read_b128 v[196:199], v144 offset:19456
	v_mfma_f32_16x16x32_bf16 v[70:73], v[236:239], v[224:227], v[70:73]
	v_mfma_f32_16x16x32_bf16 v[66:69], v[236:239], v[228:231], v[66:69]
	v_mfma_f32_16x16x32_bf16 v[62:65], v[240:243], v[200:203], v[62:65]
	v_mfma_f32_16x16x32_bf16 v[58:61], v[240:243], v[204:207], v[58:61]
	v_mfma_f32_16x16x32_bf16 v[54:57], v[240:243], v[208:211], v[54:57]
	v_mfma_f32_16x16x32_bf16 v[50:53], v[240:243], v[212:215], v[50:53]
	v_mfma_f32_16x16x32_bf16 v[46:49], v[240:243], v[216:219], v[46:49]
	v_mfma_f32_16x16x32_bf16 v[42:45], v[240:243], v[220:223], v[42:45]
	v_mfma_f32_16x16x32_bf16 v[38:41], v[240:243], v[224:227], v[38:41]
	v_mfma_f32_16x16x32_bf16 v[34:37], v[240:243], v[228:231], v[34:37]
	v_mfma_f32_16x16x32_bf16 v[30:33], v[244:247], v[200:203], v[30:33]
	v_mfma_f32_16x16x32_bf16 v[26:29], v[244:247], v[204:207], v[26:29]
	v_mfma_f32_16x16x32_bf16 v[22:25], v[244:247], v[208:211], v[22:25]
	v_mfma_f32_16x16x32_bf16 v[18:21], v[244:247], v[212:215], v[18:21]
	v_mfma_f32_16x16x32_bf16 v[14:17], v[244:247], v[216:219], v[14:17]
	v_mfma_f32_16x16x32_bf16 v[10:13], v[244:247], v[220:223], v[10:13]
	v_mfma_f32_16x16x32_bf16 v[6:9], v[244:247], v[224:227], v[6:9]
	v_mfma_f32_16x16x32_bf16 v[2:5], v[244:247], v[228:231], v[2:5]
	s_mov_b32 s42, s41
	s_add_i32 s41, s41, 0x6000
	s_cmp_eq_u32 s41, 0x12000
	s_cselect_b32 s41, 0, s41
	s_waitcnt vmcnt(0) lgkmcnt(0)
	s_barrier
	v_add_u32_e32 v144, s41, v136
	v_mfma_f32_16x16x32_bf16 v[126:129], v[184:187], v[146:149], v[126:129]
	ds_read_b128 v[200:203], v144 offset:0
	v_mfma_f32_16x16x32_bf16 v[122:125], v[184:187], v[152:155], v[122:125]
	ds_read_b128 v[204:207], v144 offset:1024
	v_mfma_f32_16x16x32_bf16 v[118:121], v[184:187], v[156:159], v[118:121]
	ds_read_b128 v[208:211], v144 offset:2048
	v_mfma_f32_16x16x32_bf16 v[114:117], v[184:187], v[162:165], v[114:117]
	ds_read_b128 v[212:215], v144 offset:3072
	v_mfma_f32_16x16x32_bf16 v[110:113], v[184:187], v[166:169], v[110:113]
	ds_read_b128 v[216:219], v144 offset:4096
	v_mfma_f32_16x16x32_bf16 v[106:109], v[184:187], v[170:173], v[106:109]
	ds_read_b128 v[220:223], v144 offset:5120
	v_mfma_f32_16x16x32_bf16 v[102:105], v[184:187], v[176:179], v[102:105]
	ds_read_b128 v[224:227], v144 offset:6144
	v_mfma_f32_16x16x32_bf16 v[98:101], v[184:187], v[180:183], v[98:101]
	ds_read_b128 v[228:231], v144 offset:7168
	v_mfma_f32_16x16x32_bf16 v[94:97], v[188:191], v[146:149], v[94:97]
	v_add_u32_e32 v144, s41, v137
	v_mfma_f32_16x16x32_bf16 v[90:93], v[188:191], v[152:155], v[90:93]
	v_mfma_f32_16x16x32_bf16 v[86:89], v[188:191], v[156:159], v[86:89]
	ds_read_b128 v[232:235], v144 offset:16384
	v_mfma_f32_16x16x32_bf16 v[82:85], v[188:191], v[162:165], v[82:85]
	ds_read_b128 v[236:239], v144 offset:17408
	v_mfma_f32_16x16x32_bf16 v[78:81], v[188:191], v[166:169], v[78:81]
	ds_read_b128 v[240:243], v144 offset:18432
	v_mfma_f32_16x16x32_bf16 v[74:77], v[188:191], v[170:173], v[74:77]
	ds_read_b128 v[244:247], v144 offset:19456
	v_mfma_f32_16x16x32_bf16 v[70:73], v[188:191], v[176:179], v[70:73]
	v_mfma_f32_16x16x32_bf16 v[66:69], v[188:191], v[180:183], v[66:69]
	v_mfma_f32_16x16x32_bf16 v[62:65], v[192:195], v[146:149], v[62:65]
	v_mfma_f32_16x16x32_bf16 v[58:61], v[192:195], v[152:155], v[58:61]
	v_mfma_f32_16x16x32_bf16 v[54:57], v[192:195], v[156:159], v[54:57]
	v_mfma_f32_16x16x32_bf16 v[50:53], v[192:195], v[162:165], v[50:53]
	v_mfma_f32_16x16x32_bf16 v[46:49], v[192:195], v[166:169], v[46:49]
	v_mfma_f32_16x16x32_bf16 v[42:45], v[192:195], v[170:173], v[42:45]
	v_mfma_f32_16x16x32_bf16 v[38:41], v[192:195], v[176:179], v[38:41]
	v_mfma_f32_16x16x32_bf16 v[34:37], v[192:195], v[180:183], v[34:37]
	v_mfma_f32_16x16x32_bf16 v[30:33], v[196:199], v[146:149], v[30:33]
	v_mfma_f32_16x16x32_bf16 v[26:29], v[196:199], v[152:155], v[26:29]
	v_mfma_f32_16x16x32_bf16 v[22:25], v[196:199], v[156:159], v[22:25]
	v_mfma_f32_16x16x32_bf16 v[18:21], v[196:199], v[162:165], v[18:21]
	v_mfma_f32_16x16x32_bf16 v[14:17], v[196:199], v[166:169], v[14:17]
	v_mfma_f32_16x16x32_bf16 v[10:13], v[196:199], v[170:173], v[10:13]
	v_mfma_f32_16x16x32_bf16 v[6:9], v[196:199], v[176:179], v[6:9]
	v_mfma_f32_16x16x32_bf16 v[2:5], v[196:199], v[180:183], v[2:5]
	s_mov_b32 s42, s41
	s_add_i32 s41, s41, 0x6000
	s_cmp_eq_u32 s41, 0x12000
	s_cselect_b32 s41, 0, s41
	s_mov_b32 s4, 0x8000
	s_mov_b32 s5, 0
	s_mov_b32 s10, 0x10000
	s_mov_b32 s11, 0
	s_mov_b32 s45, 0x3fd744fd
	s_waitcnt lgkmcnt(0)
; DEVI float blo(unsigned u) { return __uint_as_float(u << 16); }
; DEVI float bhi(unsigned u) { return __uint_as_float(u & 0xffff0000u); }
;     ...
;         acc[nf][mf] = __builtin_amdgcn_mfma_f32_16x16x32_bf16(wb[nf], xa[mf], acc[nf][mf], 0, 0, 0);
;     ...
;         if (EPI == EPI_RESID || EPI == EPI_RESID_ATOMIC) {
;           f32x4 x = a;
;           if (EPI == EPI_RESID || kpart == 0) {
;             const u32x2 xr = *(const u32x2*)((const u16*)(p.ws + WS_XB) + (size_t)row * 1024 + col);
;             x[0] += ALPHA * blo(xr[0]); x[1] += ALPHA * bhi(xr[0]); x[2] += ALPHA * blo(xr[1]); x[3] += ALPHA * bhi(xr[1]);
;           }
;           if (EPI == EPI_RESID) *(f32x4*)((float*)(p.ws + WS_XF) + (size_t)row * 1024 + col) = x;
;           else *(f32x4*)((float*)(p.ws + WS_SLAB) + ((size_t)kpart * 512 + (row - T_P)) * 1024 + col) = x;
	v_mfma_f32_16x16x32_bf16 v[126:129], v[232:235], v[200:203], v[126:129]
	v_mfma_f32_16x16x32_bf16 v[122:125], v[232:235], v[204:207], v[122:125]
	v_mfma_f32_16x16x32_bf16 v[118:121], v[232:235], v[208:211], v[118:121]
	v_mfma_f32_16x16x32_bf16 v[114:117], v[232:235], v[212:215], v[114:117]
	v_mfma_f32_16x16x32_bf16 v[110:113], v[232:235], v[216:219], v[110:113]
	global_load_dwordx4 v[146:149], v[138:139], off offset:0
	v_mfma_f32_16x16x32_bf16 v[106:109], v[232:235], v[220:223], v[106:109]
	v_mfma_f32_16x16x32_bf16 v[102:105], v[232:235], v[224:227], v[102:105]
	global_load_dwordx4 v[152:155], v[138:139], off offset:128
	v_mfma_f32_16x16x32_bf16 v[98:101], v[232:235], v[228:231], v[98:101]
	v_lshl_add_u64 v[138:139], v[138:139], 0, s[4:5]
	v_mfma_f32_16x16x32_bf16 v[94:97], v[236:239], v[200:203], v[94:97]
	global_load_dwordx4 v[156:159], v[138:139], off offset:0
	v_mfma_f32_16x16x32_bf16 v[90:93], v[236:239], v[204:207], v[90:93]
	v_mfma_f32_16x16x32_bf16 v[86:89], v[236:239], v[208:211], v[86:89]
	global_load_dwordx4 v[162:165], v[138:139], off offset:128
	v_mfma_f32_16x16x32_bf16 v[82:85], v[236:239], v[212:215], v[82:85]
	v_lshl_add_u64 v[138:139], v[138:139], 0, s[4:5]
	v_mfma_f32_16x16x32_bf16 v[78:81], v[236:239], v[216:219], v[78:81]
	global_load_dwordx4 v[166:169], v[138:139], off offset:0
	v_mfma_f32_16x16x32_bf16 v[74:77], v[236:239], v[220:223], v[74:77]
	v_mfma_f32_16x16x32_bf16 v[70:73], v[236:239], v[224:227], v[70:73]
	global_load_dwordx4 v[170:173], v[138:139], off offset:128
	v_mfma_f32_16x16x32_bf16 v[66:69], v[236:239], v[228:231], v[66:69]
	v_lshl_add_u64 v[138:139], v[138:139], 0, s[4:5]
	v_mfma_f32_16x16x32_bf16 v[62:65], v[240:243], v[200:203], v[62:65]
	global_load_dwordx4 v[176:179], v[138:139], off offset:0
	v_mfma_f32_16x16x32_bf16 v[58:61], v[240:243], v[204:207], v[58:61]
	v_mfma_f32_16x16x32_bf16 v[54:57], v[240:243], v[208:211], v[54:57]
	global_load_dwordx4 v[180:183], v[138:139], off offset:128
	v_mfma_f32_16x16x32_bf16 v[50:53], v[240:243], v[212:215], v[50:53]
	v_lshl_add_u64 v[138:139], v[138:139], 0, s[4:5]
	v_mfma_f32_16x16x32_bf16 v[46:49], v[240:243], v[216:219], v[46:49]
	global_load_dwordx4 v[184:187], v[138:139], off offset:0
	v_mfma_f32_16x16x32_bf16 v[42:45], v[240:243], v[220:223], v[42:45]
	v_mfma_f32_16x16x32_bf16 v[38:41], v[240:243], v[224:227], v[38:41]
	global_load_dwordx4 v[188:191], v[138:139], off offset:128
	v_mfma_f32_16x16x32_bf16 v[34:37], v[240:243], v[228:231], v[34:37]
	v_lshl_add_u64 v[138:139], v[138:139], 0, s[4:5]
	v_mfma_f32_16x16x32_bf16 v[30:33], v[244:247], v[200:203], v[30:33]
	global_load_dwordx4 v[192:195], v[138:139], off offset:0
	v_mfma_f32_16x16x32_bf16 v[26:29], v[244:247], v[204:207], v[26:29]
	v_mfma_f32_16x16x32_bf16 v[22:25], v[244:247], v[208:211], v[22:25]
	global_load_dwordx4 v[196:199], v[138:139], off offset:128
	v_mfma_f32_16x16x32_bf16 v[18:21], v[244:247], v[212:215], v[18:21]
	v_lshl_add_u64 v[138:139], v[138:139], 0, s[4:5]
	v_mfma_f32_16x16x32_bf16 v[14:17], v[244:247], v[216:219], v[14:17]
	v_mfma_f32_16x16x32_bf16 v[10:13], v[244:247], v[220:223], v[10:13]
	v_mfma_f32_16x16x32_bf16 v[6:9], v[244:247], v[224:227], v[6:9]
	v_mfma_f32_16x16x32_bf16 v[2:5], v[244:247], v[228:231], v[2:5]
	s_mov_b32 m0, s44
	global_load_dwordx4 v[200:203], v[138:139], off offset:0
	global_load_dwordx4 v[204:207], v[138:139], off offset:128
	v_lshl_add_u64 v[138:139], v[138:139], 0, s[4:5]
	global_load_dwordx4 v[208:211], v[138:139], off offset:0
	global_load_dwordx4 v[212:215], v[138:139], off offset:128
	v_lshl_add_u64 v[138:139], v[138:139], 0, s[4:5]
	s_nop 7
	s_waitcnt vmcnt(15)
	v_permlane16_swap_b32_e32 v146, v148
	v_permlane16_swap_b32_e32 v147, v149
	v_lshlrev_b32_e32 v216, 16, v146
	v_and_b32_e32 v146, 0xffff0000, v146
	v_lshlrev_b32_e32 v217, 16, v147
	v_and_b32_e32 v147, 0xffff0000, v147
	v_fmac_f32_e32 v126, s45, v216
	v_fmac_f32_e32 v127, s45, v146
	v_fmac_f32_e32 v128, s45, v217
	v_fmac_f32_e32 v129, s45, v147
	global_store_dwordx4 v[140:141], v[126:129], off offset:0
	v_lshlrev_b32_e32 v216, 16, v148
	v_and_b32_e32 v148, 0xffff0000, v148
	v_lshlrev_b32_e32 v217, 16, v149
	v_and_b32_e32 v149, 0xffff0000, v149
	v_fmac_f32_e32 v94, s45, v216
	v_fmac_f32_e32 v95, s45, v148
	v_fmac_f32_e32 v96, s45, v217
	v_fmac_f32_e32 v97, s45, v149
	global_store_dwordx4 v[140:141], v[94:97], off offset:64
	s_waitcnt vmcnt(16)
	v_permlane16_swap_b32_e32 v152, v154
	v_permlane16_swap_b32_e32 v153, v155
	v_lshlrev_b32_e32 v216, 16, v152
	v_and_b32_e32 v152, 0xffff0000, v152
	v_lshlrev_b32_e32 v217, 16, v153
	v_and_b32_e32 v153, 0xffff0000, v153
	v_fmac_f32_e32 v62, s45, v216
	v_fmac_f32_e32 v63, s45, v152
	v_fmac_f32_e32 v64, s45, v217
	v_fmac_f32_e32 v65, s45, v153
	global_store_dwordx4 v[140:141], v[62:65], off offset:128
	v_lshlrev_b32_e32 v216, 16, v154
	v_and_b32_e32 v154, 0xffff0000, v154
	v_lshlrev_b32_e32 v217, 16, v155
	v_and_b32_e32 v155, 0xffff0000, v155
	v_fmac_f32_e32 v30, s45, v216
	v_fmac_f32_e32 v31, s45, v154
	v_fmac_f32_e32 v32, s45, v217
	v_fmac_f32_e32 v33, s45, v155
	global_store_dwordx4 v[140:141], v[30:33], off offset:192
	v_lshl_add_u64 v[140:141], v[140:141], 0, s[10:11]
	s_waitcnt vmcnt(17)
	v_permlane16_swap_b32_e32 v156, v158
	v_permlane16_swap_b32_e32 v157, v159
	v_lshlrev_b32_e32 v216, 16, v156
	v_and_b32_e32 v156, 0xffff0000, v156
	v_lshlrev_b32_e32 v217, 16, v157
	v_and_b32_e32 v157, 0xffff0000, v157
	v_fmac_f32_e32 v122, s45, v216
	v_fmac_f32_e32 v123, s45, v156
	v_fmac_f32_e32 v124, s45, v217
	v_fmac_f32_e32 v125, s45, v157
	global_store_dwordx4 v[140:141], v[122:125], off offset:0
	v_lshlrev_b32_e32 v216, 16, v158
	v_and_b32_e32 v158, 0xffff0000, v158
	v_lshlrev_b32_e32 v217, 16, v159
	v_and_b32_e32 v159, 0xffff0000, v159
	v_fmac_f32_e32 v90, s45, v216
	v_fmac_f32_e32 v91, s45, v158
	v_fmac_f32_e32 v92, s45, v217
	v_fmac_f32_e32 v93, s45, v159
	global_store_dwordx4 v[140:141], v[90:93], off offset:64
	s_waitcnt vmcnt(18)
; DEVI float blo(unsigned u) { return __uint_as_float(u << 16); }
; DEVI float bhi(unsigned u) { return __uint_as_float(u & 0xffff0000u); }
;     ...
; #pragma unroll
;       for (int nf = 0; nf < 4; nf++) {
;         const int col = n0 + wn * 64 + nf * 16 + quad * 4;
;         f32x4 a = acc[nf][mf];
;         if (EPI == EPI_RESID || EPI == EPI_RESID_ATOMIC) {
;           f32x4 x = a;
;           if (EPI == EPI_RESID || kpart == 0) {
;             const u32x2 xr = *(const u32x2*)((const u16*)(p.ws + WS_XB) + (size_t)row * 1024 + col);
;             x[0] += ALPHA * blo(xr[0]); x[1] += ALPHA * bhi(xr[0]); x[2] += ALPHA * blo(xr[1]); x[3] += ALPHA * bhi(xr[1]);
;           }
;           if (EPI == EPI_RESID) *(f32x4*)((float*)(p.ws + WS_XF) + (size_t)row * 1024 + col) = x;
;           else *(f32x4*)((float*)(p.ws + WS_SLAB) + ((size_t)kpart * 512 + (row - T_P)) * 1024 + col) = x;
	v_permlane16_swap_b32_e32 v162, v164
	v_permlane16_swap_b32_e32 v163, v165
	v_lshlrev_b32_e32 v216, 16, v162
	v_and_b32_e32 v162, 0xffff0000, v162
	v_lshlrev_b32_e32 v217, 16, v163
	v_and_b32_e32 v163, 0xffff0000, v163
	v_fmac_f32_e32 v58, s45, v216
	v_fmac_f32_e32 v59, s45, v162
	v_fmac_f32_e32 v60, s45, v217
	v_fmac_f32_e32 v61, s45, v163
	global_store_dwordx4 v[140:141], v[58:61], off offset:128
	v_lshlrev_b32_e32 v216, 16, v164
	v_and_b32_e32 v164, 0xffff0000, v164
	v_lshlrev_b32_e32 v217, 16, v165
	v_and_b32_e32 v165, 0xffff0000, v165
	v_fmac_f32_e32 v26, s45, v216
	v_fmac_f32_e32 v27, s45, v164
	v_fmac_f32_e32 v28, s45, v217
	v_fmac_f32_e32 v29, s45, v165
	global_store_dwordx4 v[140:141], v[26:29], off offset:192
	v_lshl_add_u64 v[140:141], v[140:141], 0, s[10:11]
	s_waitcnt vmcnt(19)
	v_permlane16_swap_b32_e32 v166, v168
	v_permlane16_swap_b32_e32 v167, v169
	v_lshlrev_b32_e32 v216, 16, v166
	v_and_b32_e32 v166, 0xffff0000, v166
	v_lshlrev_b32_e32 v217, 16, v167
	v_and_b32_e32 v167, 0xffff0000, v167
	v_fmac_f32_e32 v118, s45, v216
	v_fmac_f32_e32 v119, s45, v166
	v_fmac_f32_e32 v120, s45, v217
	v_fmac_f32_e32 v121, s45, v167
	global_store_dwordx4 v[140:141], v[118:121], off offset:0
	v_lshlrev_b32_e32 v216, 16, v168
	v_and_b32_e32 v168, 0xffff0000, v168
	v_lshlrev_b32_e32 v217, 16, v169
	v_and_b32_e32 v169, 0xffff0000, v169
	v_fmac_f32_e32 v86, s45, v216
	v_fmac_f32_e32 v87, s45, v168
	v_fmac_f32_e32 v88, s45, v217
	v_fmac_f32_e32 v89, s45, v169
	global_store_dwordx4 v[140:141], v[86:89], off offset:64
	s_waitcnt vmcnt(20)
	v_permlane16_swap_b32_e32 v170, v172
	v_permlane16_swap_b32_e32 v171, v173
	v_lshlrev_b32_e32 v216, 16, v170
	v_and_b32_e32 v170, 0xffff0000, v170
	v_lshlrev_b32_e32 v217, 16, v171
	v_and_b32_e32 v171, 0xffff0000, v171
	v_fmac_f32_e32 v54, s45, v216
	v_fmac_f32_e32 v55, s45, v170
	v_fmac_f32_e32 v56, s45, v217
	v_fmac_f32_e32 v57, s45, v171
	global_store_dwordx4 v[140:141], v[54:57], off offset:128
	v_lshlrev_b32_e32 v216, 16, v172
	v_and_b32_e32 v172, 0xffff0000, v172
	v_lshlrev_b32_e32 v217, 16, v173
	v_and_b32_e32 v173, 0xffff0000, v173
	v_fmac_f32_e32 v22, s45, v216
	v_fmac_f32_e32 v23, s45, v172
	v_fmac_f32_e32 v24, s45, v217
	v_fmac_f32_e32 v25, s45, v173
	global_store_dwordx4 v[140:141], v[22:25], off offset:192
	v_lshl_add_u64 v[140:141], v[140:141], 0, s[10:11]
	s_waitcnt vmcnt(21)
	v_permlane16_swap_b32_e32 v176, v178
	v_permlane16_swap_b32_e32 v177, v179
	v_lshlrev_b32_e32 v216, 16, v176
	v_and_b32_e32 v176, 0xffff0000, v176
	v_lshlrev_b32_e32 v217, 16, v177
	v_and_b32_e32 v177, 0xffff0000, v177
	v_fmac_f32_e32 v114, s45, v216
	v_fmac_f32_e32 v115, s45, v176
	v_fmac_f32_e32 v116, s45, v217
	v_fmac_f32_e32 v117, s45, v177
	global_store_dwordx4 v[140:141], v[114:117], off offset:0
	v_lshlrev_b32_e32 v216, 16, v178
	v_and_b32_e32 v178, 0xffff0000, v178
	v_lshlrev_b32_e32 v217, 16, v179
	v_and_b32_e32 v179, 0xffff0000, v179
	v_fmac_f32_e32 v82, s45, v216
	v_fmac_f32_e32 v83, s45, v178
	v_fmac_f32_e32 v84, s45, v217
	v_fmac_f32_e32 v85, s45, v179
	global_store_dwordx4 v[140:141], v[82:85], off offset:64
	s_waitcnt vmcnt(22)
	v_permlane16_swap_b32_e32 v180, v182
	v_permlane16_swap_b32_e32 v181, v183
	v_lshlrev_b32_e32 v216, 16, v180
	v_and_b32_e32 v180, 0xffff0000, v180
	v_lshlrev_b32_e32 v217, 16, v181
	v_and_b32_e32 v181, 0xffff0000, v181
	v_fmac_f32_e32 v50, s45, v216
	v_fmac_f32_e32 v51, s45, v180
	v_fmac_f32_e32 v52, s45, v217
	v_fmac_f32_e32 v53, s45, v181
	global_store_dwordx4 v[140:141], v[50:53], off offset:128
	v_lshlrev_b32_e32 v216, 16, v182
	v_and_b32_e32 v182, 0xffff0000, v182
	v_lshlrev_b32_e32 v217, 16, v183
	v_and_b32_e32 v183, 0xffff0000, v183
	v_fmac_f32_e32 v18, s45, v216
	v_fmac_f32_e32 v19, s45, v182
	v_fmac_f32_e32 v20, s45, v217
	v_fmac_f32_e32 v21, s45, v183
	global_store_dwordx4 v[140:141], v[18:21], off offset:192
	v_lshl_add_u64 v[140:141], v[140:141], 0, s[10:11]
	s_waitcnt vmcnt(23)
	v_permlane16_swap_b32_e32 v184, v186
	v_permlane16_swap_b32_e32 v185, v187
	v_lshlrev_b32_e32 v216, 16, v184
	v_and_b32_e32 v184, 0xffff0000, v184
	v_lshlrev_b32_e32 v217, 16, v185
	v_and_b32_e32 v185, 0xffff0000, v185
	v_fmac_f32_e32 v110, s45, v216
	v_fmac_f32_e32 v111, s45, v184
	v_fmac_f32_e32 v112, s45, v217
	v_fmac_f32_e32 v113, s45, v185
	global_store_dwordx4 v[140:141], v[110:113], off offset:0
	v_lshlrev_b32_e32 v216, 16, v186
	v_and_b32_e32 v186, 0xffff0000, v186
	v_lshlrev_b32_e32 v217, 16, v187
	v_and_b32_e32 v187, 0xffff0000, v187
	v_fmac_f32_e32 v78, s45, v216
	v_fmac_f32_e32 v79, s45, v186
	v_fmac_f32_e32 v80, s45, v217
	v_fmac_f32_e32 v81, s45, v187
	global_store_dwordx4 v[140:141], v[78:81], off offset:64
	s_waitcnt vmcnt(24)
; DEVI float blo(unsigned u) { return __uint_as_float(u << 16); }
; DEVI float bhi(unsigned u) { return __uint_as_float(u & 0xffff0000u); }
;     ...
; #pragma unroll
;       for (int nf = 0; nf < 4; nf++) {
;         const int col = n0 + wn * 64 + nf * 16 + quad * 4;
;         f32x4 a = acc[nf][mf];
;         if (EPI == EPI_RESID || EPI == EPI_RESID_ATOMIC) {
;           f32x4 x = a;
;           if (EPI == EPI_RESID || kpart == 0) {
;             const u32x2 xr = *(const u32x2*)((const u16*)(p.ws + WS_XB) + (size_t)row * 1024 + col);
;             x[0] += ALPHA * blo(xr[0]); x[1] += ALPHA * bhi(xr[0]); x[2] += ALPHA * blo(xr[1]); x[3] += ALPHA * bhi(xr[1]);
;           }
;           if (EPI == EPI_RESID) *(f32x4*)((float*)(p.ws + WS_XF) + (size_t)row * 1024 + col) = x;
;           else *(f32x4*)((float*)(p.ws + WS_SLAB) + ((size_t)kpart * 512 + (row - T_P)) * 1024 + col) = x;
	v_permlane16_swap_b32_e32 v188, v190
	v_permlane16_swap_b32_e32 v189, v191
	v_lshlrev_b32_e32 v216, 16, v188
	v_and_b32_e32 v188, 0xffff0000, v188
	v_lshlrev_b32_e32 v217, 16, v189
	v_and_b32_e32 v189, 0xffff0000, v189
	v_fmac_f32_e32 v46, s45, v216
	v_fmac_f32_e32 v47, s45, v188
	v_fmac_f32_e32 v48, s45, v217
	v_fmac_f32_e32 v49, s45, v189
	global_store_dwordx4 v[140:141], v[46:49], off offset:128
	v_lshlrev_b32_e32 v216, 16, v190
	v_and_b32_e32 v190, 0xffff0000, v190
	v_lshlrev_b32_e32 v217, 16, v191
	v_and_b32_e32 v191, 0xffff0000, v191
	v_fmac_f32_e32 v14, s45, v216
	v_fmac_f32_e32 v15, s45, v190
	v_fmac_f32_e32 v16, s45, v217
	v_fmac_f32_e32 v17, s45, v191
	global_store_dwordx4 v[140:141], v[14:17], off offset:192
	v_lshl_add_u64 v[140:141], v[140:141], 0, s[10:11]
	s_waitcnt vmcnt(25)
	v_permlane16_swap_b32_e32 v192, v194
	v_permlane16_swap_b32_e32 v193, v195
	v_lshlrev_b32_e32 v216, 16, v192
	v_and_b32_e32 v192, 0xffff0000, v192
	v_lshlrev_b32_e32 v217, 16, v193
	v_and_b32_e32 v193, 0xffff0000, v193
	v_fmac_f32_e32 v106, s45, v216
	v_fmac_f32_e32 v107, s45, v192
	v_fmac_f32_e32 v108, s45, v217
	v_fmac_f32_e32 v109, s45, v193
	global_store_dwordx4 v[140:141], v[106:109], off offset:0
	v_lshlrev_b32_e32 v216, 16, v194
	v_and_b32_e32 v194, 0xffff0000, v194
	v_lshlrev_b32_e32 v217, 16, v195
	v_and_b32_e32 v195, 0xffff0000, v195
	v_fmac_f32_e32 v74, s45, v216
	v_fmac_f32_e32 v75, s45, v194
	v_fmac_f32_e32 v76, s45, v217
	v_fmac_f32_e32 v77, s45, v195
	global_store_dwordx4 v[140:141], v[74:77], off offset:64
	s_waitcnt vmcnt(26)
	v_permlane16_swap_b32_e32 v196, v198
	v_permlane16_swap_b32_e32 v197, v199
	v_lshlrev_b32_e32 v216, 16, v196
	v_and_b32_e32 v196, 0xffff0000, v196
	v_lshlrev_b32_e32 v217, 16, v197
	v_and_b32_e32 v197, 0xffff0000, v197
	v_fmac_f32_e32 v42, s45, v216
	v_fmac_f32_e32 v43, s45, v196
	v_fmac_f32_e32 v44, s45, v217
	v_fmac_f32_e32 v45, s45, v197
	global_store_dwordx4 v[140:141], v[42:45], off offset:128
	v_lshlrev_b32_e32 v216, 16, v198
	v_and_b32_e32 v198, 0xffff0000, v198
	v_lshlrev_b32_e32 v217, 16, v199
	v_and_b32_e32 v199, 0xffff0000, v199
	v_fmac_f32_e32 v10, s45, v216
	v_fmac_f32_e32 v11, s45, v198
	v_fmac_f32_e32 v12, s45, v217
	v_fmac_f32_e32 v13, s45, v199
	global_store_dwordx4 v[140:141], v[10:13], off offset:192
	v_lshl_add_u64 v[140:141], v[140:141], 0, s[10:11]
	s_waitcnt vmcnt(27)
	v_permlane16_swap_b32_e32 v200, v202
	v_permlane16_swap_b32_e32 v201, v203
	v_lshlrev_b32_e32 v216, 16, v200
	v_and_b32_e32 v200, 0xffff0000, v200
	v_lshlrev_b32_e32 v217, 16, v201
	v_and_b32_e32 v201, 0xffff0000, v201
	v_fmac_f32_e32 v102, s45, v216
	v_fmac_f32_e32 v103, s45, v200
	v_fmac_f32_e32 v104, s45, v217
	v_fmac_f32_e32 v105, s45, v201
	global_store_dwordx4 v[140:141], v[102:105], off offset:0
	v_lshlrev_b32_e32 v216, 16, v202
	v_and_b32_e32 v202, 0xffff0000, v202
	v_lshlrev_b32_e32 v217, 16, v203
	v_and_b32_e32 v203, 0xffff0000, v203
	v_fmac_f32_e32 v70, s45, v216
	v_fmac_f32_e32 v71, s45, v202
	v_fmac_f32_e32 v72, s45, v217
	v_fmac_f32_e32 v73, s45, v203
	global_store_dwordx4 v[140:141], v[70:73], off offset:64
	s_waitcnt vmcnt(28)
	v_permlane16_swap_b32_e32 v204, v206
	v_permlane16_swap_b32_e32 v205, v207
	v_lshlrev_b32_e32 v216, 16, v204
	v_and_b32_e32 v204, 0xffff0000, v204
	v_lshlrev_b32_e32 v217, 16, v205
	v_and_b32_e32 v205, 0xffff0000, v205
	v_fmac_f32_e32 v38, s45, v216
	v_fmac_f32_e32 v39, s45, v204
	v_fmac_f32_e32 v40, s45, v217
	v_fmac_f32_e32 v41, s45, v205
	global_store_dwordx4 v[140:141], v[38:41], off offset:128
	v_lshlrev_b32_e32 v216, 16, v206
	v_and_b32_e32 v206, 0xffff0000, v206
	v_lshlrev_b32_e32 v217, 16, v207
	v_and_b32_e32 v207, 0xffff0000, v207
	v_fmac_f32_e32 v6, s45, v216
	v_fmac_f32_e32 v7, s45, v206
	v_fmac_f32_e32 v8, s45, v217
	v_fmac_f32_e32 v9, s45, v207
	global_store_dwordx4 v[140:141], v[6:9], off offset:192
	v_lshl_add_u64 v[140:141], v[140:141], 0, s[10:11]
	s_waitcnt vmcnt(29)
	v_permlane16_swap_b32_e32 v208, v210
	v_permlane16_swap_b32_e32 v209, v211
	v_lshlrev_b32_e32 v216, 16, v208
	v_and_b32_e32 v208, 0xffff0000, v208
	v_lshlrev_b32_e32 v217, 16, v209
	v_and_b32_e32 v209, 0xffff0000, v209
	v_fmac_f32_e32 v98, s45, v216
	v_fmac_f32_e32 v99, s45, v208
	v_fmac_f32_e32 v100, s45, v217
	v_fmac_f32_e32 v101, s45, v209
	global_store_dwordx4 v[140:141], v[98:101], off offset:0
	v_lshlrev_b32_e32 v216, 16, v210
	v_and_b32_e32 v210, 0xffff0000, v210
	v_lshlrev_b32_e32 v217, 16, v211
	v_and_b32_e32 v211, 0xffff0000, v211
	v_fmac_f32_e32 v66, s45, v216
	v_fmac_f32_e32 v67, s45, v210
	v_fmac_f32_e32 v68, s45, v217
	v_fmac_f32_e32 v69, s45, v211
	global_store_dwordx4 v[140:141], v[66:69], off offset:64
	s_waitcnt vmcnt(30)
	v_permlane16_swap_b32_e32 v212, v214
	v_permlane16_swap_b32_e32 v213, v215
	v_lshlrev_b32_e32 v216, 16, v212
	v_and_b32_e32 v212, 0xffff0000, v212
	v_lshlrev_b32_e32 v217, 16, v213
	v_and_b32_e32 v213, 0xffff0000, v213
	v_fmac_f32_e32 v34, s45, v216
	v_fmac_f32_e32 v35, s45, v212
	v_fmac_f32_e32 v36, s45, v217
	v_fmac_f32_e32 v37, s45, v213
	global_store_dwordx4 v[140:141], v[34:37], off offset:128
	v_lshlrev_b32_e32 v216, 16, v214
	v_and_b32_e32 v214, 0xffff0000, v214
	v_lshlrev_b32_e32 v217, 16, v215
	v_and_b32_e32 v215, 0xffff0000, v215
	v_fmac_f32_e32 v2, s45, v216
	v_fmac_f32_e32 v3, s45, v214
	v_fmac_f32_e32 v4, s45, v217
	v_fmac_f32_e32 v5, s45, v215
	global_store_dwordx4 v[140:141], v[2:5], off offset:192
	s_branch .LBB0_757
